# K-loops: s_setprio 1 moved in front of the pre-MMA barrier (redundant lgkmcnt(0) after it dropped), mid-block prio flips removed, s_setprio 0 moved behind the post-MMA barrier
# speedup vs baseline: 1.0264x; 1.0079x over previous
; #define PG8_STAGE(bufoff, gbase, voff) do { _Pragma("unroll") for (int _i = 0; _i < 2; ++_i) \
;         __builtin_amdgcn_global_load_lds((const unsigned*)((const char*)(gbase) + (voff)[_i]), (PG8_LAS unsigned*)(lds + (bufoff) + ldsw + _i * 8192), 16, 0, 0); } while (0)
; #define PG8_LDA(dst, b, h) do { _Pragma("unroll") for (int m = 0; m < 4; ++m) _Pragma("unroll") for (int k = 0; k < 2; ++k) dst[m][k] = *(const PG8_LAS bf16x8*)(lds + PG8_SA(b, h) + aoff + m * 2048 + k * 1024); } while (0)
; #define PG8_LDB(dst, b, h) do { _Pragma("unroll") for (int n = 0; n < 2; ++n) _Pragma("unroll") for (int k = 0; k < 2; ++k) dst[n][k] = *(const PG8_LAS bf16x8*)(lds + PG8_SB(b, h) + boff + n * 2048 + k * 1024); } while (0)
; #define PG8_MMA(ai, bj, At, Bt) do { __builtin_amdgcn_s_setprio(1); _Pragma("unroll") for (int m = 0; m < 4; ++m) _Pragma("unroll") for (int n = 0; n < 2; ++n) _Pragma("unroll") for (int k = 0; k < 2; ++k) \
;         acc[ai][bj][m][n] = __builtin_amdgcn_mfma_f32_16x16x32_bf16(Bt[n][k], At[m][k], acc[ai][bj][m][n], 0, 0, 0); __builtin_amdgcn_s_setprio(0); } while (0)
; #define PG8_WAIT_V(n) asm volatile("s_waitcnt vmcnt(" #n ")" ::: "memory")
; #define PG8_BAR __builtin_amdgcn_s_barrier()
; template <class Epi, class Sched, bool ALIGN_EPI = false, bool SP2 = false>
; __device__ __forceinline__ void gemm_phase(PG8_LAS unsigned char* lds, const Gemm g, const Sched& S, const Epi& E) {
;     ...
;         for (int t = 0; t < nt; t += 2) {
;             const bool last = (t == nt - 2);
;             const char* a1 = cA + (size_t)(t + 1) * kstep;
;             const char* a2 = last ? nA : cA + (size_t)(t + 2) * kstep; const char* b2 = last ? nB : cB + (size_t)(t + 2) * kstep;
;             const char* a3 = a2 + kstep; const char* b3 = b2 + kstep;
;             if (last && has_next) S.a_ready(nxt);
;             if constexpr (SP2) {
;             PG8_LDB(B0, 0, 0); PG8_LDB(B1, 0, 1); PG8_SCHED; PG8_LDA(At, 0, 0); PG8_STAGE(PG8_SA(1, 1), a1 + hstep, voffA);
;             PG8_WAIT_V(8); PG8_WAIT_L(0); PG8_BAR; PG8_MMA(0, 0, At, B0); PG8_MMA(0, 1, At, B1); PG8_BAR; PG8_SCHED;
;             PG8_LDA(At, 0, 1); PG8_STAGE(PG8_SB(0, 0), b2, voffB); PG8_STAGE(PG8_SB(0, 1), b2 + hstep, voffB); PG8_STAGE(PG8_SA(0, 0), a2, voffA);
;             PG8_WAIT_V(8); PG8_WAIT_L(0); PG8_BAR; PG8_MMA(1, 0, At, B0); PG8_MMA(1, 1, At, B1); PG8_BAR; PG8_SCHED;
.LBB0_425:
	s_add_u32 s8, s6, 0xfff80080
	s_addc_u32 s9, s7, -1
	s_add_i32 s78, 0, 0x10000
	s_cmp_eq_u32 s75, 28
	s_cselect_b32 s11, s61, s9
	s_cselect_b32 s10, s69, s8
	v_add_u32_e32 v151, s78, v146
	s_cselect_b32 s9, s59, s74
	s_cselect_b32 s8, s70, s71
	s_add_i32 s80, 0, 0x14000
	s_nop 0
	ds_read_b128 v[140:143], v151
	ds_read_b128 v[152:155], v151 offset:1024
	ds_read_b128 v[156:159], v151 offset:2048
	ds_read_b128 v[160:163], v151 offset:3072
	v_add_u32_e32 v151, s80, v146
	ds_read_b128 v[164:167], v151
	ds_read_b128 v[188:191], v151 offset:1024
	ds_read_b128 v[192:195], v151 offset:2048
	ds_read_b128 v[196:199], v151 offset:3072
	v_lshl_add_u64 v[168:169], s[6:7], 0, v[136:137]
	s_add_i32 m0, s25, 0xc000
	ds_read_b128 v[200:203], v150
	ds_read_b128 v[204:207], v150 offset:1024
	ds_read_b128 v[208:211], v150 offset:2048
	ds_read_b128 v[212:215], v150 offset:3072
	ds_read_b128 v[228:231], v150 offset:4096
	ds_read_b128 v[232:235], v150 offset:5120
	ds_read_b128 v[236:239], v150 offset:6144
	ds_read_b128 v[240:243], v150 offset:7168
	global_load_lds_dwordx4 v[168:169], off
	v_lshl_add_u64 v[168:169], s[6:7], 0, v[138:139]
	s_add_i32 m0, s25, 0xe000
	s_nop 0
	global_load_lds_dwordx4 v[168:169], off
	s_waitcnt vmcnt(8)
	s_waitcnt lgkmcnt(0)
	s_setprio 1
	s_barrier
	v_mfma_f32_16x16x32_bf16 v[126:129], v[140:143], v[200:203], v[126:129]
	v_mfma_f32_16x16x32_bf16 v[118:121], v[156:159], v[200:203], v[118:121]
	v_mfma_f32_16x16x32_bf16 v[110:113], v[140:143], v[208:211], v[110:113]
	v_mfma_f32_16x16x32_bf16 v[102:105], v[156:159], v[208:211], v[102:105]
	v_mfma_f32_16x16x32_bf16 v[94:97], v[140:143], v[228:231], v[94:97]
	v_mfma_f32_16x16x32_bf16 v[86:89], v[156:159], v[228:231], v[86:89]
	v_mfma_f32_16x16x32_bf16 v[78:81], v[140:143], v[236:239], v[78:81]
	v_mfma_f32_16x16x32_bf16 v[70:73], v[156:159], v[236:239], v[70:73]
	v_mfma_f32_16x16x32_bf16 v[126:129], v[152:155], v[204:207], v[126:129]
	v_mfma_f32_16x16x32_bf16 v[118:121], v[160:163], v[204:207], v[118:121]
	v_mfma_f32_16x16x32_bf16 v[110:113], v[152:155], v[212:215], v[110:113]
	v_mfma_f32_16x16x32_bf16 v[102:105], v[160:163], v[212:215], v[102:105]
	v_mfma_f32_16x16x32_bf16 v[94:97], v[152:155], v[232:235], v[94:97]
	v_mfma_f32_16x16x32_bf16 v[86:89], v[160:163], v[232:235], v[86:89]
	v_mfma_f32_16x16x32_bf16 v[78:81], v[152:155], v[240:243], v[78:81]
	v_mfma_f32_16x16x32_bf16 v[70:73], v[160:163], v[240:243], v[70:73]
	v_mfma_f32_16x16x32_bf16 v[122:125], v[164:167], v[200:203], v[122:125]
	v_mfma_f32_16x16x32_bf16 v[114:117], v[192:195], v[200:203], v[114:117]
	v_mfma_f32_16x16x32_bf16 v[106:109], v[164:167], v[208:211], v[106:109]
	v_mfma_f32_16x16x32_bf16 v[98:101], v[192:195], v[208:211], v[98:101]
	v_mfma_f32_16x16x32_bf16 v[90:93], v[164:167], v[228:231], v[90:93]
	v_mfma_f32_16x16x32_bf16 v[82:85], v[192:195], v[228:231], v[82:85]
	v_mfma_f32_16x16x32_bf16 v[74:77], v[164:167], v[236:239], v[74:77]
	v_mfma_f32_16x16x32_bf16 v[66:69], v[192:195], v[236:239], v[66:69]
	v_mfma_f32_16x16x32_bf16 v[122:125], v[188:191], v[204:207], v[122:125]
	v_mfma_f32_16x16x32_bf16 v[114:117], v[196:199], v[204:207], v[114:117]
	v_mfma_f32_16x16x32_bf16 v[106:109], v[188:191], v[212:215], v[106:109]
	v_mfma_f32_16x16x32_bf16 v[98:101], v[196:199], v[212:215], v[98:101]
	v_mfma_f32_16x16x32_bf16 v[90:93], v[188:191], v[232:235], v[90:93]
	v_mfma_f32_16x16x32_bf16 v[82:85], v[196:199], v[232:235], v[82:85]
	v_mfma_f32_16x16x32_bf16 v[74:77], v[188:191], v[240:243], v[74:77]
	v_mfma_f32_16x16x32_bf16 v[66:69], v[196:199], v[240:243], v[66:69]
	s_barrier
	s_setprio 0
	s_add_i32 s78, s78, s24
	v_lshl_add_u64 v[168:169], s[8:9], 0, v[0:1]
	s_mov_b32 m0, s78
	ds_read_b128 v[200:203], v150 offset:16384
	ds_read_b128 v[204:207], v150 offset:17408
	ds_read_b128 v[208:211], v150 offset:18432
	ds_read_b128 v[212:215], v150 offset:19456
	ds_read_b128 v[228:231], v150 offset:20480
	ds_read_b128 v[232:235], v150 offset:21504
	ds_read_b128 v[236:239], v150 offset:22528
	ds_read_b128 v[240:243], v150 offset:23552
	global_load_lds_dwordx4 v[168:169], off
	s_add_i32 m0, s78, 0x2000
	s_add_u32 s78, s8, 0x80000
	v_lshl_add_u64 v[216:217], s[8:9], 0, v[134:135]
	s_addc_u32 s79, s9, 0
	s_add_i32 s80, s80, s24
	global_load_lds_dwordx4 v[216:217], off
	v_lshl_add_u64 v[244:245], s[78:79], 0, v[0:1]
	s_mov_b32 m0, s80
	v_lshl_add_u64 v[246:247], s[10:11], 0, v[132:133]
	global_load_lds_dwordx4 v[244:245], off
	v_lshl_add_u64 v[244:245], s[78:79], 0, v[134:135]
	s_add_i32 m0, s80, 0x2000
	s_nop 0
	global_load_lds_dwordx4 v[244:245], off
	s_waitcnt vmcnt(6)
	s_waitcnt lgkmcnt(0)
	s_setprio 1
	s_barrier
; #define PG8_STAGE(bufoff, gbase, voff) do { _Pragma("unroll") for (int _i = 0; _i < 2; ++_i) \
;         __builtin_amdgcn_global_load_lds((const unsigned*)((const char*)(gbase) + (voff)[_i]), (PG8_LAS unsigned*)(lds + (bufoff) + ldsw + _i * 8192), 16, 0, 0); } while (0)
; #define PG8_LDA(dst, b, h) do { _Pragma("unroll") for (int m = 0; m < 4; ++m) _Pragma("unroll") for (int k = 0; k < 2; ++k) dst[m][k] = *(const PG8_LAS bf16x8*)(lds + PG8_SA(b, h) + aoff + m * 2048 + k * 1024); } while (0)
; #define PG8_LDB(dst, b, h) do { _Pragma("unroll") for (int n = 0; n < 2; ++n) _Pragma("unroll") for (int k = 0; k < 2; ++k) dst[n][k] = *(const PG8_LAS bf16x8*)(lds + PG8_SB(b, h) + boff + n * 2048 + k * 1024); } while (0)
; #define PG8_MMA(ai, bj, At, Bt) do { __builtin_amdgcn_s_setprio(1); _Pragma("unroll") for (int m = 0; m < 4; ++m) _Pragma("unroll") for (int n = 0; n < 2; ++n) _Pragma("unroll") for (int k = 0; k < 2; ++k) \
;         acc[ai][bj][m][n] = __builtin_amdgcn_mfma_f32_16x16x32_bf16(Bt[n][k], At[m][k], acc[ai][bj][m][n], 0, 0, 0); __builtin_amdgcn_s_setprio(0); } while (0)
; #define PG8_WAIT_V(n) asm volatile("s_waitcnt vmcnt(" #n ")" ::: "memory")
; #define PG8_WAIT_L(n) asm volatile("s_waitcnt lgkmcnt(" #n ")" ::: "memory")
; #define PG8_BAR __builtin_amdgcn_s_barrier()
; #define PG8_SCHED __builtin_amdgcn_sched_barrier(0)
; template <class Epi, class Sched, bool ALIGN_EPI = false, bool SP2 = false>
; __device__ __forceinline__ void gemm_phase(PG8_LAS unsigned char* lds, const Gemm g, const Sched& S, const Epi& E) {
;     ...
;             PG8_WAIT_V(8); PG8_WAIT_L(0); PG8_BAR; PG8_MMA(1, 0, At, B0); PG8_MMA(1, 1, At, B1); PG8_BAR; PG8_SCHED;
;             PG8_LDB(B0, 1, 0); PG8_LDB(B1, 1, 1); PG8_SCHED; PG8_LDA(At, 1, 0); PG8_STAGE(PG8_SA(0, 1), a2 + hstep, voffA);
;             PG8_WAIT_V(8); PG8_WAIT_L(0); PG8_BAR; PG8_MMA(0, 0, At, B0); PG8_MMA(0, 1, At, B1); PG8_BAR; PG8_SCHED;
;             PG8_LDA(At, 1, 1); PG8_STAGE(PG8_SB(1, 0), b3, voffB); PG8_STAGE(PG8_SB(1, 1), b3 + hstep, voffB); PG8_STAGE(PG8_SA(1, 0), a3, voffA);
	v_mfma_f32_16x16x32_bf16 v[62:65], v[140:143], v[200:203], v[62:65]
	v_mfma_f32_16x16x32_bf16 v[54:57], v[156:159], v[200:203], v[54:57]
	v_mfma_f32_16x16x32_bf16 v[46:49], v[140:143], v[208:211], v[46:49]
	v_mfma_f32_16x16x32_bf16 v[38:41], v[156:159], v[208:211], v[38:41]
	v_mfma_f32_16x16x32_bf16 v[30:33], v[140:143], v[228:231], v[30:33]
	v_mfma_f32_16x16x32_bf16 v[22:25], v[156:159], v[228:231], v[22:25]
	v_mfma_f32_16x16x32_bf16 v[14:17], v[140:143], v[236:239], v[14:17]
	v_mfma_f32_16x16x32_bf16 v[6:9], v[156:159], v[236:239], v[6:9]
	v_mfma_f32_16x16x32_bf16 v[62:65], v[152:155], v[204:207], v[62:65]
	v_mfma_f32_16x16x32_bf16 v[54:57], v[160:163], v[204:207], v[54:57]
	v_mfma_f32_16x16x32_bf16 v[46:49], v[152:155], v[212:215], v[46:49]
	v_mfma_f32_16x16x32_bf16 v[38:41], v[160:163], v[212:215], v[38:41]
	v_mfma_f32_16x16x32_bf16 v[30:33], v[152:155], v[232:235], v[30:33]
	v_mfma_f32_16x16x32_bf16 v[22:25], v[160:163], v[232:235], v[22:25]
	v_mfma_f32_16x16x32_bf16 v[14:17], v[152:155], v[240:243], v[14:17]
	v_mfma_f32_16x16x32_bf16 v[6:9], v[160:163], v[240:243], v[6:9]
	v_mfma_f32_16x16x32_bf16 v[58:61], v[164:167], v[200:203], v[58:61]
	v_mfma_f32_16x16x32_bf16 v[50:53], v[192:195], v[200:203], v[50:53]
	v_mfma_f32_16x16x32_bf16 v[42:45], v[164:167], v[208:211], v[42:45]
	v_mfma_f32_16x16x32_bf16 v[34:37], v[192:195], v[208:211], v[34:37]
	v_mfma_f32_16x16x32_bf16 v[26:29], v[164:167], v[228:231], v[26:29]
	v_mfma_f32_16x16x32_bf16 v[18:21], v[192:195], v[228:231], v[18:21]
	v_mfma_f32_16x16x32_bf16 v[10:13], v[164:167], v[236:239], v[10:13]
	v_mfma_f32_16x16x32_bf16 v[2:5], v[192:195], v[236:239], v[2:5]
	v_mfma_f32_16x16x32_bf16 v[58:61], v[188:191], v[204:207], v[58:61]
	v_mfma_f32_16x16x32_bf16 v[50:53], v[196:199], v[204:207], v[50:53]
	v_mfma_f32_16x16x32_bf16 v[42:45], v[188:191], v[212:215], v[42:45]
	v_mfma_f32_16x16x32_bf16 v[34:37], v[196:199], v[212:215], v[34:37]
	v_mfma_f32_16x16x32_bf16 v[26:29], v[188:191], v[232:235], v[26:29]
	v_mfma_f32_16x16x32_bf16 v[18:21], v[196:199], v[232:235], v[18:21]
	v_mfma_f32_16x16x32_bf16 v[10:13], v[188:191], v[240:243], v[10:13]
	v_mfma_f32_16x16x32_bf16 v[2:5], v[196:199], v[240:243], v[2:5]
	s_barrier
	s_setprio 0
	v_lshl_add_u64 v[244:245], s[10:11], 0, v[130:131]
	s_mov_b32 m0, s25
	s_nop 0
	global_load_lds_dwordx4 v[244:245], off
	s_mov_b32 m0, s26
	s_nop 0
	global_load_lds_dwordx4 v[246:247], off
	s_add_i32 s78, 0, 0x18000
	v_add_u32_e32 v151, s78, v146
	s_add_i32 s79, 0, 0x1c000
	ds_read_b128 v[140:143], v151
	ds_read_b128 v[152:155], v151 offset:1024
	ds_read_b128 v[156:159], v151 offset:2048
	ds_read_b128 v[160:163], v151 offset:3072
	v_add_u32_e32 v151, s79, v146
	ds_read_b128 v[164:167], v151
	ds_read_b128 v[188:191], v151 offset:1024
	ds_read_b128 v[192:195], v151 offset:2048
	ds_read_b128 v[196:199], v151 offset:3072
	s_add_u32 s10, s10, 0x80000
	s_addc_u32 s11, s11, 0
	s_mov_b32 m0, s27
	v_lshl_add_u64 v[248:249], s[10:11], 0, v[130:131]
	ds_read_b128 v[200:203], v150 offset:32768
	ds_read_b128 v[204:207], v150 offset:33792
	ds_read_b128 v[208:211], v150 offset:34816
	ds_read_b128 v[212:215], v150 offset:35840
	ds_read_b128 v[228:231], v150 offset:36864
	ds_read_b128 v[232:235], v150 offset:37888
	ds_read_b128 v[236:239], v150 offset:38912
	ds_read_b128 v[240:243], v150 offset:39936
	global_load_lds_dwordx4 v[248:249], off
	v_lshl_add_u64 v[248:249], s[10:11], 0, v[132:133]
	s_mov_b32 m0, s28
	s_nop 0
	global_load_lds_dwordx4 v[248:249], off
	s_waitcnt vmcnt(8)
	s_waitcnt lgkmcnt(0)
	s_setprio 1
	s_barrier
	v_mfma_f32_16x16x32_bf16 v[126:129], v[140:143], v[200:203], v[126:129]
	v_mfma_f32_16x16x32_bf16 v[118:121], v[156:159], v[200:203], v[118:121]
	v_mfma_f32_16x16x32_bf16 v[110:113], v[140:143], v[208:211], v[110:113]
	v_mfma_f32_16x16x32_bf16 v[102:105], v[156:159], v[208:211], v[102:105]
	v_mfma_f32_16x16x32_bf16 v[94:97], v[140:143], v[228:231], v[94:97]
	v_mfma_f32_16x16x32_bf16 v[86:89], v[156:159], v[228:231], v[86:89]
	v_mfma_f32_16x16x32_bf16 v[78:81], v[140:143], v[236:239], v[78:81]
	v_mfma_f32_16x16x32_bf16 v[70:73], v[156:159], v[236:239], v[70:73]
	v_mfma_f32_16x16x32_bf16 v[126:129], v[152:155], v[204:207], v[126:129]
	v_mfma_f32_16x16x32_bf16 v[118:121], v[160:163], v[204:207], v[118:121]
	v_mfma_f32_16x16x32_bf16 v[110:113], v[152:155], v[212:215], v[110:113]
	v_mfma_f32_16x16x32_bf16 v[102:105], v[160:163], v[212:215], v[102:105]
	v_mfma_f32_16x16x32_bf16 v[94:97], v[152:155], v[232:235], v[94:97]
	v_mfma_f32_16x16x32_bf16 v[86:89], v[160:163], v[232:235], v[86:89]
	v_mfma_f32_16x16x32_bf16 v[78:81], v[152:155], v[240:243], v[78:81]
	v_mfma_f32_16x16x32_bf16 v[70:73], v[160:163], v[240:243], v[70:73]
	v_mfma_f32_16x16x32_bf16 v[122:125], v[164:167], v[200:203], v[122:125]
	v_mfma_f32_16x16x32_bf16 v[114:117], v[192:195], v[200:203], v[114:117]
	v_mfma_f32_16x16x32_bf16 v[106:109], v[164:167], v[208:211], v[106:109]
	v_mfma_f32_16x16x32_bf16 v[98:101], v[192:195], v[208:211], v[98:101]
	v_mfma_f32_16x16x32_bf16 v[90:93], v[164:167], v[228:231], v[90:93]
	v_mfma_f32_16x16x32_bf16 v[82:85], v[192:195], v[228:231], v[82:85]
	v_mfma_f32_16x16x32_bf16 v[74:77], v[164:167], v[236:239], v[74:77]
	v_mfma_f32_16x16x32_bf16 v[66:69], v[192:195], v[236:239], v[66:69]
	v_mfma_f32_16x16x32_bf16 v[122:125], v[188:191], v[204:207], v[122:125]
	v_mfma_f32_16x16x32_bf16 v[114:117], v[196:199], v[204:207], v[114:117]
	v_mfma_f32_16x16x32_bf16 v[106:109], v[188:191], v[212:215], v[106:109]
	v_mfma_f32_16x16x32_bf16 v[98:101], v[196:199], v[212:215], v[98:101]
	v_mfma_f32_16x16x32_bf16 v[90:93], v[188:191], v[232:235], v[90:93]
	v_mfma_f32_16x16x32_bf16 v[82:85], v[196:199], v[232:235], v[82:85]
	v_mfma_f32_16x16x32_bf16 v[74:77], v[188:191], v[240:243], v[74:77]
	v_mfma_f32_16x16x32_bf16 v[66:69], v[196:199], v[240:243], v[66:69]
	s_barrier
; #define PG8_STAGE(bufoff, gbase, voff) do { _Pragma("unroll") for (int _i = 0; _i < 2; ++_i) \
;         __builtin_amdgcn_global_load_lds((const unsigned*)((const char*)(gbase) + (voff)[_i]), (PG8_LAS unsigned*)(lds + (bufoff) + ldsw + _i * 8192), 16, 0, 0); } while (0)
; #define PG8_LDA(dst, b, h) do { _Pragma("unroll") for (int m = 0; m < 4; ++m) _Pragma("unroll") for (int k = 0; k < 2; ++k) dst[m][k] = *(const PG8_LAS bf16x8*)(lds + PG8_SA(b, h) + aoff + m * 2048 + k * 1024); } while (0)
; #define PG8_MMA(ai, bj, At, Bt) do { __builtin_amdgcn_s_setprio(1); _Pragma("unroll") for (int m = 0; m < 4; ++m) _Pragma("unroll") for (int n = 0; n < 2; ++n) _Pragma("unroll") for (int k = 0; k < 2; ++k) \
;         acc[ai][bj][m][n] = __builtin_amdgcn_mfma_f32_16x16x32_bf16(Bt[n][k], At[m][k], acc[ai][bj][m][n], 0, 0, 0); __builtin_amdgcn_s_setprio(0); } while (0)
; #define PG8_WAIT_V(n) asm volatile("s_waitcnt vmcnt(" #n ")" ::: "memory")
; #define PG8_WAIT_L(n) asm volatile("s_waitcnt lgkmcnt(" #n ")" ::: "memory")
; #define PG8_BAR __builtin_amdgcn_s_barrier()
; #define PG8_SCHED __builtin_amdgcn_sched_barrier(0)
; template <class Epi, class Sched, bool ALIGN_EPI = false, bool SP2 = false>
; __device__ __forceinline__ void gemm_phase(PG8_LAS unsigned char* lds, const Gemm g, const Sched& S, const Epi& E) {
;     ...
;             PG8_WAIT_V(8); PG8_WAIT_L(0); PG8_BAR; PG8_MMA(0, 0, At, B0); PG8_MMA(0, 1, At, B1); PG8_BAR; PG8_SCHED;
;             PG8_LDA(At, 1, 1); PG8_STAGE(PG8_SB(1, 0), b3, voffB); PG8_STAGE(PG8_SB(1, 1), b3 + hstep, voffB); PG8_STAGE(PG8_SA(1, 0), a3, voffA);
;             PG8_WAIT_V(8); PG8_WAIT_L(0); PG8_BAR; PG8_MMA(1, 0, At, B0); PG8_MMA(1, 1, At, B1); PG8_BAR; PG8_SCHED;
	s_setprio 0
	s_add_i32 s10, s78, s24
	v_lshl_add_u64 v[168:169], v[168:169], 0, s[88:89]
	s_mov_b32 m0, s10
	ds_read_b128 v[200:203], v150 offset:49152
	ds_read_b128 v[204:207], v150 offset:50176
	ds_read_b128 v[208:211], v150 offset:51200
	ds_read_b128 v[212:215], v150 offset:52224
	ds_read_b128 v[228:231], v150 offset:53248
	ds_read_b128 v[232:235], v150 offset:54272
	ds_read_b128 v[236:239], v150 offset:55296
	ds_read_b128 v[240:243], v150 offset:56320
	global_load_lds_dwordx4 v[168:169], off
	s_add_i32 m0, s10, 0x2000
	s_add_u32 s8, s8, 0x80080
	v_lshl_add_u64 v[168:169], v[216:217], 0, s[88:89]
	s_addc_u32 s9, s9, 0
	s_add_i32 s10, s79, s24
	global_load_lds_dwordx4 v[168:169], off
	v_lshl_add_u64 v[168:169], s[8:9], 0, v[0:1]
	s_mov_b32 m0, s10
	s_nop 0
	global_load_lds_dwordx4 v[168:169], off
	v_lshl_add_u64 v[168:169], s[8:9], 0, v[134:135]
	s_add_i32 m0, s10, 0x2000
	s_nop 0
	global_load_lds_dwordx4 v[168:169], off
	v_lshl_add_u64 v[168:169], v[244:245], 0, s[88:89]
	s_mov_b32 m0, s29
	s_nop 0
	global_load_lds_dwordx4 v[168:169], off
	v_lshl_add_u64 v[168:169], v[246:247], 0, s[88:89]
	s_mov_b32 m0, s30
	s_nop 0
	global_load_lds_dwordx4 v[168:169], off
	s_waitcnt vmcnt(8)
	s_waitcnt lgkmcnt(0)
	s_setprio 1
	s_barrier
	v_mfma_f32_16x16x32_bf16 v[62:65], v[140:143], v[200:203], v[62:65]
	v_mfma_f32_16x16x32_bf16 v[54:57], v[156:159], v[200:203], v[54:57]
	v_mfma_f32_16x16x32_bf16 v[46:49], v[140:143], v[208:211], v[46:49]
	v_mfma_f32_16x16x32_bf16 v[38:41], v[156:159], v[208:211], v[38:41]
	v_mfma_f32_16x16x32_bf16 v[30:33], v[140:143], v[228:231], v[30:33]
	v_mfma_f32_16x16x32_bf16 v[22:25], v[156:159], v[228:231], v[22:25]
	v_mfma_f32_16x16x32_bf16 v[14:17], v[140:143], v[236:239], v[14:17]
	v_mfma_f32_16x16x32_bf16 v[6:9], v[156:159], v[236:239], v[6:9]
	v_mfma_f32_16x16x32_bf16 v[62:65], v[152:155], v[204:207], v[62:65]
	v_mfma_f32_16x16x32_bf16 v[54:57], v[160:163], v[204:207], v[54:57]
	v_mfma_f32_16x16x32_bf16 v[46:49], v[152:155], v[212:215], v[46:49]
	v_mfma_f32_16x16x32_bf16 v[38:41], v[160:163], v[212:215], v[38:41]
	v_mfma_f32_16x16x32_bf16 v[30:33], v[152:155], v[232:235], v[30:33]
	v_mfma_f32_16x16x32_bf16 v[22:25], v[160:163], v[232:235], v[22:25]
	v_mfma_f32_16x16x32_bf16 v[14:17], v[152:155], v[240:243], v[14:17]
	v_mfma_f32_16x16x32_bf16 v[6:9], v[160:163], v[240:243], v[6:9]
	v_mfma_f32_16x16x32_bf16 v[58:61], v[164:167], v[200:203], v[58:61]
	v_mfma_f32_16x16x32_bf16 v[50:53], v[192:195], v[200:203], v[50:53]
	v_mfma_f32_16x16x32_bf16 v[42:45], v[164:167], v[208:211], v[42:45]
	v_mfma_f32_16x16x32_bf16 v[34:37], v[192:195], v[208:211], v[34:37]
	v_mfma_f32_16x16x32_bf16 v[26:29], v[164:167], v[228:231], v[26:29]
	v_mfma_f32_16x16x32_bf16 v[18:21], v[192:195], v[228:231], v[18:21]
	v_mfma_f32_16x16x32_bf16 v[10:13], v[164:167], v[236:239], v[10:13]
	v_mfma_f32_16x16x32_bf16 v[2:5], v[192:195], v[236:239], v[2:5]
	v_mfma_f32_16x16x32_bf16 v[58:61], v[188:191], v[204:207], v[58:61]
	v_mfma_f32_16x16x32_bf16 v[50:53], v[196:199], v[204:207], v[50:53]
	v_mfma_f32_16x16x32_bf16 v[42:45], v[188:191], v[212:215], v[42:45]
	v_mfma_f32_16x16x32_bf16 v[34:37], v[196:199], v[212:215], v[34:37]
	v_mfma_f32_16x16x32_bf16 v[26:29], v[188:191], v[232:235], v[26:29]
	v_mfma_f32_16x16x32_bf16 v[18:21], v[196:199], v[232:235], v[18:21]
	v_mfma_f32_16x16x32_bf16 v[10:13], v[188:191], v[240:243], v[10:13]
	v_mfma_f32_16x16x32_bf16 v[2:5], v[196:199], v[240:243], v[2:5]
	s_barrier
	s_setprio 0
	s_add_i32 s75, s75, 2
	s_add_u32 s6, s6, 0x100
	s_addc_u32 s7, s7, 0
	s_add_u32 s71, s71, 0x100
	s_addc_u32 s74, s74, 0
	s_cmp_gt_u32 s75, 29
	s_cbranch_scc0 .LBB0_425
	s_and_b64 vcc, exec, s[56:57]
	s_movk_i32 s36, 0x2800
	s_cbranch_vccz .LBB0_428
	s_barrier

; #define PG8_STAGE(bufoff, gbase, voff) do { _Pragma("unroll") for (int _i = 0; _i < 2; ++_i) \
;         __builtin_amdgcn_global_load_lds((const unsigned*)((const char*)(gbase) + (voff)[_i]), (PG8_LAS unsigned*)(lds + (bufoff) + ldsw + _i * 8192), 16, 0, 0); } while (0)
; #define PG8_LDA(dst, b, h) do { _Pragma("unroll") for (int m = 0; m < 4; ++m) _Pragma("unroll") for (int k = 0; k < 2; ++k) dst[m][k] = *(const PG8_LAS bf16x8*)(lds + PG8_SA(b, h) + aoff + m * 2048 + k * 1024); } while (0)
; #define PG8_LDB(dst, b, h) do { _Pragma("unroll") for (int n = 0; n < 2; ++n) _Pragma("unroll") for (int k = 0; k < 2; ++k) dst[n][k] = *(const PG8_LAS bf16x8*)(lds + PG8_SB(b, h) + boff + n * 2048 + k * 1024); } while (0)
; #define PG8_MMA(ai, bj, At, Bt) do { __builtin_amdgcn_s_setprio(1); _Pragma("unroll") for (int m = 0; m < 4; ++m) _Pragma("unroll") for (int n = 0; n < 2; ++n) _Pragma("unroll") for (int k = 0; k < 2; ++k) \
;         acc[ai][bj][m][n] = __builtin_amdgcn_mfma_f32_16x16x32_bf16(Bt[n][k], At[m][k], acc[ai][bj][m][n], 0, 0, 0); __builtin_amdgcn_s_setprio(0); } while (0)
; #define PG8_WAIT_V(n) asm volatile("s_waitcnt vmcnt(" #n ")" ::: "memory")
; #define PG8_BAR __builtin_amdgcn_s_barrier()
; template <class Epi, class Sched, bool ALIGN_EPI = false, bool SP2 = false>
; __device__ __forceinline__ void gemm_phase(PG8_LAS unsigned char* lds, const Gemm g, const Sched& S, const Epi& E) {
;     ...
;         for (int t = 0; t < nt; t += 2) {
;             const bool last = (t == nt - 2);
;             const char* a1 = cA + (size_t)(t + 1) * kstep;
;             const char* a2 = last ? nA : cA + (size_t)(t + 2) * kstep; const char* b2 = last ? nB : cB + (size_t)(t + 2) * kstep;
;             const char* a3 = a2 + kstep; const char* b3 = b2 + kstep;
;             if (last && has_next) S.a_ready(nxt);
;             if constexpr (SP2) {
;             PG8_LDB(B0, 0, 0); PG8_LDB(B1, 0, 1); PG8_SCHED; PG8_LDA(At, 0, 0); PG8_STAGE(PG8_SA(1, 1), a1 + hstep, voffA);
;             PG8_WAIT_V(8); PG8_WAIT_L(0); PG8_BAR; PG8_MMA(0, 0, At, B0); PG8_MMA(0, 1, At, B1); PG8_BAR; PG8_SCHED;
;             PG8_LDA(At, 0, 1); PG8_STAGE(PG8_SB(0, 0), b2, voffB); PG8_STAGE(PG8_SB(0, 1), b2 + hstep, voffB); PG8_STAGE(PG8_SA(0, 0), a2, voffA);
;             PG8_WAIT_V(8); PG8_WAIT_L(0); PG8_BAR; PG8_MMA(1, 0, At, B0); PG8_MMA(1, 1, At, B1); PG8_BAR; PG8_SCHED;
.LBB0_795:
	s_add_u32 s8, s6, 0x100
	s_addc_u32 s9, s7, 0
	s_add_i32 s63, 0, 0x10000
	s_cmpk_eq_i32 s62, 0x54
	s_cselect_b32 s59, s83, s9
	s_cselect_b32 s58, s82, s8
	s_cselect_b32 s11, s5, s61
	s_cselect_b32 s10, s4, s60
	s_add_i32 vcc_lo, 0, 0x14000
	v_add_u32_e32 v78, s63, v228
	v_add_u32_e32 v126, vcc_lo, v228
	ds_read_b128 v[50:53], v78
	ds_read_b128 v[62:65], v78 offset:1024
	ds_read_b128 v[74:77], v78 offset:2048
	ds_read_b128 v[78:81], v78 offset:3072
	ds_read_b128 v[90:93], v126
	ds_read_b128 v[102:105], v126 offset:1024
	ds_read_b128 v[114:117], v126 offset:2048
	ds_read_b128 v[126:129], v126 offset:3072
	v_lshl_add_u64 v[236:237], s[6:7], 0, v[194:195]
	s_add_i32 m0, s24, 0xc000
	ds_read_b128 v[162:165], v230
	ds_read_b128 v[166:169], v230 offset:1024
	ds_read_b128 v[198:201], v230 offset:2048
	ds_read_b128 v[202:205], v230 offset:3072
	ds_read_b128 v[206:209], v230 offset:4096
	ds_read_b128 v[210:213], v230 offset:5120
	ds_read_b128 v[214:217], v230 offset:6144
	ds_read_b128 v[232:235], v230 offset:7168
	global_load_lds_dwordx4 v[236:237], off
	v_lshl_add_u64 v[236:237], s[6:7], 0, v[196:197]
	s_add_i32 m0, s24, 0xe000
	s_nop 0
	global_load_lds_dwordx4 v[236:237], off
	s_waitcnt vmcnt(8)
	s_waitcnt lgkmcnt(0)
	s_setprio 1
	s_barrier
	v_mfma_f32_16x16x32_bf16 v[158:161], v[50:53], v[162:165], v[158:161]
	v_mfma_f32_16x16x32_bf16 v[154:157], v[74:77], v[162:165], v[154:157]
	v_mfma_f32_16x16x32_bf16 v[142:145], v[50:53], v[198:201], v[142:145]
	v_mfma_f32_16x16x32_bf16 v[138:141], v[74:77], v[198:201], v[138:141]
	v_mfma_f32_16x16x32_bf16 v[122:125], v[50:53], v[206:209], v[122:125]
	v_mfma_f32_16x16x32_bf16 v[118:121], v[74:77], v[206:209], v[118:121]
	v_mfma_f32_16x16x32_bf16 v[98:101], v[50:53], v[214:217], v[98:101]
	v_mfma_f32_16x16x32_bf16 v[94:97], v[74:77], v[214:217], v[94:97]
	v_mfma_f32_16x16x32_bf16 v[158:161], v[62:65], v[166:169], v[158:161]
	v_mfma_f32_16x16x32_bf16 v[154:157], v[78:81], v[166:169], v[154:157]
	v_mfma_f32_16x16x32_bf16 v[142:145], v[62:65], v[202:205], v[142:145]
	v_mfma_f32_16x16x32_bf16 v[138:141], v[78:81], v[202:205], v[138:141]
	v_mfma_f32_16x16x32_bf16 v[122:125], v[62:65], v[210:213], v[122:125]
	v_mfma_f32_16x16x32_bf16 v[118:121], v[78:81], v[210:213], v[118:121]
	v_mfma_f32_16x16x32_bf16 v[98:101], v[62:65], v[232:235], v[98:101]
	v_mfma_f32_16x16x32_bf16 v[94:97], v[78:81], v[232:235], v[94:97]
	v_mfma_f32_16x16x32_bf16 v[150:153], v[90:93], v[162:165], v[150:153]
	v_mfma_f32_16x16x32_bf16 v[146:149], v[114:117], v[162:165], v[146:149]
	v_mfma_f32_16x16x32_bf16 v[134:137], v[90:93], v[198:201], v[134:137]
	v_mfma_f32_16x16x32_bf16 v[130:133], v[114:117], v[198:201], v[130:133]
	v_mfma_f32_16x16x32_bf16 v[110:113], v[90:93], v[206:209], v[110:113]
	v_mfma_f32_16x16x32_bf16 v[106:109], v[114:117], v[206:209], v[106:109]
	v_mfma_f32_16x16x32_bf16 v[86:89], v[90:93], v[214:217], v[86:89]
	v_mfma_f32_16x16x32_bf16 v[82:85], v[114:117], v[214:217], v[82:85]
	v_mfma_f32_16x16x32_bf16 v[150:153], v[102:105], v[166:169], v[150:153]
	v_mfma_f32_16x16x32_bf16 v[146:149], v[126:129], v[166:169], v[146:149]
	v_mfma_f32_16x16x32_bf16 v[134:137], v[102:105], v[202:205], v[134:137]
	v_mfma_f32_16x16x32_bf16 v[130:133], v[126:129], v[202:205], v[130:133]
	v_mfma_f32_16x16x32_bf16 v[110:113], v[102:105], v[210:213], v[110:113]
	v_mfma_f32_16x16x32_bf16 v[106:109], v[126:129], v[210:213], v[106:109]
	v_mfma_f32_16x16x32_bf16 v[86:89], v[102:105], v[232:235], v[86:89]
	v_mfma_f32_16x16x32_bf16 v[82:85], v[126:129], v[232:235], v[82:85]
	s_barrier
	s_setprio 0
	s_add_i32 s6, s63, s2
	v_lshl_add_u64 v[236:237], s[10:11], 0, v[0:1]
	s_mov_b32 m0, s6
	ds_read_b128 v[162:165], v230 offset:16384
	ds_read_b128 v[166:169], v230 offset:17408
	ds_read_b128 v[198:201], v230 offset:18432
	ds_read_b128 v[202:205], v230 offset:19456
	ds_read_b128 v[206:209], v230 offset:20480
	ds_read_b128 v[210:213], v230 offset:21504
	ds_read_b128 v[214:217], v230 offset:22528
	ds_read_b128 v[232:235], v230 offset:23552
	global_load_lds_dwordx4 v[236:237], off
	s_add_i32 m0, s6, 0x2000
	s_add_u32 s6, s10, 0x160000
	v_lshl_add_u64 v[238:239], s[10:11], 0, v[188:189]
	s_addc_u32 s7, s11, 0
	s_add_i32 s63, vcc_lo, s2
	global_load_lds_dwordx4 v[238:239], off
	v_lshl_add_u64 v[240:241], s[6:7], 0, v[0:1]
	s_mov_b32 m0, s63
	v_lshl_add_u64 v[242:243], s[58:59], 0, v[190:191]
	global_load_lds_dwordx4 v[240:241], off
	v_lshl_add_u64 v[240:241], s[6:7], 0, v[188:189]
	s_add_i32 m0, s63, 0x2000
	s_nop 0
	global_load_lds_dwordx4 v[240:241], off
	s_waitcnt vmcnt(6)
	s_waitcnt lgkmcnt(0)
	s_setprio 1
	s_barrier
; #define PG8_STAGE(bufoff, gbase, voff) do { _Pragma("unroll") for (int _i = 0; _i < 2; ++_i) \
;         __builtin_amdgcn_global_load_lds((const unsigned*)((const char*)(gbase) + (voff)[_i]), (PG8_LAS unsigned*)(lds + (bufoff) + ldsw + _i * 8192), 16, 0, 0); } while (0)
; #define PG8_LDA(dst, b, h) do { _Pragma("unroll") for (int m = 0; m < 4; ++m) _Pragma("unroll") for (int k = 0; k < 2; ++k) dst[m][k] = *(const PG8_LAS bf16x8*)(lds + PG8_SA(b, h) + aoff + m * 2048 + k * 1024); } while (0)
; #define PG8_LDB(dst, b, h) do { _Pragma("unroll") for (int n = 0; n < 2; ++n) _Pragma("unroll") for (int k = 0; k < 2; ++k) dst[n][k] = *(const PG8_LAS bf16x8*)(lds + PG8_SB(b, h) + boff + n * 2048 + k * 1024); } while (0)
; #define PG8_MMA(ai, bj, At, Bt) do { __builtin_amdgcn_s_setprio(1); _Pragma("unroll") for (int m = 0; m < 4; ++m) _Pragma("unroll") for (int n = 0; n < 2; ++n) _Pragma("unroll") for (int k = 0; k < 2; ++k) \
;         acc[ai][bj][m][n] = __builtin_amdgcn_mfma_f32_16x16x32_bf16(Bt[n][k], At[m][k], acc[ai][bj][m][n], 0, 0, 0); __builtin_amdgcn_s_setprio(0); } while (0)
; #define PG8_WAIT_V(n) asm volatile("s_waitcnt vmcnt(" #n ")" ::: "memory")
; #define PG8_WAIT_L(n) asm volatile("s_waitcnt lgkmcnt(" #n ")" ::: "memory")
; #define PG8_BAR __builtin_amdgcn_s_barrier()
; #define PG8_SCHED __builtin_amdgcn_sched_barrier(0)
; template <class Epi, class Sched, bool ALIGN_EPI = false, bool SP2 = false>
; __device__ __forceinline__ void gemm_phase(PG8_LAS unsigned char* lds, const Gemm g, const Sched& S, const Epi& E) {
;     ...
;             PG8_WAIT_V(8); PG8_WAIT_L(0); PG8_BAR; PG8_MMA(1, 0, At, B0); PG8_MMA(1, 1, At, B1); PG8_BAR; PG8_SCHED;
;             PG8_LDB(B0, 1, 0); PG8_LDB(B1, 1, 1); PG8_SCHED; PG8_LDA(At, 1, 0); PG8_STAGE(PG8_SA(0, 1), a2 + hstep, voffA);
;             PG8_WAIT_V(8); PG8_WAIT_L(0); PG8_BAR; PG8_MMA(0, 0, At, B0); PG8_MMA(0, 1, At, B1); PG8_BAR; PG8_SCHED;
;             PG8_LDA(At, 1, 1); PG8_STAGE(PG8_SB(1, 0), b3, voffB); PG8_STAGE(PG8_SB(1, 1), b3 + hstep, voffB); PG8_STAGE(PG8_SA(1, 0), a3, voffA);
	v_mfma_f32_16x16x32_bf16 v[70:73], v[50:53], v[162:165], v[70:73]
	v_mfma_f32_16x16x32_bf16 v[66:69], v[74:77], v[162:165], v[66:69]
	v_mfma_f32_16x16x32_bf16 v[46:49], v[50:53], v[198:201], v[46:49]
	v_mfma_f32_16x16x32_bf16 v[42:45], v[74:77], v[198:201], v[42:45]
	v_mfma_f32_16x16x32_bf16 v[30:33], v[50:53], v[206:209], v[30:33]
	v_mfma_f32_16x16x32_bf16 v[26:29], v[74:77], v[206:209], v[26:29]
	v_mfma_f32_16x16x32_bf16 v[14:17], v[50:53], v[214:217], v[14:17]
	v_mfma_f32_16x16x32_bf16 v[10:13], v[74:77], v[214:217], v[10:13]
	v_mfma_f32_16x16x32_bf16 v[70:73], v[62:65], v[166:169], v[70:73]
	v_mfma_f32_16x16x32_bf16 v[66:69], v[78:81], v[166:169], v[66:69]
	v_mfma_f32_16x16x32_bf16 v[46:49], v[62:65], v[202:205], v[46:49]
	v_mfma_f32_16x16x32_bf16 v[42:45], v[78:81], v[202:205], v[42:45]
	v_mfma_f32_16x16x32_bf16 v[30:33], v[62:65], v[210:213], v[30:33]
	v_mfma_f32_16x16x32_bf16 v[26:29], v[78:81], v[210:213], v[26:29]
	v_mfma_f32_16x16x32_bf16 v[14:17], v[62:65], v[232:235], v[14:17]
	v_mfma_f32_16x16x32_bf16 v[10:13], v[78:81], v[232:235], v[10:13]
	v_mfma_f32_16x16x32_bf16 v[54:57], v[114:117], v[162:165], v[54:57]
	v_mfma_f32_16x16x32_bf16 v[38:41], v[90:93], v[198:201], v[38:41]
	v_mfma_f32_16x16x32_bf16 v[34:37], v[114:117], v[198:201], v[34:37]
	v_mfma_f32_16x16x32_bf16 v[22:25], v[90:93], v[206:209], v[22:25]
	v_mfma_f32_16x16x32_bf16 v[18:21], v[114:117], v[206:209], v[18:21]
	v_mfma_f32_16x16x32_bf16 v[6:9], v[90:93], v[214:217], v[6:9]
	v_mfma_f32_16x16x32_bf16 v[2:5], v[114:117], v[214:217], v[2:5]
	v_mfma_f32_16x16x32_bf16 v[50:53], v[90:93], v[162:165], v[58:61]
	v_mfma_f32_16x16x32_bf16 v[54:57], v[126:129], v[166:169], v[54:57]
	v_mfma_f32_16x16x32_bf16 v[38:41], v[102:105], v[202:205], v[38:41]
	v_mfma_f32_16x16x32_bf16 v[34:37], v[126:129], v[202:205], v[34:37]
	v_mfma_f32_16x16x32_bf16 v[22:25], v[102:105], v[210:213], v[22:25]
	v_mfma_f32_16x16x32_bf16 v[18:21], v[126:129], v[210:213], v[18:21]
	v_mfma_f32_16x16x32_bf16 v[6:9], v[102:105], v[232:235], v[6:9]
	v_mfma_f32_16x16x32_bf16 v[2:5], v[126:129], v[232:235], v[2:5]
	v_mfma_f32_16x16x32_bf16 v[50:53], v[102:105], v[166:169], v[50:53]
	s_barrier
	s_setprio 0
	v_lshl_add_u64 v[240:241], s[58:59], 0, v[192:193]
	s_mov_b32 m0, s24
	s_nop 0
	global_load_lds_dwordx4 v[240:241], off
	s_mov_b32 m0, s25
	s_nop 0
	global_load_lds_dwordx4 v[242:243], off
	s_add_i32 s63, 0, 0x18000
	s_add_i32 vcc_lo, 0, 0x1c000
	v_add_u32_e32 v78, s63, v228
	v_add_u32_e32 v126, vcc_lo, v228
	ds_read_b128 v[58:61], v78
	ds_read_b128 v[62:65], v78 offset:1024
	ds_read_b128 v[74:77], v78 offset:2048
	ds_read_b128 v[78:81], v78 offset:3072
	ds_read_b128 v[90:93], v126
	ds_read_b128 v[102:105], v126 offset:1024
	ds_read_b128 v[114:117], v126 offset:2048
	ds_read_b128 v[126:129], v126 offset:3072
	s_add_u32 s6, s58, 0x160000
	s_addc_u32 s7, s59, 0
	s_mov_b32 m0, s26
	v_lshl_add_u64 v[244:245], s[6:7], 0, v[192:193]
	ds_read_b128 v[162:165], v230 offset:32768
	ds_read_b128 v[166:169], v230 offset:33792
	ds_read_b128 v[198:201], v230 offset:34816
	ds_read_b128 v[202:205], v230 offset:35840
	ds_read_b128 v[206:209], v230 offset:36864
	ds_read_b128 v[210:213], v230 offset:37888
	ds_read_b128 v[214:217], v230 offset:38912
	ds_read_b128 v[232:235], v230 offset:39936
	global_load_lds_dwordx4 v[244:245], off
	v_lshl_add_u64 v[244:245], s[6:7], 0, v[190:191]
	s_mov_b32 m0, s27
	s_nop 0
	global_load_lds_dwordx4 v[244:245], off
	s_waitcnt vmcnt(8)
	s_waitcnt lgkmcnt(0)
	s_setprio 1
	s_barrier
	v_mfma_f32_16x16x32_bf16 v[158:161], v[58:61], v[162:165], v[158:161]
	v_mfma_f32_16x16x32_bf16 v[154:157], v[74:77], v[162:165], v[154:157]
	v_mfma_f32_16x16x32_bf16 v[142:145], v[58:61], v[198:201], v[142:145]
	v_mfma_f32_16x16x32_bf16 v[138:141], v[74:77], v[198:201], v[138:141]
	v_mfma_f32_16x16x32_bf16 v[122:125], v[58:61], v[206:209], v[122:125]
	v_mfma_f32_16x16x32_bf16 v[118:121], v[74:77], v[206:209], v[118:121]
	v_mfma_f32_16x16x32_bf16 v[98:101], v[58:61], v[214:217], v[98:101]
	v_mfma_f32_16x16x32_bf16 v[94:97], v[74:77], v[214:217], v[94:97]
	v_mfma_f32_16x16x32_bf16 v[158:161], v[62:65], v[166:169], v[158:161]
	v_mfma_f32_16x16x32_bf16 v[154:157], v[78:81], v[166:169], v[154:157]
	v_mfma_f32_16x16x32_bf16 v[142:145], v[62:65], v[202:205], v[142:145]
	v_mfma_f32_16x16x32_bf16 v[138:141], v[78:81], v[202:205], v[138:141]
	v_mfma_f32_16x16x32_bf16 v[122:125], v[62:65], v[210:213], v[122:125]
	v_mfma_f32_16x16x32_bf16 v[118:121], v[78:81], v[210:213], v[118:121]
	v_mfma_f32_16x16x32_bf16 v[98:101], v[62:65], v[232:235], v[98:101]
	v_mfma_f32_16x16x32_bf16 v[94:97], v[78:81], v[232:235], v[94:97]
	v_mfma_f32_16x16x32_bf16 v[150:153], v[90:93], v[162:165], v[150:153]
	v_mfma_f32_16x16x32_bf16 v[146:149], v[114:117], v[162:165], v[146:149]
	v_mfma_f32_16x16x32_bf16 v[134:137], v[90:93], v[198:201], v[134:137]
	v_mfma_f32_16x16x32_bf16 v[130:133], v[114:117], v[198:201], v[130:133]
	v_mfma_f32_16x16x32_bf16 v[110:113], v[90:93], v[206:209], v[110:113]
	v_mfma_f32_16x16x32_bf16 v[106:109], v[114:117], v[206:209], v[106:109]
	v_mfma_f32_16x16x32_bf16 v[86:89], v[90:93], v[214:217], v[86:89]
	v_mfma_f32_16x16x32_bf16 v[82:85], v[114:117], v[214:217], v[82:85]
	v_mfma_f32_16x16x32_bf16 v[150:153], v[102:105], v[166:169], v[150:153]
	v_mfma_f32_16x16x32_bf16 v[146:149], v[126:129], v[166:169], v[146:149]
	v_mfma_f32_16x16x32_bf16 v[134:137], v[102:105], v[202:205], v[134:137]
	v_mfma_f32_16x16x32_bf16 v[130:133], v[126:129], v[202:205], v[130:133]
	v_mfma_f32_16x16x32_bf16 v[110:113], v[102:105], v[210:213], v[110:113]
	v_mfma_f32_16x16x32_bf16 v[106:109], v[126:129], v[210:213], v[106:109]
	v_mfma_f32_16x16x32_bf16 v[86:89], v[102:105], v[232:235], v[86:89]
	v_mfma_f32_16x16x32_bf16 v[82:85], v[126:129], v[232:235], v[82:85]
	s_barrier
; #define PG8_STAGE(bufoff, gbase, voff) do { _Pragma("unroll") for (int _i = 0; _i < 2; ++_i) \
;         __builtin_amdgcn_global_load_lds((const unsigned*)((const char*)(gbase) + (voff)[_i]), (PG8_LAS unsigned*)(lds + (bufoff) + ldsw + _i * 8192), 16, 0, 0); } while (0)
; #define PG8_LDA(dst, b, h) do { _Pragma("unroll") for (int m = 0; m < 4; ++m) _Pragma("unroll") for (int k = 0; k < 2; ++k) dst[m][k] = *(const PG8_LAS bf16x8*)(lds + PG8_SA(b, h) + aoff + m * 2048 + k * 1024); } while (0)
; #define PG8_MMA(ai, bj, At, Bt) do { __builtin_amdgcn_s_setprio(1); _Pragma("unroll") for (int m = 0; m < 4; ++m) _Pragma("unroll") for (int n = 0; n < 2; ++n) _Pragma("unroll") for (int k = 0; k < 2; ++k) \
;         acc[ai][bj][m][n] = __builtin_amdgcn_mfma_f32_16x16x32_bf16(Bt[n][k], At[m][k], acc[ai][bj][m][n], 0, 0, 0); __builtin_amdgcn_s_setprio(0); } while (0)
; #define PG8_WAIT_V(n) asm volatile("s_waitcnt vmcnt(" #n ")" ::: "memory")
; #define PG8_WAIT_L(n) asm volatile("s_waitcnt lgkmcnt(" #n ")" ::: "memory")
; #define PG8_BAR __builtin_amdgcn_s_barrier()
; #define PG8_SCHED __builtin_amdgcn_sched_barrier(0)
; template <class Epi, class Sched, bool ALIGN_EPI = false, bool SP2 = false>
; __device__ __forceinline__ void gemm_phase(PG8_LAS unsigned char* lds, const Gemm g, const Sched& S, const Epi& E) {
;     ...
;             PG8_WAIT_V(8); PG8_WAIT_L(0); PG8_BAR; PG8_MMA(0, 0, At, B0); PG8_MMA(0, 1, At, B1); PG8_BAR; PG8_SCHED;
;             PG8_LDA(At, 1, 1); PG8_STAGE(PG8_SB(1, 0), b3, voffB); PG8_STAGE(PG8_SB(1, 1), b3 + hstep, voffB); PG8_STAGE(PG8_SA(1, 0), a3, voffA);
;             PG8_WAIT_V(8); PG8_WAIT_L(0); PG8_BAR; PG8_MMA(1, 0, At, B0); PG8_MMA(1, 1, At, B1); PG8_BAR; PG8_SCHED;
	s_setprio 0
	s_add_i32 s6, s63, s2
	v_lshl_add_u64 v[236:237], v[236:237], 0, s[88:89]
	s_mov_b32 m0, s6
	ds_read_b128 v[162:165], v230 offset:49152
	ds_read_b128 v[166:169], v230 offset:50176
	ds_read_b128 v[198:201], v230 offset:51200
	ds_read_b128 v[202:205], v230 offset:52224
	ds_read_b128 v[206:209], v230 offset:53248
	ds_read_b128 v[210:213], v230 offset:54272
	ds_read_b128 v[214:217], v230 offset:55296
	ds_read_b128 v[232:235], v230 offset:56320
	global_load_lds_dwordx4 v[236:237], off
	s_add_i32 m0, s6, 0x2000
	s_add_u32 s6, s10, 0x160080
	v_lshl_add_u64 v[236:237], v[238:239], 0, s[88:89]
	s_addc_u32 s7, s11, 0
	s_add_i32 s10, vcc_lo, s2
	global_load_lds_dwordx4 v[236:237], off
	v_lshl_add_u64 v[236:237], s[6:7], 0, v[0:1]
	s_mov_b32 m0, s10
	s_nop 0
	global_load_lds_dwordx4 v[236:237], off
	v_lshl_add_u64 v[236:237], s[6:7], 0, v[188:189]
	s_add_i32 m0, s10, 0x2000
	s_nop 0
	global_load_lds_dwordx4 v[236:237], off
	v_lshl_add_u64 v[236:237], v[240:241], 0, s[88:89]
	s_mov_b32 m0, s28
	s_nop 0
	global_load_lds_dwordx4 v[236:237], off
	v_lshl_add_u64 v[236:237], v[242:243], 0, s[88:89]
	s_mov_b32 m0, s29
	s_nop 0
	global_load_lds_dwordx4 v[236:237], off
	s_waitcnt vmcnt(8)
	s_waitcnt lgkmcnt(0)
	s_setprio 1
	s_barrier
	v_mfma_f32_16x16x32_bf16 v[70:73], v[58:61], v[162:165], v[70:73]
	v_mfma_f32_16x16x32_bf16 v[66:69], v[74:77], v[162:165], v[66:69]
	v_mfma_f32_16x16x32_bf16 v[46:49], v[58:61], v[198:201], v[46:49]
	v_mfma_f32_16x16x32_bf16 v[42:45], v[74:77], v[198:201], v[42:45]
	v_mfma_f32_16x16x32_bf16 v[30:33], v[58:61], v[206:209], v[30:33]
	v_mfma_f32_16x16x32_bf16 v[26:29], v[74:77], v[206:209], v[26:29]
	v_mfma_f32_16x16x32_bf16 v[14:17], v[58:61], v[214:217], v[14:17]
	v_mfma_f32_16x16x32_bf16 v[10:13], v[74:77], v[214:217], v[10:13]
	v_mfma_f32_16x16x32_bf16 v[70:73], v[62:65], v[166:169], v[70:73]
	v_mfma_f32_16x16x32_bf16 v[66:69], v[78:81], v[166:169], v[66:69]
	v_mfma_f32_16x16x32_bf16 v[46:49], v[62:65], v[202:205], v[46:49]
	v_mfma_f32_16x16x32_bf16 v[42:45], v[78:81], v[202:205], v[42:45]
	v_mfma_f32_16x16x32_bf16 v[30:33], v[62:65], v[210:213], v[30:33]
	v_mfma_f32_16x16x32_bf16 v[26:29], v[78:81], v[210:213], v[26:29]
	v_mfma_f32_16x16x32_bf16 v[14:17], v[62:65], v[232:235], v[14:17]
	v_mfma_f32_16x16x32_bf16 v[10:13], v[78:81], v[232:235], v[10:13]
	v_mfma_f32_16x16x32_bf16 v[50:53], v[90:93], v[162:165], v[50:53]
	v_mfma_f32_16x16x32_bf16 v[58:61], v[102:105], v[166:169], v[50:53]
	v_mfma_f32_16x16x32_bf16 v[50:53], v[114:117], v[162:165], v[54:57]
	v_mfma_f32_16x16x32_bf16 v[38:41], v[90:93], v[198:201], v[38:41]
	v_mfma_f32_16x16x32_bf16 v[34:37], v[114:117], v[198:201], v[34:37]
	v_mfma_f32_16x16x32_bf16 v[22:25], v[90:93], v[206:209], v[22:25]
	v_mfma_f32_16x16x32_bf16 v[18:21], v[114:117], v[206:209], v[18:21]
	v_mfma_f32_16x16x32_bf16 v[6:9], v[90:93], v[214:217], v[6:9]
	v_mfma_f32_16x16x32_bf16 v[2:5], v[114:117], v[214:217], v[2:5]
	v_mfma_f32_16x16x32_bf16 v[54:57], v[126:129], v[166:169], v[50:53]
	v_mfma_f32_16x16x32_bf16 v[38:41], v[102:105], v[202:205], v[38:41]
	v_mfma_f32_16x16x32_bf16 v[34:37], v[126:129], v[202:205], v[34:37]
	v_mfma_f32_16x16x32_bf16 v[22:25], v[102:105], v[210:213], v[22:25]
	v_mfma_f32_16x16x32_bf16 v[18:21], v[126:129], v[210:213], v[18:21]
	v_mfma_f32_16x16x32_bf16 v[6:9], v[102:105], v[232:235], v[6:9]
	v_mfma_f32_16x16x32_bf16 v[2:5], v[126:129], v[232:235], v[2:5]
	s_barrier
	s_setprio 0
	s_add_i32 s62, s62, 2
	s_add_u32 s60, s60, 0x100
	s_addc_u32 s61, s61, 0
	s_cmpk_gt_u32 s62, 0x55
	s_mov_b64 s[6:7], s[8:9]
	s_cbranch_scc0 .LBB0_795
	s_and_b64 vcc, exec, s[78:79]
	s_cbranch_vccz .LBB0_798
	s_barrier

; #define PG8_STAGE(bufoff, gbase, voff) do { _Pragma("unroll") for (int _i = 0; _i < 2; ++_i) \
;         __builtin_amdgcn_global_load_lds((const unsigned*)((const char*)(gbase) + (voff)[_i]), (PG8_LAS unsigned*)(lds + (bufoff) + ldsw + _i * 8192), 16, 0, 0); } while (0)
; #define PG8_LDA(dst, b, h) do { _Pragma("unroll") for (int m = 0; m < 4; ++m) _Pragma("unroll") for (int k = 0; k < 2; ++k) dst[m][k] = *(const PG8_LAS bf16x8*)(lds + PG8_SA(b, h) + aoff + m * 2048 + k * 1024); } while (0)
; #define PG8_LDB(dst, b, h) do { _Pragma("unroll") for (int n = 0; n < 2; ++n) _Pragma("unroll") for (int k = 0; k < 2; ++k) dst[n][k] = *(const PG8_LAS bf16x8*)(lds + PG8_SB(b, h) + boff + n * 2048 + k * 1024); } while (0)
; #define PG8_MMA(ai, bj, At, Bt) do { __builtin_amdgcn_s_setprio(1); _Pragma("unroll") for (int m = 0; m < 4; ++m) _Pragma("unroll") for (int n = 0; n < 2; ++n) _Pragma("unroll") for (int k = 0; k < 2; ++k) \
;         acc[ai][bj][m][n] = __builtin_amdgcn_mfma_f32_16x16x32_bf16(Bt[n][k], At[m][k], acc[ai][bj][m][n], 0, 0, 0); __builtin_amdgcn_s_setprio(0); } while (0)
; #define PG8_WAIT_V(n) asm volatile("s_waitcnt vmcnt(" #n ")" ::: "memory")
; #define PG8_BAR __builtin_amdgcn_s_barrier()
; template <class Epi, class Sched, bool ALIGN_EPI = false, bool SP2 = false>
; __device__ __forceinline__ void gemm_phase(PG8_LAS unsigned char* lds, const Gemm g, const Sched& S, const Epi& E) {
;     ...
;         for (int t = 0; t < nt; t += 2) {
;             const bool last = (t == nt - 2);
;             const char* a1 = cA + (size_t)(t + 1) * kstep;
;             const char* a2 = last ? nA : cA + (size_t)(t + 2) * kstep; const char* b2 = last ? nB : cB + (size_t)(t + 2) * kstep;
;             const char* a3 = a2 + kstep; const char* b3 = b2 + kstep;
;             if (last && has_next) S.a_ready(nxt);
;             if constexpr (SP2) {
;             PG8_LDB(B0, 0, 0); PG8_LDB(B1, 0, 1); PG8_SCHED; PG8_LDA(At, 0, 0); PG8_STAGE(PG8_SA(1, 1), a1 + hstep, voffA);
;             PG8_WAIT_V(8); PG8_WAIT_L(0); PG8_BAR; PG8_MMA(0, 0, At, B0); PG8_MMA(0, 1, At, B1); PG8_BAR; PG8_SCHED;
;             PG8_LDA(At, 0, 1); PG8_STAGE(PG8_SB(0, 0), b2, voffB); PG8_STAGE(PG8_SB(0, 1), b2 + hstep, voffB); PG8_STAGE(PG8_SA(0, 0), a2, voffA);
;             PG8_WAIT_V(8); PG8_WAIT_L(0); PG8_BAR; PG8_MMA(1, 0, At, B0); PG8_MMA(1, 1, At, B1); PG8_BAR; PG8_SCHED;
.LBB0_982:
	s_add_u32 s6, s4, 0xfff80080
	s_addc_u32 s7, s5, -1
	s_add_i32 s81, 0, 0x10000
	s_cmp_eq_u32 s79, 28
	s_cselect_b32 s9, s18, s7
	s_cselect_b32 s8, s60, s6
	v_add_u32_e32 v0, s81, v161
	s_cselect_b32 s7, s61, s65
	s_cselect_b32 s6, s62, s63
	s_add_i32 s36, 0, 0x14000
	ds_read_b128 v[144:147], v0
	ds_read_b128 v[148:151], v0 offset:1024
	ds_read_b128 v[152:155], v0 offset:2048
	ds_read_b128 v[156:159], v0 offset:3072
	v_add_u32_e32 v0, s36, v161
	ds_read_b128 v[166:169], v0
	ds_read_b128 v[188:191], v0 offset:1024
	ds_read_b128 v[192:195], v0 offset:2048
	ds_read_b128 v[196:199], v0 offset:3072
	v_lshl_add_u64 v[216:217], s[4:5], 0, v[140:141]
	s_add_i32 m0, s24, 0xc000
	ds_read_b128 v[200:203], v165
	ds_read_b128 v[204:207], v165 offset:1024
	ds_read_b128 v[208:211], v165 offset:2048
	ds_read_b128 v[212:215], v165 offset:3072
	ds_read_b128 v[228:231], v165 offset:4096
	ds_read_b128 v[232:235], v165 offset:5120
	ds_read_b128 v[236:239], v165 offset:6144
	ds_read_b128 v[240:243], v165 offset:7168
	global_load_lds_dwordx4 v[216:217], off
	v_lshl_add_u64 v[216:217], s[4:5], 0, v[142:143]
	s_add_i32 m0, s24, 0xe000
	s_nop 0
	global_load_lds_dwordx4 v[216:217], off
	s_waitcnt vmcnt(8)
	s_waitcnt lgkmcnt(0)
	s_setprio 1
	s_barrier
	v_mfma_f32_16x16x32_bf16 v[126:129], v[144:147], v[200:203], v[126:129]
	v_mfma_f32_16x16x32_bf16 v[122:125], v[152:155], v[200:203], v[122:125]
	v_mfma_f32_16x16x32_bf16 v[110:113], v[144:147], v[208:211], v[110:113]
	v_mfma_f32_16x16x32_bf16 v[106:109], v[152:155], v[208:211], v[106:109]
	v_mfma_f32_16x16x32_bf16 v[94:97], v[144:147], v[228:231], v[94:97]
	v_mfma_f32_16x16x32_bf16 v[90:93], v[152:155], v[228:231], v[90:93]
	v_mfma_f32_16x16x32_bf16 v[78:81], v[144:147], v[236:239], v[78:81]
	v_mfma_f32_16x16x32_bf16 v[74:77], v[152:155], v[236:239], v[74:77]
	v_mfma_f32_16x16x32_bf16 v[126:129], v[148:151], v[204:207], v[126:129]
	v_mfma_f32_16x16x32_bf16 v[122:125], v[156:159], v[204:207], v[122:125]
	v_mfma_f32_16x16x32_bf16 v[110:113], v[148:151], v[212:215], v[110:113]
	v_mfma_f32_16x16x32_bf16 v[106:109], v[156:159], v[212:215], v[106:109]
	v_mfma_f32_16x16x32_bf16 v[94:97], v[148:151], v[232:235], v[94:97]
	v_mfma_f32_16x16x32_bf16 v[90:93], v[156:159], v[232:235], v[90:93]
	v_mfma_f32_16x16x32_bf16 v[78:81], v[148:151], v[240:243], v[78:81]
	v_mfma_f32_16x16x32_bf16 v[74:77], v[156:159], v[240:243], v[74:77]
	v_mfma_f32_16x16x32_bf16 v[118:121], v[166:169], v[200:203], v[118:121]
	v_mfma_f32_16x16x32_bf16 v[114:117], v[192:195], v[200:203], v[114:117]
	v_mfma_f32_16x16x32_bf16 v[102:105], v[166:169], v[208:211], v[102:105]
	v_mfma_f32_16x16x32_bf16 v[98:101], v[192:195], v[208:211], v[98:101]
	v_mfma_f32_16x16x32_bf16 v[86:89], v[166:169], v[228:231], v[86:89]
	v_mfma_f32_16x16x32_bf16 v[82:85], v[192:195], v[228:231], v[82:85]
	v_mfma_f32_16x16x32_bf16 v[70:73], v[166:169], v[236:239], v[70:73]
	v_mfma_f32_16x16x32_bf16 v[66:69], v[192:195], v[236:239], v[66:69]
	v_mfma_f32_16x16x32_bf16 v[118:121], v[188:191], v[204:207], v[118:121]
	v_mfma_f32_16x16x32_bf16 v[114:117], v[196:199], v[204:207], v[114:117]
	v_mfma_f32_16x16x32_bf16 v[102:105], v[188:191], v[212:215], v[102:105]
	v_mfma_f32_16x16x32_bf16 v[98:101], v[196:199], v[212:215], v[98:101]
	v_mfma_f32_16x16x32_bf16 v[86:89], v[188:191], v[232:235], v[86:89]
	v_mfma_f32_16x16x32_bf16 v[82:85], v[196:199], v[232:235], v[82:85]
	v_mfma_f32_16x16x32_bf16 v[70:73], v[188:191], v[240:243], v[70:73]
	v_mfma_f32_16x16x32_bf16 v[66:69], v[196:199], v[240:243], v[66:69]
	s_barrier
	s_setprio 0
	s_add_i32 s37, s81, s75
	v_lshl_add_u64 v[216:217], s[6:7], 0, v[132:133]
	s_mov_b32 m0, s37
	ds_read_b128 v[200:203], v165 offset:16384
	ds_read_b128 v[204:207], v165 offset:17408
	ds_read_b128 v[208:211], v165 offset:18432
	ds_read_b128 v[212:215], v165 offset:19456
	ds_read_b128 v[228:231], v165 offset:20480
	ds_read_b128 v[232:235], v165 offset:21504
	ds_read_b128 v[236:239], v165 offset:22528
	ds_read_b128 v[240:243], v165 offset:23552
	global_load_lds_dwordx4 v[216:217], off
	s_add_i32 m0, s37, 0x2000
	s_add_u32 vcc_lo, s6, 0x80000
	v_lshl_add_u64 v[244:245], s[6:7], 0, v[136:137]
	s_addc_u32 vcc_hi, s7, 0
	s_add_i32 s36, s36, s75
	global_load_lds_dwordx4 v[244:245], off
	v_lshl_add_u64 v[246:247], vcc, 0, v[132:133]
	s_mov_b32 m0, s36
	v_lshl_add_u64 v[248:249], s[8:9], 0, v[134:135]
	global_load_lds_dwordx4 v[246:247], off
	v_lshl_add_u64 v[246:247], vcc, 0, v[136:137]
	s_add_i32 m0, s36, 0x2000
	s_nop 0
	global_load_lds_dwordx4 v[246:247], off
	s_waitcnt vmcnt(6)
	s_waitcnt lgkmcnt(0)
	s_setprio 1
	s_barrier
; #define PG8_STAGE(bufoff, gbase, voff) do { _Pragma("unroll") for (int _i = 0; _i < 2; ++_i) \
;         __builtin_amdgcn_global_load_lds((const unsigned*)((const char*)(gbase) + (voff)[_i]), (PG8_LAS unsigned*)(lds + (bufoff) + ldsw + _i * 8192), 16, 0, 0); } while (0)
; #define PG8_LDA(dst, b, h) do { _Pragma("unroll") for (int m = 0; m < 4; ++m) _Pragma("unroll") for (int k = 0; k < 2; ++k) dst[m][k] = *(const PG8_LAS bf16x8*)(lds + PG8_SA(b, h) + aoff + m * 2048 + k * 1024); } while (0)
; #define PG8_LDB(dst, b, h) do { _Pragma("unroll") for (int n = 0; n < 2; ++n) _Pragma("unroll") for (int k = 0; k < 2; ++k) dst[n][k] = *(const PG8_LAS bf16x8*)(lds + PG8_SB(b, h) + boff + n * 2048 + k * 1024); } while (0)
; #define PG8_MMA(ai, bj, At, Bt) do { __builtin_amdgcn_s_setprio(1); _Pragma("unroll") for (int m = 0; m < 4; ++m) _Pragma("unroll") for (int n = 0; n < 2; ++n) _Pragma("unroll") for (int k = 0; k < 2; ++k) \
;         acc[ai][bj][m][n] = __builtin_amdgcn_mfma_f32_16x16x32_bf16(Bt[n][k], At[m][k], acc[ai][bj][m][n], 0, 0, 0); __builtin_amdgcn_s_setprio(0); } while (0)
; #define PG8_WAIT_V(n) asm volatile("s_waitcnt vmcnt(" #n ")" ::: "memory")
; #define PG8_WAIT_L(n) asm volatile("s_waitcnt lgkmcnt(" #n ")" ::: "memory")
; #define PG8_BAR __builtin_amdgcn_s_barrier()
; #define PG8_SCHED __builtin_amdgcn_sched_barrier(0)
; template <class Epi, class Sched, bool ALIGN_EPI = false, bool SP2 = false>
; __device__ __forceinline__ void gemm_phase(PG8_LAS unsigned char* lds, const Gemm g, const Sched& S, const Epi& E) {
;     ...
;             PG8_WAIT_V(8); PG8_WAIT_L(0); PG8_BAR; PG8_MMA(1, 0, At, B0); PG8_MMA(1, 1, At, B1); PG8_BAR; PG8_SCHED;
;             PG8_LDB(B0, 1, 0); PG8_LDB(B1, 1, 1); PG8_SCHED; PG8_LDA(At, 1, 0); PG8_STAGE(PG8_SA(0, 1), a2 + hstep, voffA);
;             PG8_WAIT_V(8); PG8_WAIT_L(0); PG8_BAR; PG8_MMA(0, 0, At, B0); PG8_MMA(0, 1, At, B1); PG8_BAR; PG8_SCHED;
;             PG8_LDA(At, 1, 1); PG8_STAGE(PG8_SB(1, 0), b3, voffB); PG8_STAGE(PG8_SB(1, 1), b3 + hstep, voffB); PG8_STAGE(PG8_SA(1, 0), a3, voffA);
	v_mfma_f32_16x16x32_bf16 v[62:65], v[144:147], v[200:203], v[62:65]
	v_mfma_f32_16x16x32_bf16 v[58:61], v[152:155], v[200:203], v[58:61]
	v_mfma_f32_16x16x32_bf16 v[46:49], v[144:147], v[208:211], v[46:49]
	v_mfma_f32_16x16x32_bf16 v[42:45], v[152:155], v[208:211], v[42:45]
	v_mfma_f32_16x16x32_bf16 v[30:33], v[144:147], v[228:231], v[30:33]
	v_mfma_f32_16x16x32_bf16 v[26:29], v[152:155], v[228:231], v[26:29]
	v_mfma_f32_16x16x32_bf16 v[14:17], v[144:147], v[236:239], v[14:17]
	v_mfma_f32_16x16x32_bf16 v[10:13], v[152:155], v[236:239], v[10:13]
	v_mfma_f32_16x16x32_bf16 v[62:65], v[148:151], v[204:207], v[62:65]
	v_mfma_f32_16x16x32_bf16 v[58:61], v[156:159], v[204:207], v[58:61]
	v_mfma_f32_16x16x32_bf16 v[46:49], v[148:151], v[212:215], v[46:49]
	v_mfma_f32_16x16x32_bf16 v[42:45], v[156:159], v[212:215], v[42:45]
	v_mfma_f32_16x16x32_bf16 v[30:33], v[148:151], v[232:235], v[30:33]
	v_mfma_f32_16x16x32_bf16 v[26:29], v[156:159], v[232:235], v[26:29]
	v_mfma_f32_16x16x32_bf16 v[14:17], v[148:151], v[240:243], v[14:17]
	v_mfma_f32_16x16x32_bf16 v[10:13], v[156:159], v[240:243], v[10:13]
	v_mfma_f32_16x16x32_bf16 v[54:57], v[166:169], v[200:203], v[54:57]
	v_mfma_f32_16x16x32_bf16 v[50:53], v[192:195], v[200:203], v[50:53]
	v_mfma_f32_16x16x32_bf16 v[38:41], v[166:169], v[208:211], v[38:41]
	v_mfma_f32_16x16x32_bf16 v[34:37], v[192:195], v[208:211], v[34:37]
	v_mfma_f32_16x16x32_bf16 v[22:25], v[166:169], v[228:231], v[22:25]
	v_mfma_f32_16x16x32_bf16 v[18:21], v[192:195], v[228:231], v[18:21]
	v_mfma_f32_16x16x32_bf16 v[6:9], v[166:169], v[236:239], v[6:9]
	v_mfma_f32_16x16x32_bf16 v[2:5], v[192:195], v[236:239], v[2:5]
	v_mfma_f32_16x16x32_bf16 v[54:57], v[188:191], v[204:207], v[54:57]
	v_mfma_f32_16x16x32_bf16 v[50:53], v[196:199], v[204:207], v[50:53]
	v_mfma_f32_16x16x32_bf16 v[38:41], v[188:191], v[212:215], v[38:41]
	v_mfma_f32_16x16x32_bf16 v[34:37], v[196:199], v[212:215], v[34:37]
	v_mfma_f32_16x16x32_bf16 v[22:25], v[188:191], v[232:235], v[22:25]
	v_mfma_f32_16x16x32_bf16 v[18:21], v[196:199], v[232:235], v[18:21]
	v_mfma_f32_16x16x32_bf16 v[6:9], v[188:191], v[240:243], v[6:9]
	v_mfma_f32_16x16x32_bf16 v[2:5], v[196:199], v[240:243], v[2:5]
	s_barrier
	s_setprio 0
	v_lshl_add_u64 v[246:247], s[8:9], 0, v[130:131]
	s_mov_b32 m0, s24
	s_nop 0
	global_load_lds_dwordx4 v[246:247], off
	s_mov_b32 m0, s25
	s_nop 0
	global_load_lds_dwordx4 v[248:249], off
	s_add_i32 s36, 0, 0x18000
	v_add_u32_e32 v0, s36, v161
	s_add_i32 s37, 0, 0x1c000
	ds_read_b128 v[144:147], v0
	ds_read_b128 v[148:151], v0 offset:1024
	ds_read_b128 v[152:155], v0 offset:2048
	ds_read_b128 v[156:159], v0 offset:3072
	v_add_u32_e32 v0, s37, v161
	ds_read_b128 v[166:169], v0
	ds_read_b128 v[188:191], v0 offset:1024
	ds_read_b128 v[192:195], v0 offset:2048
	ds_read_b128 v[196:199], v0 offset:3072
	s_add_u32 s8, s8, 0x80000
	s_addc_u32 s9, s9, 0
	s_mov_b32 m0, s26
	v_lshl_add_u64 v[250:251], s[8:9], 0, v[130:131]
	ds_read_b128 v[200:203], v165 offset:32768
	ds_read_b128 v[204:207], v165 offset:33792
	ds_read_b128 v[208:211], v165 offset:34816
	ds_read_b128 v[212:215], v165 offset:35840
	ds_read_b128 v[228:231], v165 offset:36864
	ds_read_b128 v[232:235], v165 offset:37888
	ds_read_b128 v[236:239], v165 offset:38912
	ds_read_b128 v[240:243], v165 offset:39936
	global_load_lds_dwordx4 v[250:251], off
	v_lshl_add_u64 v[250:251], s[8:9], 0, v[134:135]
	s_mov_b32 m0, s27
	s_nop 0
	global_load_lds_dwordx4 v[250:251], off
	s_waitcnt vmcnt(8)
	s_waitcnt lgkmcnt(0)
	s_setprio 1
	s_barrier
	v_mfma_f32_16x16x32_bf16 v[126:129], v[144:147], v[200:203], v[126:129]
	v_mfma_f32_16x16x32_bf16 v[122:125], v[152:155], v[200:203], v[122:125]
	v_mfma_f32_16x16x32_bf16 v[110:113], v[144:147], v[208:211], v[110:113]
	v_mfma_f32_16x16x32_bf16 v[106:109], v[152:155], v[208:211], v[106:109]
	v_mfma_f32_16x16x32_bf16 v[94:97], v[144:147], v[228:231], v[94:97]
	v_mfma_f32_16x16x32_bf16 v[90:93], v[152:155], v[228:231], v[90:93]
	v_mfma_f32_16x16x32_bf16 v[78:81], v[144:147], v[236:239], v[78:81]
	v_mfma_f32_16x16x32_bf16 v[74:77], v[152:155], v[236:239], v[74:77]
	v_mfma_f32_16x16x32_bf16 v[126:129], v[148:151], v[204:207], v[126:129]
	v_mfma_f32_16x16x32_bf16 v[122:125], v[156:159], v[204:207], v[122:125]
	v_mfma_f32_16x16x32_bf16 v[110:113], v[148:151], v[212:215], v[110:113]
	v_mfma_f32_16x16x32_bf16 v[106:109], v[156:159], v[212:215], v[106:109]
	v_mfma_f32_16x16x32_bf16 v[94:97], v[148:151], v[232:235], v[94:97]
	v_mfma_f32_16x16x32_bf16 v[90:93], v[156:159], v[232:235], v[90:93]
	v_mfma_f32_16x16x32_bf16 v[78:81], v[148:151], v[240:243], v[78:81]
	v_mfma_f32_16x16x32_bf16 v[74:77], v[156:159], v[240:243], v[74:77]
	v_mfma_f32_16x16x32_bf16 v[118:121], v[166:169], v[200:203], v[118:121]
	v_mfma_f32_16x16x32_bf16 v[114:117], v[192:195], v[200:203], v[114:117]
	v_mfma_f32_16x16x32_bf16 v[102:105], v[166:169], v[208:211], v[102:105]
	v_mfma_f32_16x16x32_bf16 v[98:101], v[192:195], v[208:211], v[98:101]
	v_mfma_f32_16x16x32_bf16 v[86:89], v[166:169], v[228:231], v[86:89]
	v_mfma_f32_16x16x32_bf16 v[82:85], v[192:195], v[228:231], v[82:85]
	v_mfma_f32_16x16x32_bf16 v[70:73], v[166:169], v[236:239], v[70:73]
	v_mfma_f32_16x16x32_bf16 v[66:69], v[192:195], v[236:239], v[66:69]
	v_mfma_f32_16x16x32_bf16 v[118:121], v[188:191], v[204:207], v[118:121]
	v_mfma_f32_16x16x32_bf16 v[114:117], v[196:199], v[204:207], v[114:117]
	v_mfma_f32_16x16x32_bf16 v[102:105], v[188:191], v[212:215], v[102:105]
	v_mfma_f32_16x16x32_bf16 v[98:101], v[196:199], v[212:215], v[98:101]
	v_mfma_f32_16x16x32_bf16 v[86:89], v[188:191], v[232:235], v[86:89]
	v_mfma_f32_16x16x32_bf16 v[82:85], v[196:199], v[232:235], v[82:85]
	v_mfma_f32_16x16x32_bf16 v[70:73], v[188:191], v[240:243], v[70:73]
	v_mfma_f32_16x16x32_bf16 v[66:69], v[196:199], v[240:243], v[66:69]
	s_barrier
; #define PG8_STAGE(bufoff, gbase, voff) do { _Pragma("unroll") for (int _i = 0; _i < 2; ++_i) \
;         __builtin_amdgcn_global_load_lds((const unsigned*)((const char*)(gbase) + (voff)[_i]), (PG8_LAS unsigned*)(lds + (bufoff) + ldsw + _i * 8192), 16, 0, 0); } while (0)
; #define PG8_LDA(dst, b, h) do { _Pragma("unroll") for (int m = 0; m < 4; ++m) _Pragma("unroll") for (int k = 0; k < 2; ++k) dst[m][k] = *(const PG8_LAS bf16x8*)(lds + PG8_SA(b, h) + aoff + m * 2048 + k * 1024); } while (0)
; #define PG8_MMA(ai, bj, At, Bt) do { __builtin_amdgcn_s_setprio(1); _Pragma("unroll") for (int m = 0; m < 4; ++m) _Pragma("unroll") for (int n = 0; n < 2; ++n) _Pragma("unroll") for (int k = 0; k < 2; ++k) \
;         acc[ai][bj][m][n] = __builtin_amdgcn_mfma_f32_16x16x32_bf16(Bt[n][k], At[m][k], acc[ai][bj][m][n], 0, 0, 0); __builtin_amdgcn_s_setprio(0); } while (0)
; #define PG8_WAIT_V(n) asm volatile("s_waitcnt vmcnt(" #n ")" ::: "memory")
; #define PG8_WAIT_L(n) asm volatile("s_waitcnt lgkmcnt(" #n ")" ::: "memory")
; #define PG8_BAR __builtin_amdgcn_s_barrier()
; #define PG8_SCHED __builtin_amdgcn_sched_barrier(0)
; template <class Epi, class Sched, bool ALIGN_EPI = false, bool SP2 = false>
; __device__ __forceinline__ void gemm_phase(PG8_LAS unsigned char* lds, const Gemm g, const Sched& S, const Epi& E) {
;     ...
;             PG8_WAIT_V(8); PG8_WAIT_L(0); PG8_BAR; PG8_MMA(0, 0, At, B0); PG8_MMA(0, 1, At, B1); PG8_BAR; PG8_SCHED;
;             PG8_LDA(At, 1, 1); PG8_STAGE(PG8_SB(1, 0), b3, voffB); PG8_STAGE(PG8_SB(1, 1), b3 + hstep, voffB); PG8_STAGE(PG8_SA(1, 0), a3, voffA);
;             PG8_WAIT_V(8); PG8_WAIT_L(0); PG8_BAR; PG8_MMA(1, 0, At, B0); PG8_MMA(1, 1, At, B1); PG8_BAR; PG8_SCHED;
	s_setprio 0
	s_add_i32 s8, s36, s75
	v_lshl_add_u64 v[216:217], v[216:217], 0, s[88:89]
	s_mov_b32 m0, s8
	ds_read_b128 v[200:203], v165 offset:49152
	ds_read_b128 v[204:207], v165 offset:50176
	ds_read_b128 v[208:211], v165 offset:51200
	ds_read_b128 v[212:215], v165 offset:52224
	ds_read_b128 v[228:231], v165 offset:53248
	ds_read_b128 v[232:235], v165 offset:54272
	ds_read_b128 v[236:239], v165 offset:55296
	ds_read_b128 v[240:243], v165 offset:56320
	global_load_lds_dwordx4 v[216:217], off
	s_add_i32 m0, s8, 0x2000
	s_add_u32 s6, s6, 0x80080
	v_lshl_add_u64 v[216:217], v[244:245], 0, s[88:89]
	s_addc_u32 s7, s7, 0
	s_add_i32 s8, s37, s75
	global_load_lds_dwordx4 v[216:217], off
	v_lshl_add_u64 v[216:217], s[6:7], 0, v[132:133]
	s_mov_b32 m0, s8
	s_nop 0
	global_load_lds_dwordx4 v[216:217], off
	v_lshl_add_u64 v[216:217], s[6:7], 0, v[136:137]
	s_add_i32 m0, s8, 0x2000
	s_nop 0
	global_load_lds_dwordx4 v[216:217], off
	v_lshl_add_u64 v[216:217], v[246:247], 0, s[88:89]
	s_mov_b32 m0, s28
	s_nop 0
	global_load_lds_dwordx4 v[216:217], off
	v_lshl_add_u64 v[216:217], v[248:249], 0, s[88:89]
	s_mov_b32 m0, s29
	s_nop 0
	global_load_lds_dwordx4 v[216:217], off
	s_waitcnt vmcnt(8)
	s_waitcnt lgkmcnt(0)
	s_setprio 1
	s_barrier
	v_mfma_f32_16x16x32_bf16 v[62:65], v[144:147], v[200:203], v[62:65]
	v_mfma_f32_16x16x32_bf16 v[58:61], v[152:155], v[200:203], v[58:61]
	v_mfma_f32_16x16x32_bf16 v[46:49], v[144:147], v[208:211], v[46:49]
	v_mfma_f32_16x16x32_bf16 v[42:45], v[152:155], v[208:211], v[42:45]
	v_mfma_f32_16x16x32_bf16 v[30:33], v[144:147], v[228:231], v[30:33]
	v_mfma_f32_16x16x32_bf16 v[26:29], v[152:155], v[228:231], v[26:29]
	v_mfma_f32_16x16x32_bf16 v[14:17], v[144:147], v[236:239], v[14:17]
	v_mfma_f32_16x16x32_bf16 v[10:13], v[152:155], v[236:239], v[10:13]
	v_mfma_f32_16x16x32_bf16 v[62:65], v[148:151], v[204:207], v[62:65]
	v_mfma_f32_16x16x32_bf16 v[58:61], v[156:159], v[204:207], v[58:61]
	v_mfma_f32_16x16x32_bf16 v[46:49], v[148:151], v[212:215], v[46:49]
	v_mfma_f32_16x16x32_bf16 v[42:45], v[156:159], v[212:215], v[42:45]
	v_mfma_f32_16x16x32_bf16 v[30:33], v[148:151], v[232:235], v[30:33]
	v_mfma_f32_16x16x32_bf16 v[26:29], v[156:159], v[232:235], v[26:29]
	v_mfma_f32_16x16x32_bf16 v[14:17], v[148:151], v[240:243], v[14:17]
	v_mfma_f32_16x16x32_bf16 v[10:13], v[156:159], v[240:243], v[10:13]
	v_mfma_f32_16x16x32_bf16 v[54:57], v[166:169], v[200:203], v[54:57]
	v_mfma_f32_16x16x32_bf16 v[50:53], v[192:195], v[200:203], v[50:53]
	v_mfma_f32_16x16x32_bf16 v[38:41], v[166:169], v[208:211], v[38:41]
	v_mfma_f32_16x16x32_bf16 v[34:37], v[192:195], v[208:211], v[34:37]
	v_mfma_f32_16x16x32_bf16 v[22:25], v[166:169], v[228:231], v[22:25]
	v_mfma_f32_16x16x32_bf16 v[18:21], v[192:195], v[228:231], v[18:21]
	v_mfma_f32_16x16x32_bf16 v[6:9], v[166:169], v[236:239], v[6:9]
	v_mfma_f32_16x16x32_bf16 v[2:5], v[192:195], v[236:239], v[2:5]
	v_mfma_f32_16x16x32_bf16 v[54:57], v[188:191], v[204:207], v[54:57]
	v_mfma_f32_16x16x32_bf16 v[50:53], v[196:199], v[204:207], v[50:53]
	v_mfma_f32_16x16x32_bf16 v[38:41], v[188:191], v[212:215], v[38:41]
	v_mfma_f32_16x16x32_bf16 v[34:37], v[196:199], v[212:215], v[34:37]
	v_mfma_f32_16x16x32_bf16 v[22:25], v[188:191], v[232:235], v[22:25]
	v_mfma_f32_16x16x32_bf16 v[18:21], v[196:199], v[232:235], v[18:21]
	v_mfma_f32_16x16x32_bf16 v[6:9], v[188:191], v[240:243], v[6:9]
	v_mfma_f32_16x16x32_bf16 v[2:5], v[196:199], v[240:243], v[2:5]
	s_barrier
	s_setprio 0
	s_add_i32 s79, s79, 2
	s_add_u32 s4, s4, 0x100
	s_addc_u32 s5, s5, 0
	s_add_u32 s63, s63, 0x100
	s_addc_u32 s65, s65, 0
	s_cmp_gt_u32 s79, 29
	s_cbranch_scc0 .LBB0_982
	s_and_b64 vcc, exec, s[38:39]
	s_cbranch_vccz .LBB0_985
	s_barrier

; #define PG8_STAGE(bufoff, gbase, voff) do { _Pragma("unroll") for (int _i = 0; _i < 2; ++_i) \
;         __builtin_amdgcn_global_load_lds((const unsigned*)((const char*)(gbase) + (voff)[_i]), (PG8_LAS unsigned*)(lds + (bufoff) + ldsw + _i * 8192), 16, 0, 0); } while (0)
; #define PG8_LDA(dst, b, h) do { _Pragma("unroll") for (int m = 0; m < 4; ++m) _Pragma("unroll") for (int k = 0; k < 2; ++k) dst[m][k] = *(const PG8_LAS bf16x8*)(lds + PG8_SA(b, h) + aoff + m * 2048 + k * 1024); } while (0)
; #define PG8_LDB(dst, b, h) do { _Pragma("unroll") for (int n = 0; n < 2; ++n) _Pragma("unroll") for (int k = 0; k < 2; ++k) dst[n][k] = *(const PG8_LAS bf16x8*)(lds + PG8_SB(b, h) + boff + n * 2048 + k * 1024); } while (0)
; #define PG8_MMA(ai, bj, At, Bt) do { __builtin_amdgcn_s_setprio(1); _Pragma("unroll") for (int m = 0; m < 4; ++m) _Pragma("unroll") for (int n = 0; n < 2; ++n) _Pragma("unroll") for (int k = 0; k < 2; ++k) \
;         acc[ai][bj][m][n] = __builtin_amdgcn_mfma_f32_16x16x32_bf16(Bt[n][k], At[m][k], acc[ai][bj][m][n], 0, 0, 0); __builtin_amdgcn_s_setprio(0); } while (0)
; #define PG8_WAIT_V(n) asm volatile("s_waitcnt vmcnt(" #n ")" ::: "memory")
; #define PG8_BAR __builtin_amdgcn_s_barrier()
; template <class Epi, class Sched, bool ALIGN_EPI = false, bool SP2 = false>
; __device__ __forceinline__ void gemm_phase(PG8_LAS unsigned char* lds, const Gemm g, const Sched& S, const Epi& E) {
;     ...
;         for (int t = 0; t < nt; t += 2) {
;             const bool last = (t == nt - 2);
;             const char* a1 = cA + (size_t)(t + 1) * kstep;
;             const char* a2 = last ? nA : cA + (size_t)(t + 2) * kstep; const char* b2 = last ? nB : cB + (size_t)(t + 2) * kstep;
;             const char* a3 = a2 + kstep; const char* b3 = b2 + kstep;
;             if (last && has_next) S.a_ready(nxt);
;             if constexpr (SP2) {
;             PG8_LDB(B0, 0, 0); PG8_LDB(B1, 0, 1); PG8_SCHED; PG8_LDA(At, 0, 0); PG8_STAGE(PG8_SA(1, 1), a1 + hstep, voffA);
;             PG8_WAIT_V(8); PG8_WAIT_L(0); PG8_BAR; PG8_MMA(0, 0, At, B0); PG8_MMA(0, 1, At, B1); PG8_BAR; PG8_SCHED;
;             PG8_LDA(At, 0, 1); PG8_STAGE(PG8_SB(0, 0), b2, voffB); PG8_STAGE(PG8_SB(0, 1), b2 + hstep, voffB); PG8_STAGE(PG8_SA(0, 0), a2, voffA);
;             PG8_WAIT_V(8); PG8_WAIT_L(0); PG8_BAR; PG8_MMA(1, 0, At, B0); PG8_MMA(1, 1, At, B1); PG8_BAR; PG8_SCHED;
.LBB0_1704:
	s_add_i32 s78, s8, 2
	s_add_u32 s36, s6, 0x80
	s_addc_u32 s9, s7, 0
	s_add_i32 s37, 0, 0x10000
	s_cmp_eq_u32 s68, s8
	s_cselect_b32 s9, s10, s9
	s_cselect_b32 s8, s11, s36
	s_cselect_b32 s81, s59, s75
	s_cselect_b32 s80, s61, s74
	s_add_i32 s36, 0, 0x14000
	v_add_u32_e32 v126, s37, v200
	v_add_u32_e32 v168, s36, v200
	ds_read_b128 v[114:117], v126
	ds_read_b128 v[118:121], v126 offset:1024
	ds_read_b128 v[122:125], v126 offset:2048
	ds_read_b128 v[126:129], v126 offset:3072
	ds_read_b128 v[138:141], v168
	ds_read_b128 v[150:153], v168 offset:1024
	ds_read_b128 v[164:167], v168 offset:2048
	ds_read_b128 v[188:191], v168 offset:3072
	v_lshl_add_u64 v[168:169], s[6:7], 0, v[160:161]
	s_add_i32 m0, s27, 0xc000
	ds_read_b128 v[192:195], v202
	ds_read_b128 v[196:199], v202 offset:1024
	ds_read_b128 v[204:207], v202 offset:2048
	ds_read_b128 v[208:211], v202 offset:3072
	ds_read_b128 v[212:215], v202 offset:4096
	ds_read_b128 v[228:231], v202 offset:5120
	ds_read_b128 v[232:235], v202 offset:6144
	ds_read_b128 v[236:239], v202 offset:7168
	global_load_lds_dwordx4 v[168:169], off
	v_lshl_add_u64 v[168:169], s[6:7], 0, v[162:163]
	s_add_i32 m0, s27, 0xe000
	s_nop 0
	global_load_lds_dwordx4 v[168:169], off
	s_waitcnt vmcnt(8)
	s_waitcnt lgkmcnt(0)
	s_setprio 1
	s_barrier
	v_mfma_f32_16x16x32_bf16 v[146:149], v[114:117], v[192:195], v[146:149]
	v_mfma_f32_16x16x32_bf16 v[142:145], v[122:125], v[192:195], v[142:145]
	v_mfma_f32_16x16x32_bf16 v[110:113], v[114:117], v[204:207], v[110:113]
	v_mfma_f32_16x16x32_bf16 v[106:109], v[122:125], v[204:207], v[106:109]
	v_mfma_f32_16x16x32_bf16 v[94:97], v[114:117], v[212:215], v[94:97]
	v_mfma_f32_16x16x32_bf16 v[90:93], v[122:125], v[212:215], v[90:93]
	v_mfma_f32_16x16x32_bf16 v[78:81], v[114:117], v[232:235], v[78:81]
	v_mfma_f32_16x16x32_bf16 v[74:77], v[122:125], v[232:235], v[74:77]
	v_mfma_f32_16x16x32_bf16 v[146:149], v[118:121], v[196:199], v[146:149]
	v_mfma_f32_16x16x32_bf16 v[142:145], v[126:129], v[196:199], v[142:145]
	v_mfma_f32_16x16x32_bf16 v[110:113], v[118:121], v[208:211], v[110:113]
	v_mfma_f32_16x16x32_bf16 v[106:109], v[126:129], v[208:211], v[106:109]
	v_mfma_f32_16x16x32_bf16 v[94:97], v[118:121], v[228:231], v[94:97]
	v_mfma_f32_16x16x32_bf16 v[90:93], v[126:129], v[228:231], v[90:93]
	v_mfma_f32_16x16x32_bf16 v[78:81], v[118:121], v[236:239], v[78:81]
	v_mfma_f32_16x16x32_bf16 v[74:77], v[126:129], v[236:239], v[74:77]
	v_mfma_f32_16x16x32_bf16 v[134:137], v[138:141], v[192:195], v[134:137]
	v_mfma_f32_16x16x32_bf16 v[130:133], v[164:167], v[192:195], v[130:133]
	v_mfma_f32_16x16x32_bf16 v[102:105], v[138:141], v[204:207], v[102:105]
	v_mfma_f32_16x16x32_bf16 v[98:101], v[164:167], v[204:207], v[98:101]
	v_mfma_f32_16x16x32_bf16 v[86:89], v[138:141], v[212:215], v[86:89]
	v_mfma_f32_16x16x32_bf16 v[82:85], v[164:167], v[212:215], v[82:85]
	v_mfma_f32_16x16x32_bf16 v[70:73], v[138:141], v[232:235], v[70:73]
	v_mfma_f32_16x16x32_bf16 v[66:69], v[164:167], v[232:235], v[66:69]
	v_mfma_f32_16x16x32_bf16 v[134:137], v[150:153], v[196:199], v[134:137]
	v_mfma_f32_16x16x32_bf16 v[130:133], v[188:191], v[196:199], v[130:133]
	v_mfma_f32_16x16x32_bf16 v[102:105], v[150:153], v[208:211], v[102:105]
	v_mfma_f32_16x16x32_bf16 v[98:101], v[188:191], v[208:211], v[98:101]
	v_mfma_f32_16x16x32_bf16 v[86:89], v[150:153], v[228:231], v[86:89]
	v_mfma_f32_16x16x32_bf16 v[82:85], v[188:191], v[228:231], v[82:85]
	v_mfma_f32_16x16x32_bf16 v[70:73], v[150:153], v[236:239], v[70:73]
	v_mfma_f32_16x16x32_bf16 v[66:69], v[188:191], v[236:239], v[66:69]
	s_barrier
	s_setprio 0
	s_add_i32 s37, s37, s25
	v_lshl_add_u64 v[168:169], s[80:81], 0, v[0:1]
	s_mov_b32 m0, s37
	ds_read_b128 v[192:195], v202 offset:16384
	ds_read_b128 v[196:199], v202 offset:17408
	ds_read_b128 v[204:207], v202 offset:18432
	ds_read_b128 v[208:211], v202 offset:19456
	ds_read_b128 v[212:215], v202 offset:20480
	ds_read_b128 v[228:231], v202 offset:21504
	ds_read_b128 v[232:235], v202 offset:22528
	ds_read_b128 v[236:239], v202 offset:23552
	global_load_lds_dwordx4 v[168:169], off
	s_add_i32 m0, s37, 0x2000
	v_lshl_add_u64 v[216:217], s[80:81], 0, v[154:155]
	s_add_u32 s80, s80, s18
	s_addc_u32 s81, s81, 0
	s_add_i32 s36, s36, s25
	global_load_lds_dwordx4 v[216:217], off
	v_lshl_add_u64 v[240:241], s[80:81], 0, v[0:1]
	s_mov_b32 m0, s36
	v_lshl_add_u64 v[242:243], s[80:81], 0, v[154:155]
	global_load_lds_dwordx4 v[240:241], off
	s_add_i32 m0, s36, 0x2000
	v_lshl_add_u64 v[244:245], s[8:9], 0, v[158:159]
	global_load_lds_dwordx4 v[242:243], off
	s_waitcnt vmcnt(6)
	s_waitcnt lgkmcnt(0)
	s_setprio 1
	s_barrier
; #define PG8_STAGE(bufoff, gbase, voff) do { _Pragma("unroll") for (int _i = 0; _i < 2; ++_i) \
;         __builtin_amdgcn_global_load_lds((const unsigned*)((const char*)(gbase) + (voff)[_i]), (PG8_LAS unsigned*)(lds + (bufoff) + ldsw + _i * 8192), 16, 0, 0); } while (0)
; #define PG8_LDA(dst, b, h) do { _Pragma("unroll") for (int m = 0; m < 4; ++m) _Pragma("unroll") for (int k = 0; k < 2; ++k) dst[m][k] = *(const PG8_LAS bf16x8*)(lds + PG8_SA(b, h) + aoff + m * 2048 + k * 1024); } while (0)
; #define PG8_LDB(dst, b, h) do { _Pragma("unroll") for (int n = 0; n < 2; ++n) _Pragma("unroll") for (int k = 0; k < 2; ++k) dst[n][k] = *(const PG8_LAS bf16x8*)(lds + PG8_SB(b, h) + boff + n * 2048 + k * 1024); } while (0)
; #define PG8_MMA(ai, bj, At, Bt) do { __builtin_amdgcn_s_setprio(1); _Pragma("unroll") for (int m = 0; m < 4; ++m) _Pragma("unroll") for (int n = 0; n < 2; ++n) _Pragma("unroll") for (int k = 0; k < 2; ++k) \
;         acc[ai][bj][m][n] = __builtin_amdgcn_mfma_f32_16x16x32_bf16(Bt[n][k], At[m][k], acc[ai][bj][m][n], 0, 0, 0); __builtin_amdgcn_s_setprio(0); } while (0)
; #define PG8_WAIT_V(n) asm volatile("s_waitcnt vmcnt(" #n ")" ::: "memory")
; #define PG8_WAIT_L(n) asm volatile("s_waitcnt lgkmcnt(" #n ")" ::: "memory")
; #define PG8_BAR __builtin_amdgcn_s_barrier()
; #define PG8_SCHED __builtin_amdgcn_sched_barrier(0)
; template <class Epi, class Sched, bool ALIGN_EPI = false, bool SP2 = false>
; __device__ __forceinline__ void gemm_phase(PG8_LAS unsigned char* lds, const Gemm g, const Sched& S, const Epi& E) {
;     ...
;             PG8_WAIT_V(8); PG8_WAIT_L(0); PG8_BAR; PG8_MMA(1, 0, At, B0); PG8_MMA(1, 1, At, B1); PG8_BAR; PG8_SCHED;
;             PG8_LDB(B0, 1, 0); PG8_LDB(B1, 1, 1); PG8_SCHED; PG8_LDA(At, 1, 0); PG8_STAGE(PG8_SA(0, 1), a2 + hstep, voffA);
;             PG8_WAIT_V(8); PG8_WAIT_L(0); PG8_BAR; PG8_MMA(0, 0, At, B0); PG8_MMA(0, 1, At, B1); PG8_BAR; PG8_SCHED;
;             PG8_LDA(At, 1, 1); PG8_STAGE(PG8_SB(1, 0), b3, voffB); PG8_STAGE(PG8_SB(1, 1), b3 + hstep, voffB); PG8_STAGE(PG8_SA(1, 0), a3, voffA);
	v_mfma_f32_16x16x32_bf16 v[62:65], v[114:117], v[192:195], v[62:65]
	v_mfma_f32_16x16x32_bf16 v[58:61], v[122:125], v[192:195], v[58:61]
	v_mfma_f32_16x16x32_bf16 v[46:49], v[114:117], v[204:207], v[46:49]
	v_mfma_f32_16x16x32_bf16 v[42:45], v[122:125], v[204:207], v[42:45]
	v_mfma_f32_16x16x32_bf16 v[30:33], v[114:117], v[212:215], v[30:33]
	v_mfma_f32_16x16x32_bf16 v[26:29], v[122:125], v[212:215], v[26:29]
	v_mfma_f32_16x16x32_bf16 v[14:17], v[114:117], v[232:235], v[14:17]
	v_mfma_f32_16x16x32_bf16 v[10:13], v[122:125], v[232:235], v[10:13]
	v_mfma_f32_16x16x32_bf16 v[62:65], v[118:121], v[196:199], v[62:65]
	v_mfma_f32_16x16x32_bf16 v[58:61], v[126:129], v[196:199], v[58:61]
	v_mfma_f32_16x16x32_bf16 v[46:49], v[118:121], v[208:211], v[46:49]
	v_mfma_f32_16x16x32_bf16 v[42:45], v[126:129], v[208:211], v[42:45]
	v_mfma_f32_16x16x32_bf16 v[30:33], v[118:121], v[228:231], v[30:33]
	v_mfma_f32_16x16x32_bf16 v[26:29], v[126:129], v[228:231], v[26:29]
	v_mfma_f32_16x16x32_bf16 v[14:17], v[118:121], v[236:239], v[14:17]
	v_mfma_f32_16x16x32_bf16 v[10:13], v[126:129], v[236:239], v[10:13]
	v_mfma_f32_16x16x32_bf16 v[54:57], v[138:141], v[192:195], v[54:57]
	v_mfma_f32_16x16x32_bf16 v[50:53], v[164:167], v[192:195], v[50:53]
	v_mfma_f32_16x16x32_bf16 v[38:41], v[138:141], v[204:207], v[38:41]
	v_mfma_f32_16x16x32_bf16 v[34:37], v[164:167], v[204:207], v[34:37]
	v_mfma_f32_16x16x32_bf16 v[22:25], v[138:141], v[212:215], v[22:25]
	v_mfma_f32_16x16x32_bf16 v[18:21], v[164:167], v[212:215], v[18:21]
	v_mfma_f32_16x16x32_bf16 v[6:9], v[138:141], v[232:235], v[6:9]
	v_mfma_f32_16x16x32_bf16 v[2:5], v[164:167], v[232:235], v[2:5]
	v_mfma_f32_16x16x32_bf16 v[54:57], v[150:153], v[196:199], v[54:57]
	v_mfma_f32_16x16x32_bf16 v[50:53], v[188:191], v[196:199], v[50:53]
	v_mfma_f32_16x16x32_bf16 v[38:41], v[150:153], v[208:211], v[38:41]
	v_mfma_f32_16x16x32_bf16 v[34:37], v[188:191], v[208:211], v[34:37]
	v_mfma_f32_16x16x32_bf16 v[22:25], v[150:153], v[228:231], v[22:25]
	v_mfma_f32_16x16x32_bf16 v[18:21], v[188:191], v[228:231], v[18:21]
	v_mfma_f32_16x16x32_bf16 v[6:9], v[150:153], v[236:239], v[6:9]
	v_mfma_f32_16x16x32_bf16 v[2:5], v[188:191], v[236:239], v[2:5]
	s_barrier
	s_setprio 0
	s_mov_b32 m0, s27
	v_lshl_add_u64 v[246:247], s[8:9], 0, v[156:157]
	global_load_lds_dwordx4 v[244:245], off
	s_mov_b32 m0, s28
	s_nop 0
	global_load_lds_dwordx4 v[246:247], off
	s_add_i32 s36, 0, 0x18000
	s_add_i32 s37, 0, 0x1c000
	v_add_u32_e32 v126, s36, v200
	v_add_u32_e32 v188, s37, v200
	ds_read_b128 v[114:117], v126
	ds_read_b128 v[118:121], v126 offset:1024
	ds_read_b128 v[122:125], v126 offset:2048
	ds_read_b128 v[126:129], v126 offset:3072
	ds_read_b128 v[138:141], v188
	ds_read_b128 v[150:153], v188 offset:1024
	ds_read_b128 v[164:167], v188 offset:2048
	ds_read_b128 v[188:191], v188 offset:3072
	s_add_u32 s8, s8, s18
	s_addc_u32 s9, s9, 0
	s_mov_b32 m0, s29
	v_lshl_add_u64 v[248:249], s[8:9], 0, v[158:159]
	ds_read_b128 v[192:195], v202 offset:32768
	ds_read_b128 v[196:199], v202 offset:33792
	ds_read_b128 v[204:207], v202 offset:34816
	ds_read_b128 v[208:211], v202 offset:35840
	ds_read_b128 v[212:215], v202 offset:36864
	ds_read_b128 v[228:231], v202 offset:37888
	ds_read_b128 v[232:235], v202 offset:38912
	ds_read_b128 v[236:239], v202 offset:39936
	global_load_lds_dwordx4 v[248:249], off
	v_lshl_add_u64 v[248:249], s[8:9], 0, v[156:157]
	s_mov_b32 m0, s30
	s_nop 0
	global_load_lds_dwordx4 v[248:249], off
	s_waitcnt vmcnt(8)
	s_waitcnt lgkmcnt(0)
	s_setprio 1
	s_barrier
	v_mfma_f32_16x16x32_bf16 v[146:149], v[114:117], v[192:195], v[146:149]
	v_mfma_f32_16x16x32_bf16 v[142:145], v[122:125], v[192:195], v[142:145]
	v_mfma_f32_16x16x32_bf16 v[110:113], v[114:117], v[204:207], v[110:113]
	v_mfma_f32_16x16x32_bf16 v[106:109], v[122:125], v[204:207], v[106:109]
	v_mfma_f32_16x16x32_bf16 v[94:97], v[114:117], v[212:215], v[94:97]
	v_mfma_f32_16x16x32_bf16 v[90:93], v[122:125], v[212:215], v[90:93]
	v_mfma_f32_16x16x32_bf16 v[78:81], v[114:117], v[232:235], v[78:81]
	v_mfma_f32_16x16x32_bf16 v[74:77], v[122:125], v[232:235], v[74:77]
	v_mfma_f32_16x16x32_bf16 v[146:149], v[118:121], v[196:199], v[146:149]
	v_mfma_f32_16x16x32_bf16 v[142:145], v[126:129], v[196:199], v[142:145]
	v_mfma_f32_16x16x32_bf16 v[110:113], v[118:121], v[208:211], v[110:113]
	v_mfma_f32_16x16x32_bf16 v[106:109], v[126:129], v[208:211], v[106:109]
	v_mfma_f32_16x16x32_bf16 v[94:97], v[118:121], v[228:231], v[94:97]
	v_mfma_f32_16x16x32_bf16 v[90:93], v[126:129], v[228:231], v[90:93]
	v_mfma_f32_16x16x32_bf16 v[78:81], v[118:121], v[236:239], v[78:81]
	v_mfma_f32_16x16x32_bf16 v[74:77], v[126:129], v[236:239], v[74:77]
	v_mfma_f32_16x16x32_bf16 v[134:137], v[138:141], v[192:195], v[134:137]
	v_mfma_f32_16x16x32_bf16 v[130:133], v[164:167], v[192:195], v[130:133]
	v_mfma_f32_16x16x32_bf16 v[102:105], v[138:141], v[204:207], v[102:105]
	v_mfma_f32_16x16x32_bf16 v[98:101], v[164:167], v[204:207], v[98:101]
	v_mfma_f32_16x16x32_bf16 v[86:89], v[138:141], v[212:215], v[86:89]
	v_mfma_f32_16x16x32_bf16 v[82:85], v[164:167], v[212:215], v[82:85]
	v_mfma_f32_16x16x32_bf16 v[70:73], v[138:141], v[232:235], v[70:73]
	v_mfma_f32_16x16x32_bf16 v[66:69], v[164:167], v[232:235], v[66:69]
	v_mfma_f32_16x16x32_bf16 v[134:137], v[150:153], v[196:199], v[134:137]
	v_mfma_f32_16x16x32_bf16 v[130:133], v[188:191], v[196:199], v[130:133]
	v_mfma_f32_16x16x32_bf16 v[102:105], v[150:153], v[208:211], v[102:105]
	v_mfma_f32_16x16x32_bf16 v[98:101], v[188:191], v[208:211], v[98:101]
	v_mfma_f32_16x16x32_bf16 v[86:89], v[150:153], v[228:231], v[86:89]
	v_mfma_f32_16x16x32_bf16 v[82:85], v[188:191], v[228:231], v[82:85]
	v_mfma_f32_16x16x32_bf16 v[70:73], v[150:153], v[236:239], v[70:73]
	v_mfma_f32_16x16x32_bf16 v[66:69], v[188:191], v[236:239], v[66:69]
	s_barrier
; #define PG8_STAGE(bufoff, gbase, voff) do { _Pragma("unroll") for (int _i = 0; _i < 2; ++_i) \
;         __builtin_amdgcn_global_load_lds((const unsigned*)((const char*)(gbase) + (voff)[_i]), (PG8_LAS unsigned*)(lds + (bufoff) + ldsw + _i * 8192), 16, 0, 0); } while (0)
; #define PG8_LDA(dst, b, h) do { _Pragma("unroll") for (int m = 0; m < 4; ++m) _Pragma("unroll") for (int k = 0; k < 2; ++k) dst[m][k] = *(const PG8_LAS bf16x8*)(lds + PG8_SA(b, h) + aoff + m * 2048 + k * 1024); } while (0)
; #define PG8_MMA(ai, bj, At, Bt) do { __builtin_amdgcn_s_setprio(1); _Pragma("unroll") for (int m = 0; m < 4; ++m) _Pragma("unroll") for (int n = 0; n < 2; ++n) _Pragma("unroll") for (int k = 0; k < 2; ++k) \
;         acc[ai][bj][m][n] = __builtin_amdgcn_mfma_f32_16x16x32_bf16(Bt[n][k], At[m][k], acc[ai][bj][m][n], 0, 0, 0); __builtin_amdgcn_s_setprio(0); } while (0)
; #define PG8_WAIT_V(n) asm volatile("s_waitcnt vmcnt(" #n ")" ::: "memory")
; #define PG8_WAIT_L(n) asm volatile("s_waitcnt lgkmcnt(" #n ")" ::: "memory")
; #define PG8_BAR __builtin_amdgcn_s_barrier()
; #define PG8_SCHED __builtin_amdgcn_sched_barrier(0)
; template <class Epi, class Sched, bool ALIGN_EPI = false, bool SP2 = false>
; __device__ __forceinline__ void gemm_phase(PG8_LAS unsigned char* lds, const Gemm g, const Sched& S, const Epi& E) {
;     ...
;             PG8_WAIT_V(8); PG8_WAIT_L(0); PG8_BAR; PG8_MMA(0, 0, At, B0); PG8_MMA(0, 1, At, B1); PG8_BAR; PG8_SCHED;
;             PG8_LDA(At, 1, 1); PG8_STAGE(PG8_SB(1, 0), b3, voffB); PG8_STAGE(PG8_SB(1, 1), b3 + hstep, voffB); PG8_STAGE(PG8_SA(1, 0), a3, voffA);
;             PG8_WAIT_V(8); PG8_WAIT_L(0); PG8_BAR; PG8_MMA(1, 0, At, B0); PG8_MMA(1, 1, At, B1); PG8_BAR; PG8_SCHED;
	s_setprio 0
	s_add_i32 s8, s36, s25
	v_lshl_add_u64 v[168:169], v[168:169], 0, s[88:89]
	s_mov_b32 m0, s8
	ds_read_b128 v[192:195], v202 offset:49152
	ds_read_b128 v[196:199], v202 offset:50176
	ds_read_b128 v[204:207], v202 offset:51200
	ds_read_b128 v[208:211], v202 offset:52224
	ds_read_b128 v[212:215], v202 offset:53248
	ds_read_b128 v[228:231], v202 offset:54272
	ds_read_b128 v[232:235], v202 offset:55296
	ds_read_b128 v[236:239], v202 offset:56320
	global_load_lds_dwordx4 v[168:169], off
	v_lshl_add_u64 v[168:169], v[216:217], 0, s[88:89]
	s_add_i32 m0, s8, 0x2000
	s_add_i32 s8, s37, s25
	global_load_lds_dwordx4 v[168:169], off
	v_lshl_add_u64 v[168:169], v[240:241], 0, s[88:89]
	s_mov_b32 m0, s8
	s_nop 0
	global_load_lds_dwordx4 v[168:169], off
	v_lshl_add_u64 v[168:169], v[242:243], 0, s[88:89]
	s_add_i32 m0, s8, 0x2000
	s_nop 0
	global_load_lds_dwordx4 v[168:169], off
	v_lshl_add_u64 v[168:169], v[244:245], 0, s[88:89]
	s_mov_b32 m0, s31
	s_nop 0
	global_load_lds_dwordx4 v[168:169], off
	v_lshl_add_u64 v[168:169], v[246:247], 0, s[88:89]
	s_mov_b32 m0, s34
	s_nop 0
	global_load_lds_dwordx4 v[168:169], off
	s_waitcnt vmcnt(8)
	s_waitcnt lgkmcnt(0)
	s_setprio 1
	s_barrier
	v_mfma_f32_16x16x32_bf16 v[62:65], v[114:117], v[192:195], v[62:65]
	v_mfma_f32_16x16x32_bf16 v[58:61], v[122:125], v[192:195], v[58:61]
	v_mfma_f32_16x16x32_bf16 v[46:49], v[114:117], v[204:207], v[46:49]
	v_mfma_f32_16x16x32_bf16 v[42:45], v[122:125], v[204:207], v[42:45]
	v_mfma_f32_16x16x32_bf16 v[30:33], v[114:117], v[212:215], v[30:33]
	v_mfma_f32_16x16x32_bf16 v[26:29], v[122:125], v[212:215], v[26:29]
	v_mfma_f32_16x16x32_bf16 v[14:17], v[114:117], v[232:235], v[14:17]
	v_mfma_f32_16x16x32_bf16 v[10:13], v[122:125], v[232:235], v[10:13]
	v_mfma_f32_16x16x32_bf16 v[62:65], v[118:121], v[196:199], v[62:65]
	v_mfma_f32_16x16x32_bf16 v[58:61], v[126:129], v[196:199], v[58:61]
	v_mfma_f32_16x16x32_bf16 v[46:49], v[118:121], v[208:211], v[46:49]
	v_mfma_f32_16x16x32_bf16 v[42:45], v[126:129], v[208:211], v[42:45]
	v_mfma_f32_16x16x32_bf16 v[30:33], v[118:121], v[228:231], v[30:33]
	v_mfma_f32_16x16x32_bf16 v[26:29], v[126:129], v[228:231], v[26:29]
	v_mfma_f32_16x16x32_bf16 v[14:17], v[118:121], v[236:239], v[14:17]
	v_mfma_f32_16x16x32_bf16 v[10:13], v[126:129], v[236:239], v[10:13]
	v_mfma_f32_16x16x32_bf16 v[54:57], v[138:141], v[192:195], v[54:57]
	v_mfma_f32_16x16x32_bf16 v[50:53], v[164:167], v[192:195], v[50:53]
	v_mfma_f32_16x16x32_bf16 v[38:41], v[138:141], v[204:207], v[38:41]
	v_mfma_f32_16x16x32_bf16 v[34:37], v[164:167], v[204:207], v[34:37]
	v_mfma_f32_16x16x32_bf16 v[22:25], v[138:141], v[212:215], v[22:25]
	v_mfma_f32_16x16x32_bf16 v[18:21], v[164:167], v[212:215], v[18:21]
	v_mfma_f32_16x16x32_bf16 v[6:9], v[138:141], v[232:235], v[6:9]
	v_mfma_f32_16x16x32_bf16 v[2:5], v[164:167], v[232:235], v[2:5]
	v_mfma_f32_16x16x32_bf16 v[54:57], v[150:153], v[196:199], v[54:57]
	v_mfma_f32_16x16x32_bf16 v[50:53], v[188:191], v[196:199], v[50:53]
	v_mfma_f32_16x16x32_bf16 v[38:41], v[150:153], v[208:211], v[38:41]
	v_mfma_f32_16x16x32_bf16 v[34:37], v[188:191], v[208:211], v[34:37]
	v_mfma_f32_16x16x32_bf16 v[22:25], v[150:153], v[228:231], v[22:25]
	v_mfma_f32_16x16x32_bf16 v[18:21], v[188:191], v[228:231], v[18:21]
	v_mfma_f32_16x16x32_bf16 v[6:9], v[150:153], v[236:239], v[6:9]
	v_mfma_f32_16x16x32_bf16 v[2:5], v[188:191], v[236:239], v[2:5]
	s_barrier
	s_setprio 0
	s_add_u32 s6, s6, 0x100
	s_addc_u32 s7, s7, 0
	s_add_u32 s74, s74, 0x100
	s_addc_u32 s75, s75, 0
	s_cmp_ge_u32 s78, s35
	s_mov_b32 s8, s78
	s_cbranch_scc0 .LBB0_1704
	s_and_b64 vcc, exec, s[52:53]
	s_cbranch_vccz .LBB0_1707
	s_barrier

; #define PG8_STAGE(bufoff, gbase, voff) do { _Pragma("unroll") for (int _i = 0; _i < 2; ++_i) \
;         __builtin_amdgcn_global_load_lds((const unsigned*)((const char*)(gbase) + (voff)[_i]), (PG8_LAS unsigned*)(lds + (bufoff) + ldsw + _i * 8192), 16, 0, 0); } while (0)
; #define PG8_LDA(dst, b, h) do { _Pragma("unroll") for (int m = 0; m < 4; ++m) _Pragma("unroll") for (int k = 0; k < 2; ++k) dst[m][k] = *(const PG8_LAS bf16x8*)(lds + PG8_SA(b, h) + aoff + m * 2048 + k * 1024); } while (0)
; #define PG8_LDB(dst, b, h) do { _Pragma("unroll") for (int n = 0; n < 2; ++n) _Pragma("unroll") for (int k = 0; k < 2; ++k) dst[n][k] = *(const PG8_LAS bf16x8*)(lds + PG8_SB(b, h) + boff + n * 2048 + k * 1024); } while (0)
; #define PG8_MMA(ai, bj, At, Bt) do { __builtin_amdgcn_s_setprio(1); _Pragma("unroll") for (int m = 0; m < 4; ++m) _Pragma("unroll") for (int n = 0; n < 2; ++n) _Pragma("unroll") for (int k = 0; k < 2; ++k) \
;         acc[ai][bj][m][n] = __builtin_amdgcn_mfma_f32_16x16x32_bf16(Bt[n][k], At[m][k], acc[ai][bj][m][n], 0, 0, 0); __builtin_amdgcn_s_setprio(0); } while (0)
; #define PG8_WAIT_V(n) asm volatile("s_waitcnt vmcnt(" #n ")" ::: "memory")
; #define PG8_BAR __builtin_amdgcn_s_barrier()
; template <class Epi, class Sched, bool ALIGN_EPI = false, bool SP2 = false>
; __device__ __forceinline__ void gemm_phase(PG8_LAS unsigned char* lds, const Gemm g, const Sched& S, const Epi& E) {
;     ...
;         for (int t = 0; t < nt; t += 2) {
;             const bool last = (t == nt - 2);
;             const char* a1 = cA + (size_t)(t + 1) * kstep;
;             const char* a2 = last ? nA : cA + (size_t)(t + 2) * kstep; const char* b2 = last ? nB : cB + (size_t)(t + 2) * kstep;
;             const char* a3 = a2 + kstep; const char* b3 = b2 + kstep;
;             if (last && has_next) S.a_ready(nxt);
;             if constexpr (SP2) {
;             PG8_LDB(B0, 0, 0); PG8_LDB(B1, 0, 1); PG8_SCHED; PG8_LDA(At, 0, 0); PG8_STAGE(PG8_SA(1, 1), a1 + hstep, voffA);
;             PG8_WAIT_V(8); PG8_WAIT_L(0); PG8_BAR; PG8_MMA(0, 0, At, B0); PG8_MMA(0, 1, At, B1); PG8_BAR; PG8_SCHED;
;             PG8_LDA(At, 0, 1); PG8_STAGE(PG8_SB(0, 0), b2, voffB); PG8_STAGE(PG8_SB(0, 1), b2 + hstep, voffB); PG8_STAGE(PG8_SA(0, 0), a2, voffA);
;             PG8_WAIT_V(8); PG8_WAIT_L(0); PG8_BAR; PG8_MMA(1, 0, At, B0); PG8_MMA(1, 1, At, B1); PG8_BAR; PG8_SCHED;
.LBB0_1773:
	s_add_u32 s8, s6, 0xfff80080
	s_addc_u32 s9, s7, -1
	s_add_i32 s36, 0, 0x10000
	s_cmp_eq_u32 s74, 28
	s_cselect_b32 s11, s59, s9
	s_cselect_b32 s10, s68, s8
	v_add_u32_e32 v147, s36, v142
	s_cselect_b32 s9, s57, s71
	s_cselect_b32 s8, s69, s70
	s_add_i32 s37, 0, 0x14000
	ds_read_b128 v[148:151], v147
	ds_read_b128 v[152:155], v147 offset:1024
	ds_read_b128 v[156:159], v147 offset:2048
	ds_read_b128 v[160:163], v147 offset:3072
	v_add_u32_e32 v147, s37, v142
	ds_read_b128 v[164:167], v147
	ds_read_b128 v[188:191], v147 offset:1024
	ds_read_b128 v[192:195], v147 offset:2048
	ds_read_b128 v[196:199], v147 offset:3072
	v_lshl_add_u64 v[168:169], s[6:7], 0, v[136:137]
	s_add_i32 m0, s26, 0xc000
	ds_read_b128 v[200:203], v146
	ds_read_b128 v[204:207], v146 offset:1024
	ds_read_b128 v[208:211], v146 offset:2048
	ds_read_b128 v[212:215], v146 offset:3072
	ds_read_b128 v[228:231], v146 offset:4096
	ds_read_b128 v[232:235], v146 offset:5120
	ds_read_b128 v[236:239], v146 offset:6144
	ds_read_b128 v[240:243], v146 offset:7168
	global_load_lds_dwordx4 v[168:169], off
	v_lshl_add_u64 v[168:169], s[6:7], 0, v[138:139]
	s_add_i32 m0, s26, 0xe000
	s_nop 0
	global_load_lds_dwordx4 v[168:169], off
	s_waitcnt vmcnt(8)
	s_waitcnt lgkmcnt(0)
	s_setprio 1
	s_barrier
	v_mfma_f32_16x16x32_bf16 v[126:129], v[148:151], v[200:203], v[126:129]
	v_mfma_f32_16x16x32_bf16 v[118:121], v[156:159], v[200:203], v[118:121]
	v_mfma_f32_16x16x32_bf16 v[110:113], v[148:151], v[208:211], v[110:113]
	v_mfma_f32_16x16x32_bf16 v[102:105], v[156:159], v[208:211], v[102:105]
	v_mfma_f32_16x16x32_bf16 v[94:97], v[148:151], v[228:231], v[94:97]
	v_mfma_f32_16x16x32_bf16 v[86:89], v[156:159], v[228:231], v[86:89]
	v_mfma_f32_16x16x32_bf16 v[78:81], v[148:151], v[236:239], v[78:81]
	v_mfma_f32_16x16x32_bf16 v[70:73], v[156:159], v[236:239], v[70:73]
	v_mfma_f32_16x16x32_bf16 v[126:129], v[152:155], v[204:207], v[126:129]
	v_mfma_f32_16x16x32_bf16 v[118:121], v[160:163], v[204:207], v[118:121]
	v_mfma_f32_16x16x32_bf16 v[110:113], v[152:155], v[212:215], v[110:113]
	v_mfma_f32_16x16x32_bf16 v[102:105], v[160:163], v[212:215], v[102:105]
	v_mfma_f32_16x16x32_bf16 v[94:97], v[152:155], v[232:235], v[94:97]
	v_mfma_f32_16x16x32_bf16 v[86:89], v[160:163], v[232:235], v[86:89]
	v_mfma_f32_16x16x32_bf16 v[78:81], v[152:155], v[240:243], v[78:81]
	v_mfma_f32_16x16x32_bf16 v[70:73], v[160:163], v[240:243], v[70:73]
	v_mfma_f32_16x16x32_bf16 v[122:125], v[164:167], v[200:203], v[122:125]
	v_mfma_f32_16x16x32_bf16 v[114:117], v[192:195], v[200:203], v[114:117]
	v_mfma_f32_16x16x32_bf16 v[106:109], v[164:167], v[208:211], v[106:109]
	v_mfma_f32_16x16x32_bf16 v[98:101], v[192:195], v[208:211], v[98:101]
	v_mfma_f32_16x16x32_bf16 v[90:93], v[164:167], v[228:231], v[90:93]
	v_mfma_f32_16x16x32_bf16 v[82:85], v[192:195], v[228:231], v[82:85]
	v_mfma_f32_16x16x32_bf16 v[74:77], v[164:167], v[236:239], v[74:77]
	v_mfma_f32_16x16x32_bf16 v[66:69], v[192:195], v[236:239], v[66:69]
	v_mfma_f32_16x16x32_bf16 v[122:125], v[188:191], v[204:207], v[122:125]
	v_mfma_f32_16x16x32_bf16 v[114:117], v[196:199], v[204:207], v[114:117]
	v_mfma_f32_16x16x32_bf16 v[106:109], v[188:191], v[212:215], v[106:109]
	v_mfma_f32_16x16x32_bf16 v[98:101], v[196:199], v[212:215], v[98:101]
	v_mfma_f32_16x16x32_bf16 v[90:93], v[188:191], v[232:235], v[90:93]
	v_mfma_f32_16x16x32_bf16 v[82:85], v[196:199], v[232:235], v[82:85]
	v_mfma_f32_16x16x32_bf16 v[74:77], v[188:191], v[240:243], v[74:77]
	v_mfma_f32_16x16x32_bf16 v[66:69], v[196:199], v[240:243], v[66:69]
	s_barrier
	s_setprio 0
	s_add_i32 s36, s36, s25
	v_lshl_add_u64 v[168:169], s[8:9], 0, v[0:1]
	s_mov_b32 m0, s36
	ds_read_b128 v[200:203], v146 offset:16384
	ds_read_b128 v[204:207], v146 offset:17408
	ds_read_b128 v[208:211], v146 offset:18432
	ds_read_b128 v[212:215], v146 offset:19456
	ds_read_b128 v[228:231], v146 offset:20480
	ds_read_b128 v[232:235], v146 offset:21504
	ds_read_b128 v[236:239], v146 offset:22528
	ds_read_b128 v[240:243], v146 offset:23552
	global_load_lds_dwordx4 v[168:169], off
	s_add_i32 m0, s36, 0x2000
	s_add_u32 s78, s8, 0x80000
	v_lshl_add_u64 v[216:217], s[8:9], 0, v[134:135]
	s_addc_u32 s79, s9, 0
	s_add_i32 s36, s37, s25
	global_load_lds_dwordx4 v[216:217], off
	v_lshl_add_u64 v[244:245], s[78:79], 0, v[0:1]
	s_mov_b32 m0, s36
	v_lshl_add_u64 v[246:247], s[10:11], 0, v[132:133]
	global_load_lds_dwordx4 v[244:245], off
	v_lshl_add_u64 v[244:245], s[78:79], 0, v[134:135]
	s_add_i32 m0, s36, 0x2000
	s_nop 0
	global_load_lds_dwordx4 v[244:245], off
	s_waitcnt vmcnt(6)
	s_waitcnt lgkmcnt(0)
	s_setprio 1
	s_barrier
; #define PG8_STAGE(bufoff, gbase, voff) do { _Pragma("unroll") for (int _i = 0; _i < 2; ++_i) \
;         __builtin_amdgcn_global_load_lds((const unsigned*)((const char*)(gbase) + (voff)[_i]), (PG8_LAS unsigned*)(lds + (bufoff) + ldsw + _i * 8192), 16, 0, 0); } while (0)
; #define PG8_LDA(dst, b, h) do { _Pragma("unroll") for (int m = 0; m < 4; ++m) _Pragma("unroll") for (int k = 0; k < 2; ++k) dst[m][k] = *(const PG8_LAS bf16x8*)(lds + PG8_SA(b, h) + aoff + m * 2048 + k * 1024); } while (0)
; #define PG8_LDB(dst, b, h) do { _Pragma("unroll") for (int n = 0; n < 2; ++n) _Pragma("unroll") for (int k = 0; k < 2; ++k) dst[n][k] = *(const PG8_LAS bf16x8*)(lds + PG8_SB(b, h) + boff + n * 2048 + k * 1024); } while (0)
; #define PG8_MMA(ai, bj, At, Bt) do { __builtin_amdgcn_s_setprio(1); _Pragma("unroll") for (int m = 0; m < 4; ++m) _Pragma("unroll") for (int n = 0; n < 2; ++n) _Pragma("unroll") for (int k = 0; k < 2; ++k) \
;         acc[ai][bj][m][n] = __builtin_amdgcn_mfma_f32_16x16x32_bf16(Bt[n][k], At[m][k], acc[ai][bj][m][n], 0, 0, 0); __builtin_amdgcn_s_setprio(0); } while (0)
; #define PG8_WAIT_V(n) asm volatile("s_waitcnt vmcnt(" #n ")" ::: "memory")
; #define PG8_WAIT_L(n) asm volatile("s_waitcnt lgkmcnt(" #n ")" ::: "memory")
; #define PG8_BAR __builtin_amdgcn_s_barrier()
; #define PG8_SCHED __builtin_amdgcn_sched_barrier(0)
; template <class Epi, class Sched, bool ALIGN_EPI = false, bool SP2 = false>
; __device__ __forceinline__ void gemm_phase(PG8_LAS unsigned char* lds, const Gemm g, const Sched& S, const Epi& E) {
;     ...
;             PG8_WAIT_V(8); PG8_WAIT_L(0); PG8_BAR; PG8_MMA(1, 0, At, B0); PG8_MMA(1, 1, At, B1); PG8_BAR; PG8_SCHED;
;             PG8_LDB(B0, 1, 0); PG8_LDB(B1, 1, 1); PG8_SCHED; PG8_LDA(At, 1, 0); PG8_STAGE(PG8_SA(0, 1), a2 + hstep, voffA);
;             PG8_WAIT_V(8); PG8_WAIT_L(0); PG8_BAR; PG8_MMA(0, 0, At, B0); PG8_MMA(0, 1, At, B1); PG8_BAR; PG8_SCHED;
;             PG8_LDA(At, 1, 1); PG8_STAGE(PG8_SB(1, 0), b3, voffB); PG8_STAGE(PG8_SB(1, 1), b3 + hstep, voffB); PG8_STAGE(PG8_SA(1, 0), a3, voffA);
	v_mfma_f32_16x16x32_bf16 v[62:65], v[148:151], v[200:203], v[62:65]
	v_mfma_f32_16x16x32_bf16 v[54:57], v[156:159], v[200:203], v[54:57]
	v_mfma_f32_16x16x32_bf16 v[46:49], v[148:151], v[208:211], v[46:49]
	v_mfma_f32_16x16x32_bf16 v[38:41], v[156:159], v[208:211], v[38:41]
	v_mfma_f32_16x16x32_bf16 v[30:33], v[148:151], v[228:231], v[30:33]
	v_mfma_f32_16x16x32_bf16 v[22:25], v[156:159], v[228:231], v[22:25]
	v_mfma_f32_16x16x32_bf16 v[14:17], v[148:151], v[236:239], v[14:17]
	v_mfma_f32_16x16x32_bf16 v[6:9], v[156:159], v[236:239], v[6:9]
	v_mfma_f32_16x16x32_bf16 v[62:65], v[152:155], v[204:207], v[62:65]
	v_mfma_f32_16x16x32_bf16 v[54:57], v[160:163], v[204:207], v[54:57]
	v_mfma_f32_16x16x32_bf16 v[46:49], v[152:155], v[212:215], v[46:49]
	v_mfma_f32_16x16x32_bf16 v[38:41], v[160:163], v[212:215], v[38:41]
	v_mfma_f32_16x16x32_bf16 v[30:33], v[152:155], v[232:235], v[30:33]
	v_mfma_f32_16x16x32_bf16 v[22:25], v[160:163], v[232:235], v[22:25]
	v_mfma_f32_16x16x32_bf16 v[14:17], v[152:155], v[240:243], v[14:17]
	v_mfma_f32_16x16x32_bf16 v[6:9], v[160:163], v[240:243], v[6:9]
	v_mfma_f32_16x16x32_bf16 v[58:61], v[164:167], v[200:203], v[58:61]
	v_mfma_f32_16x16x32_bf16 v[50:53], v[192:195], v[200:203], v[50:53]
	v_mfma_f32_16x16x32_bf16 v[42:45], v[164:167], v[208:211], v[42:45]
	v_mfma_f32_16x16x32_bf16 v[34:37], v[192:195], v[208:211], v[34:37]
	v_mfma_f32_16x16x32_bf16 v[26:29], v[164:167], v[228:231], v[26:29]
	v_mfma_f32_16x16x32_bf16 v[18:21], v[192:195], v[228:231], v[18:21]
	v_mfma_f32_16x16x32_bf16 v[10:13], v[164:167], v[236:239], v[10:13]
	v_mfma_f32_16x16x32_bf16 v[2:5], v[192:195], v[236:239], v[2:5]
	v_mfma_f32_16x16x32_bf16 v[58:61], v[188:191], v[204:207], v[58:61]
	v_mfma_f32_16x16x32_bf16 v[50:53], v[196:199], v[204:207], v[50:53]
	v_mfma_f32_16x16x32_bf16 v[42:45], v[188:191], v[212:215], v[42:45]
	v_mfma_f32_16x16x32_bf16 v[34:37], v[196:199], v[212:215], v[34:37]
	v_mfma_f32_16x16x32_bf16 v[26:29], v[188:191], v[232:235], v[26:29]
	v_mfma_f32_16x16x32_bf16 v[18:21], v[196:199], v[232:235], v[18:21]
	v_mfma_f32_16x16x32_bf16 v[10:13], v[188:191], v[240:243], v[10:13]
	v_mfma_f32_16x16x32_bf16 v[2:5], v[196:199], v[240:243], v[2:5]
	s_barrier
	s_setprio 0
	v_lshl_add_u64 v[244:245], s[10:11], 0, v[130:131]
	s_mov_b32 m0, s26
	s_nop 0
	global_load_lds_dwordx4 v[244:245], off
	s_mov_b32 m0, s27
	s_nop 0
	global_load_lds_dwordx4 v[246:247], off
	s_add_i32 s36, 0, 0x18000
	v_add_u32_e32 v147, s36, v142
	s_add_i32 s37, 0, 0x1c000
	ds_read_b128 v[148:151], v147
	ds_read_b128 v[152:155], v147 offset:1024
	ds_read_b128 v[156:159], v147 offset:2048
	ds_read_b128 v[160:163], v147 offset:3072
	v_add_u32_e32 v147, s37, v142
	ds_read_b128 v[164:167], v147
	ds_read_b128 v[188:191], v147 offset:1024
	ds_read_b128 v[192:195], v147 offset:2048
	ds_read_b128 v[196:199], v147 offset:3072
	s_add_u32 s10, s10, 0x80000
	s_addc_u32 s11, s11, 0
	s_mov_b32 m0, s28
	v_lshl_add_u64 v[248:249], s[10:11], 0, v[130:131]
	ds_read_b128 v[200:203], v146 offset:32768
	ds_read_b128 v[204:207], v146 offset:33792
	ds_read_b128 v[208:211], v146 offset:34816
	ds_read_b128 v[212:215], v146 offset:35840
	ds_read_b128 v[228:231], v146 offset:36864
	ds_read_b128 v[232:235], v146 offset:37888
	ds_read_b128 v[236:239], v146 offset:38912
	ds_read_b128 v[240:243], v146 offset:39936
	global_load_lds_dwordx4 v[248:249], off
	v_lshl_add_u64 v[248:249], s[10:11], 0, v[132:133]
	s_mov_b32 m0, s29
	s_nop 0
	global_load_lds_dwordx4 v[248:249], off
	s_waitcnt vmcnt(8)
	s_waitcnt lgkmcnt(0)
	s_setprio 1
	s_barrier
	v_mfma_f32_16x16x32_bf16 v[126:129], v[148:151], v[200:203], v[126:129]
	v_mfma_f32_16x16x32_bf16 v[118:121], v[156:159], v[200:203], v[118:121]
	v_mfma_f32_16x16x32_bf16 v[110:113], v[148:151], v[208:211], v[110:113]
	v_mfma_f32_16x16x32_bf16 v[102:105], v[156:159], v[208:211], v[102:105]
	v_mfma_f32_16x16x32_bf16 v[94:97], v[148:151], v[228:231], v[94:97]
	v_mfma_f32_16x16x32_bf16 v[86:89], v[156:159], v[228:231], v[86:89]
	v_mfma_f32_16x16x32_bf16 v[78:81], v[148:151], v[236:239], v[78:81]
	v_mfma_f32_16x16x32_bf16 v[70:73], v[156:159], v[236:239], v[70:73]
	v_mfma_f32_16x16x32_bf16 v[126:129], v[152:155], v[204:207], v[126:129]
	v_mfma_f32_16x16x32_bf16 v[118:121], v[160:163], v[204:207], v[118:121]
	v_mfma_f32_16x16x32_bf16 v[110:113], v[152:155], v[212:215], v[110:113]
	v_mfma_f32_16x16x32_bf16 v[102:105], v[160:163], v[212:215], v[102:105]
	v_mfma_f32_16x16x32_bf16 v[94:97], v[152:155], v[232:235], v[94:97]
	v_mfma_f32_16x16x32_bf16 v[86:89], v[160:163], v[232:235], v[86:89]
	v_mfma_f32_16x16x32_bf16 v[78:81], v[152:155], v[240:243], v[78:81]
	v_mfma_f32_16x16x32_bf16 v[70:73], v[160:163], v[240:243], v[70:73]
	v_mfma_f32_16x16x32_bf16 v[122:125], v[164:167], v[200:203], v[122:125]
	v_mfma_f32_16x16x32_bf16 v[114:117], v[192:195], v[200:203], v[114:117]
	v_mfma_f32_16x16x32_bf16 v[106:109], v[164:167], v[208:211], v[106:109]
	v_mfma_f32_16x16x32_bf16 v[98:101], v[192:195], v[208:211], v[98:101]
	v_mfma_f32_16x16x32_bf16 v[90:93], v[164:167], v[228:231], v[90:93]
	v_mfma_f32_16x16x32_bf16 v[82:85], v[192:195], v[228:231], v[82:85]
	v_mfma_f32_16x16x32_bf16 v[74:77], v[164:167], v[236:239], v[74:77]
	v_mfma_f32_16x16x32_bf16 v[66:69], v[192:195], v[236:239], v[66:69]
	v_mfma_f32_16x16x32_bf16 v[122:125], v[188:191], v[204:207], v[122:125]
	v_mfma_f32_16x16x32_bf16 v[114:117], v[196:199], v[204:207], v[114:117]
	v_mfma_f32_16x16x32_bf16 v[106:109], v[188:191], v[212:215], v[106:109]
	v_mfma_f32_16x16x32_bf16 v[98:101], v[196:199], v[212:215], v[98:101]
	v_mfma_f32_16x16x32_bf16 v[90:93], v[188:191], v[232:235], v[90:93]
	v_mfma_f32_16x16x32_bf16 v[82:85], v[196:199], v[232:235], v[82:85]
	v_mfma_f32_16x16x32_bf16 v[74:77], v[188:191], v[240:243], v[74:77]
	v_mfma_f32_16x16x32_bf16 v[66:69], v[196:199], v[240:243], v[66:69]
	s_barrier
; #define PG8_STAGE(bufoff, gbase, voff) do { _Pragma("unroll") for (int _i = 0; _i < 2; ++_i) \
;         __builtin_amdgcn_global_load_lds((const unsigned*)((const char*)(gbase) + (voff)[_i]), (PG8_LAS unsigned*)(lds + (bufoff) + ldsw + _i * 8192), 16, 0, 0); } while (0)
; #define PG8_LDA(dst, b, h) do { _Pragma("unroll") for (int m = 0; m < 4; ++m) _Pragma("unroll") for (int k = 0; k < 2; ++k) dst[m][k] = *(const PG8_LAS bf16x8*)(lds + PG8_SA(b, h) + aoff + m * 2048 + k * 1024); } while (0)
; #define PG8_MMA(ai, bj, At, Bt) do { __builtin_amdgcn_s_setprio(1); _Pragma("unroll") for (int m = 0; m < 4; ++m) _Pragma("unroll") for (int n = 0; n < 2; ++n) _Pragma("unroll") for (int k = 0; k < 2; ++k) \
;         acc[ai][bj][m][n] = __builtin_amdgcn_mfma_f32_16x16x32_bf16(Bt[n][k], At[m][k], acc[ai][bj][m][n], 0, 0, 0); __builtin_amdgcn_s_setprio(0); } while (0)
; #define PG8_WAIT_V(n) asm volatile("s_waitcnt vmcnt(" #n ")" ::: "memory")
; #define PG8_WAIT_L(n) asm volatile("s_waitcnt lgkmcnt(" #n ")" ::: "memory")
; #define PG8_BAR __builtin_amdgcn_s_barrier()
; #define PG8_SCHED __builtin_amdgcn_sched_barrier(0)
; template <class Epi, class Sched, bool ALIGN_EPI = false, bool SP2 = false>
; __device__ __forceinline__ void gemm_phase(PG8_LAS unsigned char* lds, const Gemm g, const Sched& S, const Epi& E) {
;     ...
;             PG8_WAIT_V(8); PG8_WAIT_L(0); PG8_BAR; PG8_MMA(0, 0, At, B0); PG8_MMA(0, 1, At, B1); PG8_BAR; PG8_SCHED;
;             PG8_LDA(At, 1, 1); PG8_STAGE(PG8_SB(1, 0), b3, voffB); PG8_STAGE(PG8_SB(1, 1), b3 + hstep, voffB); PG8_STAGE(PG8_SA(1, 0), a3, voffA);
;             PG8_WAIT_V(8); PG8_WAIT_L(0); PG8_BAR; PG8_MMA(1, 0, At, B0); PG8_MMA(1, 1, At, B1); PG8_BAR; PG8_SCHED;
	s_setprio 0
	s_add_i32 s10, s36, s25
	v_lshl_add_u64 v[168:169], v[168:169], 0, s[88:89]
	s_mov_b32 m0, s10
	ds_read_b128 v[200:203], v146 offset:49152
	ds_read_b128 v[204:207], v146 offset:50176
	ds_read_b128 v[208:211], v146 offset:51200
	ds_read_b128 v[212:215], v146 offset:52224
	ds_read_b128 v[228:231], v146 offset:53248
	ds_read_b128 v[232:235], v146 offset:54272
	ds_read_b128 v[236:239], v146 offset:55296
	ds_read_b128 v[240:243], v146 offset:56320
	global_load_lds_dwordx4 v[168:169], off
	s_add_i32 m0, s10, 0x2000
	s_add_u32 s8, s8, 0x80080
	v_lshl_add_u64 v[168:169], v[216:217], 0, s[88:89]
	s_addc_u32 s9, s9, 0
	s_add_i32 s10, s37, s25
	global_load_lds_dwordx4 v[168:169], off
	v_lshl_add_u64 v[168:169], s[8:9], 0, v[0:1]
	s_mov_b32 m0, s10
	s_nop 0
	global_load_lds_dwordx4 v[168:169], off
	v_lshl_add_u64 v[168:169], s[8:9], 0, v[134:135]
	s_add_i32 m0, s10, 0x2000
	s_nop 0
	global_load_lds_dwordx4 v[168:169], off
	v_lshl_add_u64 v[168:169], v[244:245], 0, s[88:89]
	s_mov_b32 m0, s30
	s_nop 0
	global_load_lds_dwordx4 v[168:169], off
	v_lshl_add_u64 v[168:169], v[246:247], 0, s[88:89]
	s_mov_b32 m0, s31
	s_nop 0
	global_load_lds_dwordx4 v[168:169], off
	s_waitcnt vmcnt(8)
	s_waitcnt lgkmcnt(0)
	s_setprio 1
	s_barrier
	v_mfma_f32_16x16x32_bf16 v[62:65], v[148:151], v[200:203], v[62:65]
	v_mfma_f32_16x16x32_bf16 v[54:57], v[156:159], v[200:203], v[54:57]
	v_mfma_f32_16x16x32_bf16 v[46:49], v[148:151], v[208:211], v[46:49]
	v_mfma_f32_16x16x32_bf16 v[38:41], v[156:159], v[208:211], v[38:41]
	v_mfma_f32_16x16x32_bf16 v[30:33], v[148:151], v[228:231], v[30:33]
	v_mfma_f32_16x16x32_bf16 v[22:25], v[156:159], v[228:231], v[22:25]
	v_mfma_f32_16x16x32_bf16 v[14:17], v[148:151], v[236:239], v[14:17]
	v_mfma_f32_16x16x32_bf16 v[6:9], v[156:159], v[236:239], v[6:9]
	v_mfma_f32_16x16x32_bf16 v[62:65], v[152:155], v[204:207], v[62:65]
	v_mfma_f32_16x16x32_bf16 v[54:57], v[160:163], v[204:207], v[54:57]
	v_mfma_f32_16x16x32_bf16 v[46:49], v[152:155], v[212:215], v[46:49]
	v_mfma_f32_16x16x32_bf16 v[38:41], v[160:163], v[212:215], v[38:41]
	v_mfma_f32_16x16x32_bf16 v[30:33], v[152:155], v[232:235], v[30:33]
	v_mfma_f32_16x16x32_bf16 v[22:25], v[160:163], v[232:235], v[22:25]
	v_mfma_f32_16x16x32_bf16 v[14:17], v[152:155], v[240:243], v[14:17]
	v_mfma_f32_16x16x32_bf16 v[6:9], v[160:163], v[240:243], v[6:9]
	v_mfma_f32_16x16x32_bf16 v[58:61], v[164:167], v[200:203], v[58:61]
	v_mfma_f32_16x16x32_bf16 v[50:53], v[192:195], v[200:203], v[50:53]
	v_mfma_f32_16x16x32_bf16 v[42:45], v[164:167], v[208:211], v[42:45]
	v_mfma_f32_16x16x32_bf16 v[34:37], v[192:195], v[208:211], v[34:37]
	v_mfma_f32_16x16x32_bf16 v[26:29], v[164:167], v[228:231], v[26:29]
	v_mfma_f32_16x16x32_bf16 v[18:21], v[192:195], v[228:231], v[18:21]
	v_mfma_f32_16x16x32_bf16 v[10:13], v[164:167], v[236:239], v[10:13]
	v_mfma_f32_16x16x32_bf16 v[2:5], v[192:195], v[236:239], v[2:5]
	v_mfma_f32_16x16x32_bf16 v[58:61], v[188:191], v[204:207], v[58:61]
	v_mfma_f32_16x16x32_bf16 v[50:53], v[196:199], v[204:207], v[50:53]
	v_mfma_f32_16x16x32_bf16 v[42:45], v[188:191], v[212:215], v[42:45]
	v_mfma_f32_16x16x32_bf16 v[34:37], v[196:199], v[212:215], v[34:37]
	v_mfma_f32_16x16x32_bf16 v[26:29], v[188:191], v[232:235], v[26:29]
	v_mfma_f32_16x16x32_bf16 v[18:21], v[196:199], v[232:235], v[18:21]
	v_mfma_f32_16x16x32_bf16 v[10:13], v[188:191], v[240:243], v[10:13]
	v_mfma_f32_16x16x32_bf16 v[2:5], v[196:199], v[240:243], v[2:5]
	s_barrier
	s_setprio 0
	s_add_i32 s74, s74, 2
	s_add_u32 s6, s6, 0x100
	s_addc_u32 s7, s7, 0
	s_add_u32 s70, s70, 0x100
	s_addc_u32 s71, s71, 0
	s_cmp_gt_u32 s74, 29
	s_cbranch_scc0 .LBB0_1773
	s_and_b64 vcc, exec, s[52:53]
	s_cbranch_vccz .LBB0_1776
	s_barrier

; #define PG8_STAGE(bufoff, gbase, voff) do { _Pragma("unroll") for (int _i = 0; _i < 2; ++_i) \
;         __builtin_amdgcn_global_load_lds((const unsigned*)((const char*)(gbase) + (voff)[_i]), (PG8_LAS unsigned*)(lds + (bufoff) + ldsw + _i * 8192), 16, 0, 0); } while (0)
; #define PG8_LDA(dst, b, h) do { _Pragma("unroll") for (int m = 0; m < 4; ++m) _Pragma("unroll") for (int k = 0; k < 2; ++k) dst[m][k] = *(const PG8_LAS bf16x8*)(lds + PG8_SA(b, h) + aoff + m * 2048 + k * 1024); } while (0)
; #define PG8_LDB(dst, b, h) do { _Pragma("unroll") for (int n = 0; n < 2; ++n) _Pragma("unroll") for (int k = 0; k < 2; ++k) dst[n][k] = *(const PG8_LAS bf16x8*)(lds + PG8_SB(b, h) + boff + n * 2048 + k * 1024); } while (0)
; #define PG8_MMA(ai, bj, At, Bt) do { __builtin_amdgcn_s_setprio(1); _Pragma("unroll") for (int m = 0; m < 4; ++m) _Pragma("unroll") for (int n = 0; n < 2; ++n) _Pragma("unroll") for (int k = 0; k < 2; ++k) \
;         acc[ai][bj][m][n] = __builtin_amdgcn_mfma_f32_16x16x32_bf16(Bt[n][k], At[m][k], acc[ai][bj][m][n], 0, 0, 0); __builtin_amdgcn_s_setprio(0); } while (0)
; #define PG8_WAIT_V(n) asm volatile("s_waitcnt vmcnt(" #n ")" ::: "memory")
; #define PG8_BAR __builtin_amdgcn_s_barrier()
; template <class Epi, class Sched, bool ALIGN_EPI = false, bool SP2 = false>
; __device__ __forceinline__ void gemm_phase(PG8_LAS unsigned char* lds, const Gemm g, const Sched& S, const Epi& E) {
;     ...
;         for (int t = 0; t < nt; t += 2) {
;             const bool last = (t == nt - 2);
;             const char* a1 = cA + (size_t)(t + 1) * kstep;
;             const char* a2 = last ? nA : cA + (size_t)(t + 2) * kstep; const char* b2 = last ? nB : cB + (size_t)(t + 2) * kstep;
;             const char* a3 = a2 + kstep; const char* b3 = b2 + kstep;
;             if (last && has_next) S.a_ready(nxt);
;             if constexpr (SP2) {
;             PG8_LDB(B0, 0, 0); PG8_LDB(B1, 0, 1); PG8_SCHED; PG8_LDA(At, 0, 0); PG8_STAGE(PG8_SA(1, 1), a1 + hstep, voffA);
;             PG8_WAIT_V(8); PG8_WAIT_L(0); PG8_BAR; PG8_MMA(0, 0, At, B0); PG8_MMA(0, 1, At, B1); PG8_BAR; PG8_SCHED;
;             PG8_LDA(At, 0, 1); PG8_STAGE(PG8_SB(0, 0), b2, voffB); PG8_STAGE(PG8_SB(0, 1), b2 + hstep, voffB); PG8_STAGE(PG8_SA(0, 0), a2, voffA);
;             PG8_WAIT_V(8); PG8_WAIT_L(0); PG8_BAR; PG8_MMA(1, 0, At, B0); PG8_MMA(1, 1, At, B1); PG8_BAR; PG8_SCHED;
.LBB0_2135:
	s_add_u32 s8, s6, 0x100
	s_addc_u32 s9, s7, 0
	s_add_i32 s36, 0, 0x10000
	s_cmpk_eq_i32 s82, 0x54
	s_cselect_b32 s79, s55, s9
	s_cselect_b32 s78, s54, s8
	s_cselect_b32 s11, s71, s81
	s_cselect_b32 s10, s70, s80
	s_add_i32 s37, 0, 0x14000
	v_add_u32_e32 v142, s36, v208
	v_add_u32_e32 v168, s37, v208
	ds_read_b128 v[114:117], v142
	ds_read_b128 v[126:129], v142 offset:1024
	ds_read_b128 v[138:141], v142 offset:2048
	ds_read_b128 v[142:145], v142 offset:3072
	ds_read_b128 v[146:149], v168
	ds_read_b128 v[150:153], v168 offset:1024
	ds_read_b128 v[154:157], v168 offset:2048
	ds_read_b128 v[188:191], v168 offset:3072
	v_lshl_add_u64 v[168:169], s[6:7], 0, v[164:165]
	s_add_i32 m0, s25, 0xc000
	ds_read_b128 v[192:195], v210
	ds_read_b128 v[196:199], v210 offset:1024
	ds_read_b128 v[200:203], v210 offset:2048
	ds_read_b128 v[204:207], v210 offset:3072
	ds_read_b128 v[212:215], v210 offset:4096
	ds_read_b128 v[228:231], v210 offset:5120
	ds_read_b128 v[232:235], v210 offset:6144
	ds_read_b128 v[236:239], v210 offset:7168
	global_load_lds_dwordx4 v[168:169], off
	v_lshl_add_u64 v[168:169], s[6:7], 0, v[166:167]
	s_add_i32 m0, s25, 0xe000
	s_nop 0
	global_load_lds_dwordx4 v[168:169], off
	s_waitcnt vmcnt(8)
	s_waitcnt lgkmcnt(0)
	s_setprio 1
	s_barrier
	v_mfma_f32_16x16x32_bf16 v[134:137], v[114:117], v[192:195], v[134:137]
	v_mfma_f32_16x16x32_bf16 v[130:133], v[138:141], v[192:195], v[130:133]
	v_mfma_f32_16x16x32_bf16 v[110:113], v[114:117], v[200:203], v[110:113]
	v_mfma_f32_16x16x32_bf16 v[106:109], v[138:141], v[200:203], v[106:109]
	v_mfma_f32_16x16x32_bf16 v[94:97], v[114:117], v[212:215], v[94:97]
	v_mfma_f32_16x16x32_bf16 v[90:93], v[138:141], v[212:215], v[90:93]
	v_mfma_f32_16x16x32_bf16 v[78:81], v[114:117], v[232:235], v[78:81]
	v_mfma_f32_16x16x32_bf16 v[74:77], v[138:141], v[232:235], v[74:77]
	v_mfma_f32_16x16x32_bf16 v[134:137], v[126:129], v[196:199], v[134:137]
	v_mfma_f32_16x16x32_bf16 v[130:133], v[142:145], v[196:199], v[130:133]
	v_mfma_f32_16x16x32_bf16 v[110:113], v[126:129], v[204:207], v[110:113]
	v_mfma_f32_16x16x32_bf16 v[106:109], v[142:145], v[204:207], v[106:109]
	v_mfma_f32_16x16x32_bf16 v[94:97], v[126:129], v[228:231], v[94:97]
	v_mfma_f32_16x16x32_bf16 v[90:93], v[142:145], v[228:231], v[90:93]
	v_mfma_f32_16x16x32_bf16 v[78:81], v[126:129], v[236:239], v[78:81]
	v_mfma_f32_16x16x32_bf16 v[74:77], v[142:145], v[236:239], v[74:77]
	v_mfma_f32_16x16x32_bf16 v[122:125], v[146:149], v[192:195], v[122:125]
	v_mfma_f32_16x16x32_bf16 v[118:121], v[154:157], v[192:195], v[118:121]
	v_mfma_f32_16x16x32_bf16 v[102:105], v[146:149], v[200:203], v[102:105]
	v_mfma_f32_16x16x32_bf16 v[98:101], v[154:157], v[200:203], v[98:101]
	v_mfma_f32_16x16x32_bf16 v[86:89], v[146:149], v[212:215], v[86:89]
	v_mfma_f32_16x16x32_bf16 v[82:85], v[154:157], v[212:215], v[82:85]
	v_mfma_f32_16x16x32_bf16 v[70:73], v[146:149], v[232:235], v[70:73]
	v_mfma_f32_16x16x32_bf16 v[66:69], v[154:157], v[232:235], v[66:69]
	v_mfma_f32_16x16x32_bf16 v[122:125], v[150:153], v[196:199], v[122:125]
	v_mfma_f32_16x16x32_bf16 v[118:121], v[188:191], v[196:199], v[118:121]
	v_mfma_f32_16x16x32_bf16 v[102:105], v[150:153], v[204:207], v[102:105]
	v_mfma_f32_16x16x32_bf16 v[98:101], v[188:191], v[204:207], v[98:101]
	v_mfma_f32_16x16x32_bf16 v[86:89], v[150:153], v[228:231], v[86:89]
	v_mfma_f32_16x16x32_bf16 v[82:85], v[188:191], v[228:231], v[82:85]
	v_mfma_f32_16x16x32_bf16 v[70:73], v[150:153], v[236:239], v[70:73]
	v_mfma_f32_16x16x32_bf16 v[66:69], v[188:191], v[236:239], v[66:69]
	s_barrier
	s_setprio 0
	s_add_i32 s6, s36, s24
	v_lshl_add_u64 v[168:169], s[10:11], 0, v[0:1]
	s_mov_b32 m0, s6
	ds_read_b128 v[192:195], v210 offset:16384
	ds_read_b128 v[196:199], v210 offset:17408
	ds_read_b128 v[200:203], v210 offset:18432
	ds_read_b128 v[204:207], v210 offset:19456
	ds_read_b128 v[212:215], v210 offset:20480
	ds_read_b128 v[228:231], v210 offset:21504
	ds_read_b128 v[232:235], v210 offset:22528
	ds_read_b128 v[236:239], v210 offset:23552
	global_load_lds_dwordx4 v[168:169], off
	s_add_i32 m0, s6, 0x2000
	s_add_u32 s6, s10, 0x160000
	v_lshl_add_u64 v[216:217], s[10:11], 0, v[158:159]
	s_addc_u32 s7, s11, 0
	s_add_i32 s36, s37, s24
	global_load_lds_dwordx4 v[216:217], off
	v_lshl_add_u64 v[240:241], s[6:7], 0, v[0:1]
	s_mov_b32 m0, s36
	v_lshl_add_u64 v[242:243], s[78:79], 0, v[160:161]
	global_load_lds_dwordx4 v[240:241], off
	v_lshl_add_u64 v[240:241], s[6:7], 0, v[158:159]
	s_add_i32 m0, s36, 0x2000
	s_nop 0
	global_load_lds_dwordx4 v[240:241], off
	s_waitcnt vmcnt(6)
	s_waitcnt lgkmcnt(0)
	s_setprio 1
	s_barrier
; #define PG8_STAGE(bufoff, gbase, voff) do { _Pragma("unroll") for (int _i = 0; _i < 2; ++_i) \
;         __builtin_amdgcn_global_load_lds((const unsigned*)((const char*)(gbase) + (voff)[_i]), (PG8_LAS unsigned*)(lds + (bufoff) + ldsw + _i * 8192), 16, 0, 0); } while (0)
; #define PG8_LDA(dst, b, h) do { _Pragma("unroll") for (int m = 0; m < 4; ++m) _Pragma("unroll") for (int k = 0; k < 2; ++k) dst[m][k] = *(const PG8_LAS bf16x8*)(lds + PG8_SA(b, h) + aoff + m * 2048 + k * 1024); } while (0)
; #define PG8_LDB(dst, b, h) do { _Pragma("unroll") for (int n = 0; n < 2; ++n) _Pragma("unroll") for (int k = 0; k < 2; ++k) dst[n][k] = *(const PG8_LAS bf16x8*)(lds + PG8_SB(b, h) + boff + n * 2048 + k * 1024); } while (0)
; #define PG8_MMA(ai, bj, At, Bt) do { __builtin_amdgcn_s_setprio(1); _Pragma("unroll") for (int m = 0; m < 4; ++m) _Pragma("unroll") for (int n = 0; n < 2; ++n) _Pragma("unroll") for (int k = 0; k < 2; ++k) \
;         acc[ai][bj][m][n] = __builtin_amdgcn_mfma_f32_16x16x32_bf16(Bt[n][k], At[m][k], acc[ai][bj][m][n], 0, 0, 0); __builtin_amdgcn_s_setprio(0); } while (0)
; #define PG8_WAIT_V(n) asm volatile("s_waitcnt vmcnt(" #n ")" ::: "memory")
; #define PG8_WAIT_L(n) asm volatile("s_waitcnt lgkmcnt(" #n ")" ::: "memory")
; #define PG8_BAR __builtin_amdgcn_s_barrier()
; #define PG8_SCHED __builtin_amdgcn_sched_barrier(0)
; template <class Epi, class Sched, bool ALIGN_EPI = false, bool SP2 = false>
; __device__ __forceinline__ void gemm_phase(PG8_LAS unsigned char* lds, const Gemm g, const Sched& S, const Epi& E) {
;     ...
;             PG8_WAIT_V(8); PG8_WAIT_L(0); PG8_BAR; PG8_MMA(0, 0, At, B0); PG8_MMA(0, 1, At, B1); PG8_BAR; PG8_SCHED;
;             PG8_LDA(At, 0, 1); PG8_STAGE(PG8_SB(0, 0), b2, voffB); PG8_STAGE(PG8_SB(0, 1), b2 + hstep, voffB); PG8_STAGE(PG8_SA(0, 0), a2, voffA);
;             PG8_WAIT_V(8); PG8_WAIT_L(0); PG8_BAR; PG8_MMA(1, 0, At, B0); PG8_MMA(1, 1, At, B1); PG8_BAR; PG8_SCHED;
;             PG8_LDB(B0, 1, 0); PG8_LDB(B1, 1, 1); PG8_SCHED; PG8_LDA(At, 1, 0); PG8_STAGE(PG8_SA(0, 1), a2 + hstep, voffA);
;             PG8_WAIT_V(8); PG8_WAIT_L(0); PG8_BAR; PG8_MMA(0, 0, At, B0); PG8_MMA(0, 1, At, B1); PG8_BAR; PG8_SCHED;
	v_mfma_f32_16x16x32_bf16 v[62:65], v[114:117], v[192:195], v[62:65]
	v_mfma_f32_16x16x32_bf16 v[58:61], v[138:141], v[192:195], v[58:61]
	v_mfma_f32_16x16x32_bf16 v[46:49], v[114:117], v[200:203], v[46:49]
	v_mfma_f32_16x16x32_bf16 v[42:45], v[138:141], v[200:203], v[42:45]
	v_mfma_f32_16x16x32_bf16 v[30:33], v[114:117], v[212:215], v[30:33]
	v_mfma_f32_16x16x32_bf16 v[26:29], v[138:141], v[212:215], v[26:29]
	v_mfma_f32_16x16x32_bf16 v[14:17], v[114:117], v[232:235], v[14:17]
	v_mfma_f32_16x16x32_bf16 v[10:13], v[138:141], v[232:235], v[10:13]
	v_mfma_f32_16x16x32_bf16 v[62:65], v[126:129], v[196:199], v[62:65]
	v_mfma_f32_16x16x32_bf16 v[58:61], v[142:145], v[196:199], v[58:61]
	v_mfma_f32_16x16x32_bf16 v[46:49], v[126:129], v[204:207], v[46:49]
	v_mfma_f32_16x16x32_bf16 v[42:45], v[142:145], v[204:207], v[42:45]
	v_mfma_f32_16x16x32_bf16 v[30:33], v[126:129], v[228:231], v[30:33]
	v_mfma_f32_16x16x32_bf16 v[26:29], v[142:145], v[228:231], v[26:29]
	v_mfma_f32_16x16x32_bf16 v[14:17], v[126:129], v[236:239], v[14:17]
	v_mfma_f32_16x16x32_bf16 v[10:13], v[142:145], v[236:239], v[10:13]
	v_mfma_f32_16x16x32_bf16 v[54:57], v[146:149], v[192:195], v[54:57]
	v_mfma_f32_16x16x32_bf16 v[50:53], v[154:157], v[192:195], v[50:53]
	v_mfma_f32_16x16x32_bf16 v[38:41], v[146:149], v[200:203], v[38:41]
	v_mfma_f32_16x16x32_bf16 v[34:37], v[154:157], v[200:203], v[34:37]
	v_mfma_f32_16x16x32_bf16 v[22:25], v[146:149], v[212:215], v[22:25]
	v_mfma_f32_16x16x32_bf16 v[18:21], v[154:157], v[212:215], v[18:21]
	v_mfma_f32_16x16x32_bf16 v[6:9], v[146:149], v[232:235], v[6:9]
	v_mfma_f32_16x16x32_bf16 v[2:5], v[154:157], v[232:235], v[2:5]
	v_mfma_f32_16x16x32_bf16 v[54:57], v[150:153], v[196:199], v[54:57]
	v_mfma_f32_16x16x32_bf16 v[50:53], v[188:191], v[196:199], v[50:53]
	v_mfma_f32_16x16x32_bf16 v[38:41], v[150:153], v[204:207], v[38:41]
	v_mfma_f32_16x16x32_bf16 v[34:37], v[188:191], v[204:207], v[34:37]
	v_mfma_f32_16x16x32_bf16 v[22:25], v[150:153], v[228:231], v[22:25]
	v_mfma_f32_16x16x32_bf16 v[18:21], v[188:191], v[228:231], v[18:21]
	v_mfma_f32_16x16x32_bf16 v[6:9], v[150:153], v[236:239], v[6:9]
	v_mfma_f32_16x16x32_bf16 v[2:5], v[188:191], v[236:239], v[2:5]
	s_barrier
	s_setprio 0
	v_lshl_add_u64 v[240:241], s[78:79], 0, v[162:163]
	s_mov_b32 m0, s25
	s_nop 0
	global_load_lds_dwordx4 v[240:241], off
	s_mov_b32 m0, s26
	s_nop 0
	global_load_lds_dwordx4 v[242:243], off
	s_add_i32 s36, 0, 0x18000
	s_add_i32 s37, 0, 0x1c000
	v_add_u32_e32 v142, s36, v208
	v_add_u32_e32 v188, s37, v208
	ds_read_b128 v[114:117], v142
	ds_read_b128 v[126:129], v142 offset:1024
	ds_read_b128 v[138:141], v142 offset:2048
	ds_read_b128 v[142:145], v142 offset:3072
	ds_read_b128 v[146:149], v188
	ds_read_b128 v[150:153], v188 offset:1024
	ds_read_b128 v[154:157], v188 offset:2048
	ds_read_b128 v[188:191], v188 offset:3072
	s_add_u32 s6, s78, 0x160000
	s_addc_u32 s7, s79, 0
	s_mov_b32 m0, s27
	v_lshl_add_u64 v[244:245], s[6:7], 0, v[162:163]
	ds_read_b128 v[192:195], v210 offset:32768
	ds_read_b128 v[196:199], v210 offset:33792
	ds_read_b128 v[200:203], v210 offset:34816
	ds_read_b128 v[204:207], v210 offset:35840
	ds_read_b128 v[212:215], v210 offset:36864
	ds_read_b128 v[228:231], v210 offset:37888
	ds_read_b128 v[232:235], v210 offset:38912
	ds_read_b128 v[236:239], v210 offset:39936
	global_load_lds_dwordx4 v[244:245], off
	v_lshl_add_u64 v[244:245], s[6:7], 0, v[160:161]
	s_mov_b32 m0, s28
	s_nop 0
	global_load_lds_dwordx4 v[244:245], off
	s_waitcnt vmcnt(8)
	s_waitcnt lgkmcnt(0)
	s_setprio 1
	s_barrier
	v_mfma_f32_16x16x32_bf16 v[134:137], v[114:117], v[192:195], v[134:137]
	v_mfma_f32_16x16x32_bf16 v[130:133], v[138:141], v[192:195], v[130:133]
	v_mfma_f32_16x16x32_bf16 v[110:113], v[114:117], v[200:203], v[110:113]
	v_mfma_f32_16x16x32_bf16 v[106:109], v[138:141], v[200:203], v[106:109]
	v_mfma_f32_16x16x32_bf16 v[94:97], v[114:117], v[212:215], v[94:97]
	v_mfma_f32_16x16x32_bf16 v[90:93], v[138:141], v[212:215], v[90:93]
	v_mfma_f32_16x16x32_bf16 v[78:81], v[114:117], v[232:235], v[78:81]
	v_mfma_f32_16x16x32_bf16 v[74:77], v[138:141], v[232:235], v[74:77]
	v_mfma_f32_16x16x32_bf16 v[134:137], v[126:129], v[196:199], v[134:137]
	v_mfma_f32_16x16x32_bf16 v[130:133], v[142:145], v[196:199], v[130:133]
	v_mfma_f32_16x16x32_bf16 v[110:113], v[126:129], v[204:207], v[110:113]
	v_mfma_f32_16x16x32_bf16 v[106:109], v[142:145], v[204:207], v[106:109]
	v_mfma_f32_16x16x32_bf16 v[94:97], v[126:129], v[228:231], v[94:97]
	v_mfma_f32_16x16x32_bf16 v[90:93], v[142:145], v[228:231], v[90:93]
	v_mfma_f32_16x16x32_bf16 v[78:81], v[126:129], v[236:239], v[78:81]
	v_mfma_f32_16x16x32_bf16 v[74:77], v[142:145], v[236:239], v[74:77]
	v_mfma_f32_16x16x32_bf16 v[122:125], v[146:149], v[192:195], v[122:125]
	v_mfma_f32_16x16x32_bf16 v[118:121], v[154:157], v[192:195], v[118:121]
	v_mfma_f32_16x16x32_bf16 v[102:105], v[146:149], v[200:203], v[102:105]
	v_mfma_f32_16x16x32_bf16 v[98:101], v[154:157], v[200:203], v[98:101]
	v_mfma_f32_16x16x32_bf16 v[86:89], v[146:149], v[212:215], v[86:89]
	v_mfma_f32_16x16x32_bf16 v[82:85], v[154:157], v[212:215], v[82:85]
	v_mfma_f32_16x16x32_bf16 v[70:73], v[146:149], v[232:235], v[70:73]
	v_mfma_f32_16x16x32_bf16 v[66:69], v[154:157], v[232:235], v[66:69]
	v_mfma_f32_16x16x32_bf16 v[122:125], v[150:153], v[196:199], v[122:125]
	v_mfma_f32_16x16x32_bf16 v[118:121], v[188:191], v[196:199], v[118:121]
	v_mfma_f32_16x16x32_bf16 v[102:105], v[150:153], v[204:207], v[102:105]
	v_mfma_f32_16x16x32_bf16 v[98:101], v[188:191], v[204:207], v[98:101]
	v_mfma_f32_16x16x32_bf16 v[86:89], v[150:153], v[228:231], v[86:89]
	v_mfma_f32_16x16x32_bf16 v[82:85], v[188:191], v[228:231], v[82:85]
	v_mfma_f32_16x16x32_bf16 v[70:73], v[150:153], v[236:239], v[70:73]
	v_mfma_f32_16x16x32_bf16 v[66:69], v[188:191], v[236:239], v[66:69]
	s_barrier
; #define PG8_STAGE(bufoff, gbase, voff) do { _Pragma("unroll") for (int _i = 0; _i < 2; ++_i) \
;         __builtin_amdgcn_global_load_lds((const unsigned*)((const char*)(gbase) + (voff)[_i]), (PG8_LAS unsigned*)(lds + (bufoff) + ldsw + _i * 8192), 16, 0, 0); } while (0)
; #define PG8_LDA(dst, b, h) do { _Pragma("unroll") for (int m = 0; m < 4; ++m) _Pragma("unroll") for (int k = 0; k < 2; ++k) dst[m][k] = *(const PG8_LAS bf16x8*)(lds + PG8_SA(b, h) + aoff + m * 2048 + k * 1024); } while (0)
; #define PG8_MMA(ai, bj, At, Bt) do { __builtin_amdgcn_s_setprio(1); _Pragma("unroll") for (int m = 0; m < 4; ++m) _Pragma("unroll") for (int n = 0; n < 2; ++n) _Pragma("unroll") for (int k = 0; k < 2; ++k) \
;         acc[ai][bj][m][n] = __builtin_amdgcn_mfma_f32_16x16x32_bf16(Bt[n][k], At[m][k], acc[ai][bj][m][n], 0, 0, 0); __builtin_amdgcn_s_setprio(0); } while (0)
; #define PG8_WAIT_V(n) asm volatile("s_waitcnt vmcnt(" #n ")" ::: "memory")
; #define PG8_WAIT_L(n) asm volatile("s_waitcnt lgkmcnt(" #n ")" ::: "memory")
; #define PG8_BAR __builtin_amdgcn_s_barrier()
; #define PG8_SCHED __builtin_amdgcn_sched_barrier(0)
; template <class Epi, class Sched, bool ALIGN_EPI = false, bool SP2 = false>
; __device__ __forceinline__ void gemm_phase(PG8_LAS unsigned char* lds, const Gemm g, const Sched& S, const Epi& E) {
;     ...
;             PG8_LDA(At, 1, 1); PG8_STAGE(PG8_SB(1, 0), b3, voffB); PG8_STAGE(PG8_SB(1, 1), b3 + hstep, voffB); PG8_STAGE(PG8_SA(1, 0), a3, voffA);
;             PG8_WAIT_V(8); PG8_WAIT_L(0); PG8_BAR; PG8_MMA(1, 0, At, B0); PG8_MMA(1, 1, At, B1); PG8_BAR; PG8_SCHED;
	s_setprio 0
	s_add_i32 s6, s36, s24
	v_lshl_add_u64 v[168:169], v[168:169], 0, s[88:89]
	s_mov_b32 m0, s6
	ds_read_b128 v[192:195], v210 offset:49152
	ds_read_b128 v[196:199], v210 offset:50176
	ds_read_b128 v[200:203], v210 offset:51200
	ds_read_b128 v[204:207], v210 offset:52224
	ds_read_b128 v[212:215], v210 offset:53248
	ds_read_b128 v[228:231], v210 offset:54272
	ds_read_b128 v[232:235], v210 offset:55296
	ds_read_b128 v[236:239], v210 offset:56320
	global_load_lds_dwordx4 v[168:169], off
	s_add_i32 m0, s6, 0x2000
	s_add_u32 s6, s10, 0x160080
	v_lshl_add_u64 v[168:169], v[216:217], 0, s[88:89]
	s_addc_u32 s7, s11, 0
	s_add_i32 s10, s37, s24
	global_load_lds_dwordx4 v[168:169], off
	v_lshl_add_u64 v[168:169], s[6:7], 0, v[0:1]
	s_mov_b32 m0, s10
	s_nop 0
	global_load_lds_dwordx4 v[168:169], off
	v_lshl_add_u64 v[168:169], s[6:7], 0, v[158:159]
	s_add_i32 m0, s10, 0x2000
	s_nop 0
	global_load_lds_dwordx4 v[168:169], off
	v_lshl_add_u64 v[168:169], v[240:241], 0, s[88:89]
	s_mov_b32 m0, s29
	s_nop 0
	global_load_lds_dwordx4 v[168:169], off
	v_lshl_add_u64 v[168:169], v[242:243], 0, s[88:89]
	s_mov_b32 m0, s30
	s_nop 0
	global_load_lds_dwordx4 v[168:169], off
	s_waitcnt vmcnt(8)
	s_waitcnt lgkmcnt(0)
	s_setprio 1
	s_barrier
	v_mfma_f32_16x16x32_bf16 v[62:65], v[114:117], v[192:195], v[62:65]
	v_mfma_f32_16x16x32_bf16 v[58:61], v[138:141], v[192:195], v[58:61]
	v_mfma_f32_16x16x32_bf16 v[46:49], v[114:117], v[200:203], v[46:49]
	v_mfma_f32_16x16x32_bf16 v[42:45], v[138:141], v[200:203], v[42:45]
	v_mfma_f32_16x16x32_bf16 v[30:33], v[114:117], v[212:215], v[30:33]
	v_mfma_f32_16x16x32_bf16 v[26:29], v[138:141], v[212:215], v[26:29]
	v_mfma_f32_16x16x32_bf16 v[14:17], v[114:117], v[232:235], v[14:17]
	v_mfma_f32_16x16x32_bf16 v[10:13], v[138:141], v[232:235], v[10:13]
	v_mfma_f32_16x16x32_bf16 v[62:65], v[126:129], v[196:199], v[62:65]
	v_mfma_f32_16x16x32_bf16 v[58:61], v[142:145], v[196:199], v[58:61]
	v_mfma_f32_16x16x32_bf16 v[46:49], v[126:129], v[204:207], v[46:49]
	v_mfma_f32_16x16x32_bf16 v[42:45], v[142:145], v[204:207], v[42:45]
	v_mfma_f32_16x16x32_bf16 v[30:33], v[126:129], v[228:231], v[30:33]
	v_mfma_f32_16x16x32_bf16 v[26:29], v[142:145], v[228:231], v[26:29]
	v_mfma_f32_16x16x32_bf16 v[14:17], v[126:129], v[236:239], v[14:17]
	v_mfma_f32_16x16x32_bf16 v[10:13], v[142:145], v[236:239], v[10:13]
	v_mfma_f32_16x16x32_bf16 v[54:57], v[146:149], v[192:195], v[54:57]
	v_mfma_f32_16x16x32_bf16 v[50:53], v[154:157], v[192:195], v[50:53]
	v_mfma_f32_16x16x32_bf16 v[38:41], v[146:149], v[200:203], v[38:41]
	v_mfma_f32_16x16x32_bf16 v[34:37], v[154:157], v[200:203], v[34:37]
	v_mfma_f32_16x16x32_bf16 v[22:25], v[146:149], v[212:215], v[22:25]
	v_mfma_f32_16x16x32_bf16 v[18:21], v[154:157], v[212:215], v[18:21]
	v_mfma_f32_16x16x32_bf16 v[6:9], v[146:149], v[232:235], v[6:9]
	v_mfma_f32_16x16x32_bf16 v[2:5], v[154:157], v[232:235], v[2:5]
	v_mfma_f32_16x16x32_bf16 v[54:57], v[150:153], v[196:199], v[54:57]
	v_mfma_f32_16x16x32_bf16 v[50:53], v[188:191], v[196:199], v[50:53]
	v_mfma_f32_16x16x32_bf16 v[38:41], v[150:153], v[204:207], v[38:41]
	v_mfma_f32_16x16x32_bf16 v[34:37], v[188:191], v[204:207], v[34:37]
	v_mfma_f32_16x16x32_bf16 v[22:25], v[150:153], v[228:231], v[22:25]
	v_mfma_f32_16x16x32_bf16 v[18:21], v[188:191], v[228:231], v[18:21]
	v_mfma_f32_16x16x32_bf16 v[6:9], v[150:153], v[236:239], v[6:9]
	v_mfma_f32_16x16x32_bf16 v[2:5], v[188:191], v[236:239], v[2:5]
	s_barrier
	s_setprio 0
	s_add_i32 s82, s82, 2
	s_add_u32 s80, s80, 0x100
	s_addc_u32 s81, s81, 0
	s_cmpk_gt_u32 s82, 0x55
	s_mov_b64 s[6:7], s[8:9]
	s_cbranch_scc0 .LBB0_2135
	s_and_b64 vcc, exec, s[68:69]
	s_cbranch_vccz .LBB0_2138
	s_barrier

; #define PG8_STAGE(bufoff, gbase, voff) do { _Pragma("unroll") for (int _i = 0; _i < 2; ++_i) \
;         __builtin_amdgcn_global_load_lds((const unsigned*)((const char*)(gbase) + (voff)[_i]), (PG8_LAS unsigned*)(lds + (bufoff) + ldsw + _i * 8192), 16, 0, 0); } while (0)
; #define PG8_LDA(dst, b, h) do { _Pragma("unroll") for (int m = 0; m < 4; ++m) _Pragma("unroll") for (int k = 0; k < 2; ++k) dst[m][k] = *(const PG8_LAS bf16x8*)(lds + PG8_SA(b, h) + aoff + m * 2048 + k * 1024); } while (0)
; #define PG8_LDB(dst, b, h) do { _Pragma("unroll") for (int n = 0; n < 2; ++n) _Pragma("unroll") for (int k = 0; k < 2; ++k) dst[n][k] = *(const PG8_LAS bf16x8*)(lds + PG8_SB(b, h) + boff + n * 2048 + k * 1024); } while (0)
; #define PG8_MMA(ai, bj, At, Bt) do { __builtin_amdgcn_s_setprio(1); _Pragma("unroll") for (int m = 0; m < 4; ++m) _Pragma("unroll") for (int n = 0; n < 2; ++n) _Pragma("unroll") for (int k = 0; k < 2; ++k) \
;         acc[ai][bj][m][n] = __builtin_amdgcn_mfma_f32_16x16x32_bf16(Bt[n][k], At[m][k], acc[ai][bj][m][n], 0, 0, 0); __builtin_amdgcn_s_setprio(0); } while (0)
; #define PG8_WAIT_V(n) asm volatile("s_waitcnt vmcnt(" #n ")" ::: "memory")
; #define PG8_WAIT_L(n) asm volatile("s_waitcnt lgkmcnt(" #n ")" ::: "memory")
; template <class Epi, class Sched, bool ALIGN_EPI = false, bool SP2 = false>
; __device__ __forceinline__ void gemm_phase(PG8_LAS unsigned char* lds, const Gemm g, const Sched& S, const Epi& E) {
;     ...
;             const bool last = (t == nt - 2);
;             const char* a1 = cA + (size_t)(t + 1) * kstep;
;             const char* a2 = last ? nA : cA + (size_t)(t + 2) * kstep; const char* b2 = last ? nB : cB + (size_t)(t + 2) * kstep;
;             const char* a3 = a2 + kstep; const char* b3 = b2 + kstep;
;             if (last && has_next) S.a_ready(nxt);
;             if constexpr (SP2) {
;             PG8_LDB(B0, 0, 0); PG8_LDB(B1, 0, 1); PG8_SCHED; PG8_LDA(At, 0, 0); PG8_STAGE(PG8_SA(1, 1), a1 + hstep, voffA);
;             PG8_WAIT_V(8); PG8_WAIT_L(0); PG8_BAR; PG8_MMA(0, 0, At, B0); PG8_MMA(0, 1, At, B1); PG8_BAR; PG8_SCHED;
;             PG8_LDA(At, 0, 1); PG8_STAGE(PG8_SB(0, 0), b2, voffB); PG8_STAGE(PG8_SB(0, 1), b2 + hstep, voffB); PG8_STAGE(PG8_SA(0, 0), a2, voffA);
;             PG8_WAIT_V(8); PG8_WAIT_L(0); PG8_BAR; PG8_MMA(1, 0, At, B0); PG8_MMA(1, 1, At, B1); PG8_BAR; PG8_SCHED;
.LBB0_2274:
	s_add_u32 s10, s6, s50
	s_addc_u32 s11, s7, s51
	s_add_u32 s10, s10, 0x100
	s_addc_u32 s11, s11, 0
	s_add_u32 s36, s65, s50
	s_addc_u32 s37, s68, s51
	s_add_i32 s70, 0, 0x10000
	s_cmpk_eq_i32 s50, 0x2b00
	s_cselect_b32 s55, s9, s11
	s_cselect_b32 s54, s8, s10
	s_cselect_b32 s11, s39, s37
	s_cselect_b32 s10, s38, s36
	s_add_i32 s36, 0, 0x14000
	v_add_u32_e32 v160, s70, v146
	v_add_u32_e32 v168, s36, v146
	ds_read_b128 v[148:151], v160
	ds_read_b128 v[152:155], v160 offset:1024
	ds_read_b128 v[156:159], v160 offset:2048
	ds_read_b128 v[160:163], v160 offset:3072
	ds_read_b128 v[164:167], v168
	ds_read_b128 v[188:191], v168 offset:1024
	ds_read_b128 v[192:195], v168 offset:2048
	ds_read_b128 v[196:199], v168 offset:3072
	v_lshl_add_u64 v[168:169], v[140:141], 0, s[50:51]
	s_add_i32 m0, s26, 0xc000
	ds_read_b128 v[200:203], v147
	ds_read_b128 v[204:207], v147 offset:1024
	ds_read_b128 v[208:211], v147 offset:2048
	ds_read_b128 v[212:215], v147 offset:3072
	ds_read_b128 v[228:231], v147 offset:4096
	ds_read_b128 v[232:235], v147 offset:5120
	ds_read_b128 v[236:239], v147 offset:6144
	ds_read_b128 v[240:243], v147 offset:7168
	global_load_lds_dwordx4 v[168:169], off
	v_lshl_add_u64 v[168:169], v[142:143], 0, s[50:51]
	s_add_i32 m0, s26, 0xe000
	s_nop 0
	global_load_lds_dwordx4 v[168:169], off
	s_waitcnt vmcnt(8)
	s_waitcnt lgkmcnt(0)
	s_setprio 1
	s_barrier
	v_mfma_f32_16x16x32_bf16 v[126:129], v[148:151], v[200:203], v[126:129]
	v_mfma_f32_16x16x32_bf16 v[122:125], v[156:159], v[200:203], v[122:125]
	v_mfma_f32_16x16x32_bf16 v[110:113], v[148:151], v[208:211], v[110:113]
	v_mfma_f32_16x16x32_bf16 v[106:109], v[156:159], v[208:211], v[106:109]
	v_mfma_f32_16x16x32_bf16 v[94:97], v[148:151], v[228:231], v[94:97]
	v_mfma_f32_16x16x32_bf16 v[90:93], v[156:159], v[228:231], v[90:93]
	v_mfma_f32_16x16x32_bf16 v[78:81], v[148:151], v[236:239], v[78:81]
	v_mfma_f32_16x16x32_bf16 v[74:77], v[156:159], v[236:239], v[74:77]
	v_mfma_f32_16x16x32_bf16 v[126:129], v[152:155], v[204:207], v[126:129]
	v_mfma_f32_16x16x32_bf16 v[122:125], v[160:163], v[204:207], v[122:125]
	v_mfma_f32_16x16x32_bf16 v[110:113], v[152:155], v[212:215], v[110:113]
	v_mfma_f32_16x16x32_bf16 v[106:109], v[160:163], v[212:215], v[106:109]
	v_mfma_f32_16x16x32_bf16 v[94:97], v[152:155], v[232:235], v[94:97]
	v_mfma_f32_16x16x32_bf16 v[90:93], v[160:163], v[232:235], v[90:93]
	v_mfma_f32_16x16x32_bf16 v[78:81], v[152:155], v[240:243], v[78:81]
	v_mfma_f32_16x16x32_bf16 v[74:77], v[160:163], v[240:243], v[74:77]
	v_mfma_f32_16x16x32_bf16 v[118:121], v[164:167], v[200:203], v[118:121]
	v_mfma_f32_16x16x32_bf16 v[114:117], v[192:195], v[200:203], v[114:117]
	v_mfma_f32_16x16x32_bf16 v[102:105], v[164:167], v[208:211], v[102:105]
	v_mfma_f32_16x16x32_bf16 v[98:101], v[192:195], v[208:211], v[98:101]
	v_mfma_f32_16x16x32_bf16 v[86:89], v[164:167], v[228:231], v[86:89]
	v_mfma_f32_16x16x32_bf16 v[82:85], v[192:195], v[228:231], v[82:85]
	v_mfma_f32_16x16x32_bf16 v[70:73], v[164:167], v[236:239], v[70:73]
	v_mfma_f32_16x16x32_bf16 v[66:69], v[192:195], v[236:239], v[66:69]
	v_mfma_f32_16x16x32_bf16 v[118:121], v[188:191], v[204:207], v[118:121]
	v_mfma_f32_16x16x32_bf16 v[114:117], v[196:199], v[204:207], v[114:117]
	v_mfma_f32_16x16x32_bf16 v[102:105], v[188:191], v[212:215], v[102:105]
	v_mfma_f32_16x16x32_bf16 v[98:101], v[196:199], v[212:215], v[98:101]
	v_mfma_f32_16x16x32_bf16 v[86:89], v[188:191], v[232:235], v[86:89]
	v_mfma_f32_16x16x32_bf16 v[82:85], v[196:199], v[232:235], v[82:85]
	v_mfma_f32_16x16x32_bf16 v[70:73], v[188:191], v[240:243], v[70:73]
	v_mfma_f32_16x16x32_bf16 v[66:69], v[196:199], v[240:243], v[66:69]
	s_barrier
	s_setprio 0
	s_add_i32 s37, s70, s25
	v_lshl_add_u64 v[168:169], s[10:11], 0, v[0:1]
	s_mov_b32 m0, s37
	ds_read_b128 v[200:203], v147 offset:16384
	ds_read_b128 v[204:207], v147 offset:17408
	ds_read_b128 v[208:211], v147 offset:18432
	ds_read_b128 v[212:215], v147 offset:19456
	ds_read_b128 v[228:231], v147 offset:20480
	ds_read_b128 v[232:235], v147 offset:21504
	ds_read_b128 v[236:239], v147 offset:22528
	ds_read_b128 v[240:243], v147 offset:23552
	global_load_lds_dwordx4 v[168:169], off
	s_add_i32 m0, s37, 0x2000
	s_add_u32 s70, s10, 0x160000
	v_lshl_add_u64 v[216:217], s[10:11], 0, v[130:131]
	s_addc_u32 s71, s11, 0
	s_add_i32 s36, s36, s25
	global_load_lds_dwordx4 v[216:217], off
	v_lshl_add_u64 v[244:245], s[70:71], 0, v[0:1]
	s_mov_b32 m0, s36
	v_lshl_add_u64 v[246:247], s[54:55], 0, v[132:133]
	global_load_lds_dwordx4 v[244:245], off
	v_lshl_add_u64 v[244:245], s[70:71], 0, v[130:131]
	s_add_i32 m0, s36, 0x2000
	s_nop 0
	global_load_lds_dwordx4 v[244:245], off
	s_waitcnt vmcnt(6)
	s_waitcnt lgkmcnt(0)
	s_setprio 1
	s_barrier
; #define PG8_STAGE(bufoff, gbase, voff) do { _Pragma("unroll") for (int _i = 0; _i < 2; ++_i) \
;         __builtin_amdgcn_global_load_lds((const unsigned*)((const char*)(gbase) + (voff)[_i]), (PG8_LAS unsigned*)(lds + (bufoff) + ldsw + _i * 8192), 16, 0, 0); } while (0)
; #define PG8_LDA(dst, b, h) do { _Pragma("unroll") for (int m = 0; m < 4; ++m) _Pragma("unroll") for (int k = 0; k < 2; ++k) dst[m][k] = *(const PG8_LAS bf16x8*)(lds + PG8_SA(b, h) + aoff + m * 2048 + k * 1024); } while (0)
; #define PG8_LDB(dst, b, h) do { _Pragma("unroll") for (int n = 0; n < 2; ++n) _Pragma("unroll") for (int k = 0; k < 2; ++k) dst[n][k] = *(const PG8_LAS bf16x8*)(lds + PG8_SB(b, h) + boff + n * 2048 + k * 1024); } while (0)
; #define PG8_MMA(ai, bj, At, Bt) do { __builtin_amdgcn_s_setprio(1); _Pragma("unroll") for (int m = 0; m < 4; ++m) _Pragma("unroll") for (int n = 0; n < 2; ++n) _Pragma("unroll") for (int k = 0; k < 2; ++k) \
;         acc[ai][bj][m][n] = __builtin_amdgcn_mfma_f32_16x16x32_bf16(Bt[n][k], At[m][k], acc[ai][bj][m][n], 0, 0, 0); __builtin_amdgcn_s_setprio(0); } while (0)
; #define PG8_WAIT_V(n) asm volatile("s_waitcnt vmcnt(" #n ")" ::: "memory")
; #define PG8_WAIT_L(n) asm volatile("s_waitcnt lgkmcnt(" #n ")" ::: "memory")
; #define PG8_BAR __builtin_amdgcn_s_barrier()
; #define PG8_SCHED __builtin_amdgcn_sched_barrier(0)
; template <class Epi, class Sched, bool ALIGN_EPI = false, bool SP2 = false>
; __device__ __forceinline__ void gemm_phase(PG8_LAS unsigned char* lds, const Gemm g, const Sched& S, const Epi& E) {
;     ...
;             PG8_WAIT_V(8); PG8_WAIT_L(0); PG8_BAR; PG8_MMA(1, 0, At, B0); PG8_MMA(1, 1, At, B1); PG8_BAR; PG8_SCHED;
;             PG8_LDB(B0, 1, 0); PG8_LDB(B1, 1, 1); PG8_SCHED; PG8_LDA(At, 1, 0); PG8_STAGE(PG8_SA(0, 1), a2 + hstep, voffA);
;             PG8_WAIT_V(8); PG8_WAIT_L(0); PG8_BAR; PG8_MMA(0, 0, At, B0); PG8_MMA(0, 1, At, B1); PG8_BAR; PG8_SCHED;
	v_mfma_f32_16x16x32_bf16 v[62:65], v[148:151], v[200:203], v[62:65]
	v_mfma_f32_16x16x32_bf16 v[58:61], v[156:159], v[200:203], v[58:61]
	v_mfma_f32_16x16x32_bf16 v[46:49], v[148:151], v[208:211], v[46:49]
	v_mfma_f32_16x16x32_bf16 v[42:45], v[156:159], v[208:211], v[42:45]
	v_mfma_f32_16x16x32_bf16 v[30:33], v[148:151], v[228:231], v[30:33]
	v_mfma_f32_16x16x32_bf16 v[26:29], v[156:159], v[228:231], v[26:29]
	v_mfma_f32_16x16x32_bf16 v[14:17], v[148:151], v[236:239], v[14:17]
	v_mfma_f32_16x16x32_bf16 v[10:13], v[156:159], v[236:239], v[10:13]
	v_mfma_f32_16x16x32_bf16 v[62:65], v[152:155], v[204:207], v[62:65]
	v_mfma_f32_16x16x32_bf16 v[58:61], v[160:163], v[204:207], v[58:61]
	v_mfma_f32_16x16x32_bf16 v[46:49], v[152:155], v[212:215], v[46:49]
	v_mfma_f32_16x16x32_bf16 v[42:45], v[160:163], v[212:215], v[42:45]
	v_mfma_f32_16x16x32_bf16 v[30:33], v[152:155], v[232:235], v[30:33]
	v_mfma_f32_16x16x32_bf16 v[26:29], v[160:163], v[232:235], v[26:29]
	v_mfma_f32_16x16x32_bf16 v[14:17], v[152:155], v[240:243], v[14:17]
	v_mfma_f32_16x16x32_bf16 v[10:13], v[160:163], v[240:243], v[10:13]
	v_mfma_f32_16x16x32_bf16 v[54:57], v[164:167], v[200:203], v[54:57]
	v_mfma_f32_16x16x32_bf16 v[50:53], v[192:195], v[200:203], v[50:53]
	v_mfma_f32_16x16x32_bf16 v[38:41], v[164:167], v[208:211], v[38:41]
	v_mfma_f32_16x16x32_bf16 v[34:37], v[192:195], v[208:211], v[34:37]
	v_mfma_f32_16x16x32_bf16 v[22:25], v[164:167], v[228:231], v[22:25]
	v_mfma_f32_16x16x32_bf16 v[18:21], v[192:195], v[228:231], v[18:21]
	v_mfma_f32_16x16x32_bf16 v[6:9], v[164:167], v[236:239], v[6:9]
	v_mfma_f32_16x16x32_bf16 v[2:5], v[192:195], v[236:239], v[2:5]
	v_mfma_f32_16x16x32_bf16 v[54:57], v[188:191], v[204:207], v[54:57]
	v_mfma_f32_16x16x32_bf16 v[50:53], v[196:199], v[204:207], v[50:53]
	v_mfma_f32_16x16x32_bf16 v[38:41], v[188:191], v[212:215], v[38:41]
	v_mfma_f32_16x16x32_bf16 v[34:37], v[196:199], v[212:215], v[34:37]
	v_mfma_f32_16x16x32_bf16 v[22:25], v[188:191], v[232:235], v[22:25]
	v_mfma_f32_16x16x32_bf16 v[18:21], v[196:199], v[232:235], v[18:21]
	v_mfma_f32_16x16x32_bf16 v[6:9], v[188:191], v[240:243], v[6:9]
	v_mfma_f32_16x16x32_bf16 v[2:5], v[196:199], v[240:243], v[2:5]
	s_barrier
	s_setprio 0
	v_lshl_add_u64 v[244:245], s[54:55], 0, v[134:135]
	s_mov_b32 m0, s26
	s_nop 0
	global_load_lds_dwordx4 v[244:245], off
	s_mov_b32 m0, s27
	s_nop 0
	global_load_lds_dwordx4 v[246:247], off
	s_add_i32 s36, 0, 0x18000
	s_add_i32 s37, 0, 0x1c000
	v_add_u32_e32 v160, s36, v146
	v_add_u32_e32 v175, s37, v146
	ds_read_b128 v[148:151], v160
	ds_read_b128 v[152:155], v160 offset:1024
	ds_read_b128 v[156:159], v160 offset:2048
	ds_read_b128 v[160:163], v160 offset:3072
	ds_read_b128 v[164:167], v175
	ds_read_b128 v[188:191], v175 offset:1024
	ds_read_b128 v[192:195], v175 offset:2048
	ds_read_b128 v[196:199], v175 offset:3072
	s_add_u32 s54, s54, 0x160000
	s_addc_u32 s55, s55, 0
	s_mov_b32 m0, s28
	v_lshl_add_u64 v[248:249], s[54:55], 0, v[134:135]
	ds_read_b128 v[200:203], v147 offset:32768
	ds_read_b128 v[204:207], v147 offset:33792
	ds_read_b128 v[208:211], v147 offset:34816
	ds_read_b128 v[212:215], v147 offset:35840
	ds_read_b128 v[228:231], v147 offset:36864
	ds_read_b128 v[232:235], v147 offset:37888
	ds_read_b128 v[236:239], v147 offset:38912
	ds_read_b128 v[240:243], v147 offset:39936
	global_load_lds_dwordx4 v[248:249], off
	v_lshl_add_u64 v[248:249], s[54:55], 0, v[132:133]
	s_mov_b32 m0, s29
	s_nop 0
	global_load_lds_dwordx4 v[248:249], off
	s_waitcnt vmcnt(8)
	s_waitcnt lgkmcnt(0)
	s_setprio 1
	s_barrier
	v_mfma_f32_16x16x32_bf16 v[126:129], v[148:151], v[200:203], v[126:129]
	v_mfma_f32_16x16x32_bf16 v[122:125], v[156:159], v[200:203], v[122:125]
	v_mfma_f32_16x16x32_bf16 v[110:113], v[148:151], v[208:211], v[110:113]
	v_mfma_f32_16x16x32_bf16 v[106:109], v[156:159], v[208:211], v[106:109]
	v_mfma_f32_16x16x32_bf16 v[94:97], v[148:151], v[228:231], v[94:97]
	v_mfma_f32_16x16x32_bf16 v[90:93], v[156:159], v[228:231], v[90:93]
	v_mfma_f32_16x16x32_bf16 v[78:81], v[148:151], v[236:239], v[78:81]
	v_mfma_f32_16x16x32_bf16 v[74:77], v[156:159], v[236:239], v[74:77]
	v_mfma_f32_16x16x32_bf16 v[126:129], v[152:155], v[204:207], v[126:129]
	v_mfma_f32_16x16x32_bf16 v[122:125], v[160:163], v[204:207], v[122:125]
	v_mfma_f32_16x16x32_bf16 v[110:113], v[152:155], v[212:215], v[110:113]
	v_mfma_f32_16x16x32_bf16 v[106:109], v[160:163], v[212:215], v[106:109]
	v_mfma_f32_16x16x32_bf16 v[94:97], v[152:155], v[232:235], v[94:97]
	v_mfma_f32_16x16x32_bf16 v[90:93], v[160:163], v[232:235], v[90:93]
	v_mfma_f32_16x16x32_bf16 v[78:81], v[152:155], v[240:243], v[78:81]
	v_mfma_f32_16x16x32_bf16 v[74:77], v[160:163], v[240:243], v[74:77]
	v_mfma_f32_16x16x32_bf16 v[118:121], v[164:167], v[200:203], v[118:121]
	v_mfma_f32_16x16x32_bf16 v[114:117], v[192:195], v[200:203], v[114:117]
	v_mfma_f32_16x16x32_bf16 v[102:105], v[164:167], v[208:211], v[102:105]
	v_mfma_f32_16x16x32_bf16 v[98:101], v[192:195], v[208:211], v[98:101]
	v_mfma_f32_16x16x32_bf16 v[86:89], v[164:167], v[228:231], v[86:89]
	v_mfma_f32_16x16x32_bf16 v[82:85], v[192:195], v[228:231], v[82:85]
	v_mfma_f32_16x16x32_bf16 v[70:73], v[164:167], v[236:239], v[70:73]
	v_mfma_f32_16x16x32_bf16 v[66:69], v[192:195], v[236:239], v[66:69]
	v_mfma_f32_16x16x32_bf16 v[118:121], v[188:191], v[204:207], v[118:121]
	v_mfma_f32_16x16x32_bf16 v[114:117], v[196:199], v[204:207], v[114:117]
	v_mfma_f32_16x16x32_bf16 v[102:105], v[188:191], v[212:215], v[102:105]
	v_mfma_f32_16x16x32_bf16 v[98:101], v[196:199], v[212:215], v[98:101]
	v_mfma_f32_16x16x32_bf16 v[86:89], v[188:191], v[232:235], v[86:89]
	v_mfma_f32_16x16x32_bf16 v[82:85], v[196:199], v[232:235], v[82:85]
	v_mfma_f32_16x16x32_bf16 v[70:73], v[188:191], v[240:243], v[70:73]
	v_mfma_f32_16x16x32_bf16 v[66:69], v[196:199], v[240:243], v[66:69]
	s_barrier
; #define PG8_STAGE(bufoff, gbase, voff) do { _Pragma("unroll") for (int _i = 0; _i < 2; ++_i) \
;         __builtin_amdgcn_global_load_lds((const unsigned*)((const char*)(gbase) + (voff)[_i]), (PG8_LAS unsigned*)(lds + (bufoff) + ldsw + _i * 8192), 16, 0, 0); } while (0)
; #define PG8_LDA(dst, b, h) do { _Pragma("unroll") for (int m = 0; m < 4; ++m) _Pragma("unroll") for (int k = 0; k < 2; ++k) dst[m][k] = *(const PG8_LAS bf16x8*)(lds + PG8_SA(b, h) + aoff + m * 2048 + k * 1024); } while (0)
; #define PG8_MMA(ai, bj, At, Bt) do { __builtin_amdgcn_s_setprio(1); _Pragma("unroll") for (int m = 0; m < 4; ++m) _Pragma("unroll") for (int n = 0; n < 2; ++n) _Pragma("unroll") for (int k = 0; k < 2; ++k) \
;         acc[ai][bj][m][n] = __builtin_amdgcn_mfma_f32_16x16x32_bf16(Bt[n][k], At[m][k], acc[ai][bj][m][n], 0, 0, 0); __builtin_amdgcn_s_setprio(0); } while (0)
; #define PG8_WAIT_V(n) asm volatile("s_waitcnt vmcnt(" #n ")" ::: "memory")
; #define PG8_WAIT_L(n) asm volatile("s_waitcnt lgkmcnt(" #n ")" ::: "memory")
; #define PG8_BAR __builtin_amdgcn_s_barrier()
; #define PG8_SCHED __builtin_amdgcn_sched_barrier(0)
; template <class Epi, class Sched, bool ALIGN_EPI = false, bool SP2 = false>
; __device__ __forceinline__ void gemm_phase(PG8_LAS unsigned char* lds, const Gemm g, const Sched& S, const Epi& E) {
;     ...
;             PG8_LDA(At, 1, 1); PG8_STAGE(PG8_SB(1, 0), b3, voffB); PG8_STAGE(PG8_SB(1, 1), b3 + hstep, voffB); PG8_STAGE(PG8_SA(1, 0), a3, voffA);
;             PG8_WAIT_V(8); PG8_WAIT_L(0); PG8_BAR; PG8_MMA(1, 0, At, B0); PG8_MMA(1, 1, At, B1); PG8_BAR; PG8_SCHED;
;     ...
; #pragma unroll
;         for (int a = 0; a < 2; ++a)
; #pragma unroll
;             for (int b = 0; b < 2; ++b)
; #pragma unroll
;                 for (int m = 0; m < 4; ++m)
; #pragma unroll
;                     for (int n = 0; n < 2; ++n) acc[a][b][m][n] = (f32x4){0.f, 0.f, 0.f, 0.f};
;         cur = nxt; cA = nA; cB = nB; ++ui;
	s_setprio 0
	s_add_i32 s36, s36, s25
	v_lshl_add_u64 v[168:169], v[168:169], 0, s[88:89]
	s_mov_b32 m0, s36
	ds_read_b128 v[200:203], v147 offset:49152
	ds_read_b128 v[204:207], v147 offset:50176
	ds_read_b128 v[208:211], v147 offset:51200
	ds_read_b128 v[212:215], v147 offset:52224
	ds_read_b128 v[228:231], v147 offset:53248
	ds_read_b128 v[232:235], v147 offset:54272
	ds_read_b128 v[236:239], v147 offset:55296
	ds_read_b128 v[240:243], v147 offset:56320
	global_load_lds_dwordx4 v[168:169], off
	s_add_i32 m0, s36, 0x2000
	s_add_u32 s10, s10, 0x160080
	v_lshl_add_u64 v[168:169], v[216:217], 0, s[88:89]
	s_addc_u32 s11, s11, 0
	s_add_i32 s36, s37, s25
	global_load_lds_dwordx4 v[168:169], off
	v_lshl_add_u64 v[168:169], s[10:11], 0, v[0:1]
	s_mov_b32 m0, s36
	s_nop 0
	global_load_lds_dwordx4 v[168:169], off
	v_lshl_add_u64 v[168:169], s[10:11], 0, v[130:131]
	s_add_i32 m0, s36, 0x2000
	s_nop 0
	global_load_lds_dwordx4 v[168:169], off
	v_lshl_add_u64 v[168:169], v[244:245], 0, s[88:89]
	s_mov_b32 m0, s30
	s_nop 0
	global_load_lds_dwordx4 v[168:169], off
	v_lshl_add_u64 v[168:169], v[246:247], 0, s[88:89]
	s_mov_b32 m0, s31
	s_nop 0
	global_load_lds_dwordx4 v[168:169], off
	s_waitcnt vmcnt(8)
	s_waitcnt lgkmcnt(0)
	s_setprio 1
	s_barrier
	v_mfma_f32_16x16x32_bf16 v[62:65], v[148:151], v[200:203], v[62:65]
	v_mfma_f32_16x16x32_bf16 v[58:61], v[156:159], v[200:203], v[58:61]
	v_mfma_f32_16x16x32_bf16 v[46:49], v[148:151], v[208:211], v[46:49]
	v_mfma_f32_16x16x32_bf16 v[42:45], v[156:159], v[208:211], v[42:45]
	v_mfma_f32_16x16x32_bf16 v[30:33], v[148:151], v[228:231], v[30:33]
	v_mfma_f32_16x16x32_bf16 v[26:29], v[156:159], v[228:231], v[26:29]
	v_mfma_f32_16x16x32_bf16 v[14:17], v[148:151], v[236:239], v[14:17]
	v_mfma_f32_16x16x32_bf16 v[10:13], v[156:159], v[236:239], v[10:13]
	v_mfma_f32_16x16x32_bf16 v[62:65], v[152:155], v[204:207], v[62:65]
	v_mfma_f32_16x16x32_bf16 v[58:61], v[160:163], v[204:207], v[58:61]
	v_mfma_f32_16x16x32_bf16 v[46:49], v[152:155], v[212:215], v[46:49]
	v_mfma_f32_16x16x32_bf16 v[42:45], v[160:163], v[212:215], v[42:45]
	v_mfma_f32_16x16x32_bf16 v[30:33], v[152:155], v[232:235], v[30:33]
	v_mfma_f32_16x16x32_bf16 v[26:29], v[160:163], v[232:235], v[26:29]
	v_mfma_f32_16x16x32_bf16 v[14:17], v[152:155], v[240:243], v[14:17]
	v_mfma_f32_16x16x32_bf16 v[10:13], v[160:163], v[240:243], v[10:13]
	v_mfma_f32_16x16x32_bf16 v[54:57], v[164:167], v[200:203], v[54:57]
	v_mfma_f32_16x16x32_bf16 v[50:53], v[192:195], v[200:203], v[50:53]
	v_mfma_f32_16x16x32_bf16 v[38:41], v[164:167], v[208:211], v[38:41]
	v_mfma_f32_16x16x32_bf16 v[34:37], v[192:195], v[208:211], v[34:37]
	v_mfma_f32_16x16x32_bf16 v[22:25], v[164:167], v[228:231], v[22:25]
	v_mfma_f32_16x16x32_bf16 v[18:21], v[192:195], v[228:231], v[18:21]
	v_mfma_f32_16x16x32_bf16 v[6:9], v[164:167], v[236:239], v[6:9]
	v_mfma_f32_16x16x32_bf16 v[2:5], v[192:195], v[236:239], v[2:5]
	v_mfma_f32_16x16x32_bf16 v[54:57], v[188:191], v[204:207], v[54:57]
	v_mfma_f32_16x16x32_bf16 v[50:53], v[196:199], v[204:207], v[50:53]
	v_mfma_f32_16x16x32_bf16 v[38:41], v[188:191], v[212:215], v[38:41]
	v_mfma_f32_16x16x32_bf16 v[34:37], v[196:199], v[212:215], v[34:37]
	v_mfma_f32_16x16x32_bf16 v[22:25], v[188:191], v[232:235], v[22:25]
	v_mfma_f32_16x16x32_bf16 v[18:21], v[196:199], v[232:235], v[18:21]
	v_mfma_f32_16x16x32_bf16 v[6:9], v[188:191], v[240:243], v[6:9]
	v_mfma_f32_16x16x32_bf16 v[2:5], v[196:199], v[240:243], v[2:5]
	s_barrier
	s_setprio 0
	s_add_i32 s69, s69, 2
	s_add_u32 s50, s50, 0x100
	s_addc_u32 s51, s51, 0
	s_cmpk_gt_u32 s69, 0x55
	s_cbranch_scc0 .LBB0_2274
	s_add_u32 s10, s65, 0xffffff00
	s_addc_u32 s11, s68, -1
	s_and_b64 vcc, exec, s[48:49]
	s_cbranch_vccnz .LBB0_2261
	v_mov_b32_e32 v2, 0
	s_mov_b32 s61, s62
	s_mov_b32 s18, s63
	s_mov_b64 s[6:7], s[8:9]
	s_mov_b32 s60, s64
	v_mov_b32_e32 v3, v2
	v_mov_b32_e32 v4, v2
	v_mov_b32_e32 v5, v2
	v_mov_b32_e32 v6, v2
	v_mov_b32_e32 v7, v2
	v_mov_b32_e32 v8, v2
	v_mov_b32_e32 v9, v2
	v_mov_b32_e32 v18, v2
	v_mov_b32_e32 v19, v2
	v_mov_b32_e32 v20, v2
	v_mov_b32_e32 v21, v2
	v_mov_b32_e32 v22, v2
	v_mov_b32_e32 v23, v2
	v_mov_b32_e32 v24, v2
	v_mov_b32_e32 v25, v2
	v_mov_b32_e32 v34, v2
	v_mov_b32_e32 v35, v2
	v_mov_b32_e32 v36, v2
	v_mov_b32_e32 v37, v2
	v_mov_b32_e32 v38, v2
	v_mov_b32_e32 v39, v2
	v_mov_b32_e32 v40, v2
	v_mov_b32_e32 v41, v2
	v_mov_b32_e32 v50, v2
	v_mov_b32_e32 v51, v2
	v_mov_b32_e32 v52, v2
	v_mov_b32_e32 v53, v2
	v_mov_b32_e32 v54, v2
	v_mov_b32_e32 v55, v2
	v_mov_b32_e32 v56, v2
	v_mov_b32_e32 v57, v2
	v_mov_b32_e32 v10, v2
	v_mov_b32_e32 v11, v2
	v_mov_b32_e32 v12, v2
	v_mov_b32_e32 v13, v2
	v_mov_b32_e32 v14, v2
	v_mov_b32_e32 v15, v2
	v_mov_b32_e32 v16, v2
	v_mov_b32_e32 v17, v2
	v_mov_b32_e32 v26, v2
	v_mov_b32_e32 v27, v2
	v_mov_b32_e32 v28, v2
	v_mov_b32_e32 v29, v2
	v_mov_b32_e32 v30, v2
	v_mov_b32_e32 v31, v2
	v_mov_b32_e32 v32, v2
	v_mov_b32_e32 v33, v2
	v_mov_b32_e32 v42, v2
	v_mov_b32_e32 v43, v2
	v_mov_b32_e32 v44, v2
	v_mov_b32_e32 v45, v2
	v_mov_b32_e32 v46, v2
	v_mov_b32_e32 v47, v2
	v_mov_b32_e32 v48, v2
	v_mov_b32_e32 v49, v2
	v_mov_b32_e32 v58, v2
	v_mov_b32_e32 v59, v2
	v_mov_b32_e32 v60, v2
	v_mov_b32_e32 v61, v2
	v_mov_b32_e32 v62, v2
	v_mov_b32_e32 v63, v2
	v_mov_b32_e32 v64, v2
	v_mov_b32_e32 v65, v2
	v_mov_b32_e32 v66, v2
	v_mov_b32_e32 v67, v2
	v_mov_b32_e32 v68, v2
	v_mov_b32_e32 v69, v2
	v_mov_b32_e32 v70, v2
	v_mov_b32_e32 v71, v2
	v_mov_b32_e32 v72, v2
	v_mov_b32_e32 v73, v2
	v_mov_b32_e32 v82, v2
	v_mov_b32_e32 v83, v2
	v_mov_b32_e32 v84, v2
	v_mov_b32_e32 v85, v2
	v_mov_b32_e32 v86, v2
	v_mov_b32_e32 v87, v2
	v_mov_b32_e32 v88, v2
	v_mov_b32_e32 v89, v2
	v_mov_b32_e32 v98, v2
	v_mov_b32_e32 v99, v2
	v_mov_b32_e32 v100, v2
	v_mov_b32_e32 v101, v2
	v_mov_b32_e32 v102, v2
	v_mov_b32_e32 v103, v2
	v_mov_b32_e32 v104, v2
	v_mov_b32_e32 v105, v2
	v_mov_b32_e32 v114, v2
	v_mov_b32_e32 v115, v2
	v_mov_b32_e32 v116, v2
	v_mov_b32_e32 v117, v2
	v_mov_b32_e32 v118, v2
	v_mov_b32_e32 v119, v2
	v_mov_b32_e32 v120, v2
	v_mov_b32_e32 v121, v2
	v_mov_b32_e32 v74, v2
	v_mov_b32_e32 v75, v2
	v_mov_b32_e32 v76, v2
	v_mov_b32_e32 v77, v2
	v_mov_b32_e32 v78, v2
	v_mov_b32_e32 v79, v2
	v_mov_b32_e32 v80, v2
	v_mov_b32_e32 v81, v2
	v_mov_b32_e32 v90, v2
	v_mov_b32_e32 v91, v2
	v_mov_b32_e32 v92, v2
	v_mov_b32_e32 v93, v2
	v_mov_b32_e32 v94, v2
	v_mov_b32_e32 v95, v2
	v_mov_b32_e32 v96, v2
	v_mov_b32_e32 v97, v2
	v_mov_b32_e32 v106, v2
	v_mov_b32_e32 v107, v2
	v_mov_b32_e32 v108, v2
	v_mov_b32_e32 v109, v2
	v_mov_b32_e32 v110, v2
	v_mov_b32_e32 v111, v2
	v_mov_b32_e32 v112, v2
	v_mov_b32_e32 v113, v2
	v_mov_b32_e32 v122, v2
	v_mov_b32_e32 v123, v2
	v_mov_b32_e32 v124, v2
	v_mov_b32_e32 v125, v2
	v_mov_b32_e32 v126, v2
	v_mov_b32_e32 v127, v2
	v_mov_b32_e32 v128, v2
	v_mov_b32_e32 v129, v2
	s_movk_i32 s36, 0x2800
	s_andn2_b64 vcc, exec, s[46:47]
	s_cbranch_vccnz .LBB0_2262
